# out-proj k-loop: MFMA-only waves L2-prefetch the HBM-cold Y slabs 4-11 K-tiles ahead (the 2-slot ring only hides one iteration of DMA latency)
# speedup vs baseline: 1.0176x; 1.0097x over previous
; DI f32x4 mfma16(bf16x8 a, bf16x8 b, f32x4 c) { return __builtin_amdgcn_mfma_f32_16x16x32_bf16(a, b, c, 0, 0, 0); }
; template <int N> DI void wait_vm() { asm volatile("s_waitcnt vmcnt(%0)" ::"n"(N) : "memory"); }
; DI void raw_barrier() { asm volatile("" ::: "memory"); __builtin_amdgcn_s_barrier(); asm volatile("" ::: "memory"); }
;     ...
;     auto compute = [&](int cb, bool do_issue, int ikt, int ib) {
;         const char* base = lds + cb * BUF;
;         bf16x8 af[MT], bfr[NT];
; #pragma unroll
;         for (int nt = 0; nt < NT; ++nt) {
;             const int br = BM + (nt / NTS) * (BN / NSEG) + wc * (NTS * 16) + (nt % NTS) * 16;
;             bfr[nt] = *(const bf16x8*)(base + (br + l15) * 64 + rsw);
;         }
; #pragma unroll
;         for (int mt = 0; mt < MT; ++mt) af[mt] = *(const bf16x8*)(base + (wr * WM + mt * 16 + l15) * 64 + rsw);
;         constexpr int TOT = MT * NT, PER = (TOT + NIT - 1) / NIT;
; #pragma unroll
;         for (int part = 0; part < NIT; ++part) {
; #pragma unroll
;             for (int q = 0; q < PER; ++q) {
;                 const int idx = part * PER + q;
;                 if (idx < TOT) {
;                     const int mt = idx / NT, nt = idx % NT;
;                     acc[mt][nt] = SWAP ? mfma16(bfr[nt], af[mt], acc[mt][nt]) : mfma16(af[mt], bfr[nt], acc[mt][nt]);
;                 }
;             }
;             __builtin_amdgcn_sched_barrier(0);
;             if (do_issue) issue_one(ikt, ib, part);
;             __builtin_amdgcn_sched_barrier(0);
;         }
;     };
;     __syncthreads();
; #pragma unroll
;     for (int d = 0; d < D; ++d) issue(d, d);
;     int cb = 0, ib = D;
;     for (int kt = 0; kt < KT; ++kt) {
;         if (D > 1 && kt + D - 1 < KT) wait_vm<(D - 1) * NIT>(); else wait_vm<0>();
;         raw_barrier();
;         compute(cb, kt + D < KT, kt + D, ib);
;         cb = (cb + 1 == NST) ? 0 : cb + 1;
;         ib = (ib + 1 == NST) ? 0 : ib + 1;
;     }
.Lpo1_c_entry:
	v_subrev_u32_e32 v246, 0x100, v212
	v_readfirstlane_b32 s96, v130
	v_readfirstlane_b32 s97, v131
	v_readfirstlane_b32 s94, v0
	s_nop 3
	s_sub_u32 s96, s96, s94
	s_subb_u32 s97, s97, 0
	s_add_i32 s94, s33, 2
	v_lshrrev_b32_e32 v247, 5, v246
	v_add_u32_e32 v247, s94, v247
	v_and_b32_e32 v247, 31, v247
	v_and_b32_e32 v199, 31, v246
	v_lshlrev_b32_e32 v199, 7, v199
	v_lshl_or_b32 v247, v247, 12, v199
	s_nop 1
	global_load_dword v247, v247, s[96:97]
	s_mov_b32 s9, 2
	s_waitcnt vmcnt(1)
	s_barrier
	v_add_u32_e32 v197, v140, v141
	v_add_u32_e32 v196, v140, v139
	ds_read_b128 v[146:149], v196
	ds_read_b128 v[154:157], v196 offset:1024
	ds_read_b128 v[182:185], v196 offset:2048
	ds_read_b128 v[142:145], v197 offset:4096
	ds_read_b128 v[150:153], v197 offset:5120
	ds_read_b128 v[158:161], v197 offset:6144
	ds_read_b128 v[162:165], v197 offset:7168
	ds_read_b128 v[166:169], v197 offset:8192
	ds_read_b128 v[170:173], v197 offset:9216
	ds_read_b128 v[174:177], v197 offset:10240
	ds_read_b128 v[178:181], v197 offset:11264
	ds_read_b128 v[186:189], v196 offset:3072
.Lpo1_c_loop:
	s_bitcmp1_b32 s9, 0
	s_cselect_b32 s46, 0, 0x11000
	v_add_u32_e32 v198, s46, v140
	v_add_u32_e32 v197, v198, v141
	v_add_u32_e32 v196, v198, v139
	s_waitcnt lgkmcnt(8)
	v_mfma_f32_16x16x32_bf16 v[98:101], v[142:145], v[146:149], v[98:101]
	s_waitcnt lgkmcnt(7)
	v_mfma_f32_16x16x32_bf16 v[94:97], v[150:153], v[146:149], v[94:97]
	s_waitcnt lgkmcnt(6)
	v_mfma_f32_16x16x32_bf16 v[90:93], v[158:161], v[146:149], v[90:93]
	s_waitcnt lgkmcnt(5)
	v_mfma_f32_16x16x32_bf16 v[86:89], v[162:165], v[146:149], v[86:89]
	s_waitcnt lgkmcnt(4)
	v_mfma_f32_16x16x32_bf16 v[82:85], v[166:169], v[146:149], v[82:85]
	s_waitcnt lgkmcnt(3)
	v_mfma_f32_16x16x32_bf16 v[78:81], v[170:173], v[146:149], v[78:81]
	s_waitcnt lgkmcnt(2)
	v_mfma_f32_16x16x32_bf16 v[74:77], v[174:177], v[146:149], v[74:77]
	s_waitcnt lgkmcnt(1)
	v_mfma_f32_16x16x32_bf16 v[70:73], v[178:181], v[146:149], v[70:73]
	s_waitcnt lgkmcnt(0)
	s_barrier
	ds_read_b128 v[146:149], v196
	s_and_b32 s94, s9, 7
	s_cmp_lg_u32 s94, 6
	s_cbranch_scc1 .Lpo1_ypf_skip
	s_add_i32 s94, s33, s9
	s_add_i32 s94, s94, 4
	v_lshrrev_b32_e32 v247, 5, v246
	v_add_u32_e32 v247, s94, v247
	v_and_b32_e32 v247, 31, v247
	v_and_b32_e32 v199, 31, v246
	v_lshlrev_b32_e32 v199, 7, v199
	v_lshl_or_b32 v247, v247, 12, v199
	global_load_dword v247, v247, s[96:97]

;     ...
;     auto compute = [&](int cb, bool do_issue, int ikt, int ib) {
;         const char* base = lds + cb * BUF;
;         bf16x8 af[MT], bfr[NT];
; #pragma unroll
;         for (int nt = 0; nt < NT; ++nt) {
;             const int br = BM + (nt / NTS) * (BN / NSEG) + wc * (NTS * 16) + (nt % NTS) * 16;
;             bfr[nt] = *(const bf16x8*)(base + (br + l15) * 64 + rsw);
;         }
; #pragma unroll
;         for (int mt = 0; mt < MT; ++mt) af[mt] = *(const bf16x8*)(base + (wr * WM + mt * 16 + l15) * 64 + rsw);
;         constexpr int TOT = MT * NT, PER = (TOT + NIT - 1) / NIT;
; #pragma unroll
;         for (int part = 0; part < NIT; ++part) {
; #pragma unroll
;             for (int q = 0; q < PER; ++q) {
;                 const int idx = part * PER + q;
;                 if (idx < TOT) {
;                     const int mt = idx / NT, nt = idx % NT;
;                     acc[mt][nt] = SWAP ? mfma16(bfr[nt], af[mt], acc[mt][nt]) : mfma16(af[mt], bfr[nt], acc[mt][nt]);
;                 }
;             }
;             __builtin_amdgcn_sched_barrier(0);
;             if (do_issue) issue_one(ikt, ib, part);
;             __builtin_amdgcn_sched_barrier(0);
;         }
; DI void unit_O(const Params& p, char* lds, int l, int tile, int glu_tiles, int tile_b) {
;     ...
;     auto issue_x = [&](int half) {
;         if (l == 0) {
; #pragma unroll 1
;             for (int i = 0; i < 16; ++i) {
;                 const int pc = (wid * 16 + i + xrot) & 127, row = pc >> 2, phys = (pc & 3) * 64 + lane, logical = phys ^ (row & 15);
;                 __builtin_amdgcn_global_load_lds((const unsigned*)(xres + (r0 + half * 32 + row) * 1024 + logical * 4), (unsigned*)(XR + pc * 1024 + lane * 16), 16, 0, 0);
;             }
;         } else {
; #pragma unroll 1
;             for (int i = 0; i < 8; ++i) {
;                 const int pc = (wid * 8 + i + (xrot >> 1)) & 63, kt = pc >> 1, sub = pc & 1;
;                 __builtin_amdgcn_global_load_lds((const unsigned*)(xbres + ((size_t)kt * 128 + half * 32) * 32 + sub * 512 + lane * 8), (unsigned*)(XR + pc * 1024 + lane * 16), 16, 0, 0);
;             }
;         }
;     };
;     issue_x(0);
;     {
;         const float* gsrc = (tid < 256) ? (p.ln_g + l * 1024 + tid * 4) : (p.ln_b + l * 1024 + (tid - 256) * 4);
;         *(f32x4*)(GB + tid * 4) = *(const f32x4*)gsrc;
;     }
.Lpo1_join:
.LBB0_100:
	s_waitcnt vmcnt(0)
	v_add_u32_e32 v0, 0x11000, v140
	s_barrier
	v_add_u32_e32 v134, v0, v141
	v_add_u32_e32 v0, v0, v139
	ds_read_b128 v[130:133], v134 offset:4096
	ds_read_b128 v[138:141], v0
	ds_read_b128 v[142:145], v134 offset:5120
	ds_read_b128 v[146:149], v0 offset:1024
	ds_read_b128 v[150:153], v134 offset:6144
	ds_read_b128 v[154:157], v134 offset:7168
	ds_read_b128 v[158:161], v134 offset:8192
	ds_read_b128 v[162:165], v134 offset:9216
	ds_read_b128 v[166:169], v134 offset:10240
	ds_read_b128 v[170:173], v134 offset:11264
	ds_read_b128 v[174:177], v0 offset:2048
	ds_read_b128 v[178:181], v0 offset:3072
	s_waitcnt lgkmcnt(0)
	v_mfma_f32_16x16x32_bf16 v[98:101], v[130:133], v[138:141], v[98:101]
	v_and_b32_e32 v197, 63, v136
	v_ashrrev_i32_e32 v236, 6, v136
	v_mfma_f32_16x16x32_bf16 v[94:97], v[142:145], v[138:141], v[94:97]
	v_mfma_f32_16x16x32_bf16 v[90:93], v[150:153], v[138:141], v[90:93]
	v_mfma_f32_16x16x32_bf16 v[86:89], v[154:157], v[138:141], v[86:89]
	v_mfma_f32_16x16x32_bf16 v[82:85], v[158:161], v[138:141], v[82:85]
	v_mfma_f32_16x16x32_bf16 v[78:81], v[162:165], v[138:141], v[78:81]
	v_mfma_f32_16x16x32_bf16 v[74:77], v[166:169], v[138:141], v[74:77]
	v_mfma_f32_16x16x32_bf16 v[70:73], v[170:173], v[138:141], v[70:73]
	v_mfma_f32_16x16x32_bf16 v[126:129], v[130:133], v[146:149], v[126:129]
	v_mfma_f32_16x16x32_bf16 v[122:125], v[142:145], v[146:149], v[122:125]
	v_mfma_f32_16x16x32_bf16 v[118:121], v[150:153], v[146:149], v[118:121]
	v_mfma_f32_16x16x32_bf16 v[114:117], v[154:157], v[146:149], v[114:117]
	v_mfma_f32_16x16x32_bf16 v[110:113], v[158:161], v[146:149], v[110:113]
	v_mfma_f32_16x16x32_bf16 v[106:109], v[162:165], v[146:149], v[106:109]
	v_mfma_f32_16x16x32_bf16 v[102:105], v[166:169], v[146:149], v[102:105]
	v_mfma_f32_16x16x32_bf16 v[66:69], v[170:173], v[146:149], v[66:69]
	v_mfma_f32_16x16x32_bf16 v[34:37], v[130:133], v[174:177], v[34:37]
	v_mfma_f32_16x16x32_bf16 v[30:33], v[142:145], v[174:177], v[30:33]
	v_mfma_f32_16x16x32_bf16 v[26:29], v[150:153], v[174:177], v[26:29]
	v_mfma_f32_16x16x32_bf16 v[22:25], v[154:157], v[174:177], v[22:25]
	v_mfma_f32_16x16x32_bf16 v[18:21], v[158:161], v[174:177], v[18:21]
	v_mfma_f32_16x16x32_bf16 v[14:17], v[162:165], v[174:177], v[14:17]
	v_mfma_f32_16x16x32_bf16 v[10:13], v[166:169], v[174:177], v[10:13]
	v_mfma_f32_16x16x32_bf16 v[6:9], v[170:173], v[174:177], v[6:9]
	v_mfma_f32_16x16x32_bf16 v[62:65], v[130:133], v[178:181], v[62:65]
	v_mfma_f32_16x16x32_bf16 v[58:61], v[142:145], v[178:181], v[58:61]
	v_mfma_f32_16x16x32_bf16 v[54:57], v[150:153], v[178:181], v[54:57]
	v_mfma_f32_16x16x32_bf16 v[50:53], v[154:157], v[178:181], v[50:53]
	v_mfma_f32_16x16x32_bf16 v[46:49], v[158:161], v[178:181], v[46:49]
	v_mfma_f32_16x16x32_bf16 v[42:45], v[162:165], v[178:181], v[42:45]
	v_mfma_f32_16x16x32_bf16 v[38:41], v[166:169], v[178:181], v[38:41]
	v_mfma_f32_16x16x32_bf16 v[2:5], v[170:173], v[178:181], v[2:5]
	s_barrier
	s_not_b64 s[6:7], s[10:11]
	v_and_b32_e32 v138, 15, v212
	v_bfe_u32 v139, v212, 4, 2
	v_lshrrev_b32_e32 v140, 6, v212
	v_and_b32_e32 v141, 63, v212
	v_readfirstlane_b32 s90, v140
	v_and_b32_e32 v142, 0xff, v212
	v_lshlrev_b32_e32 v142, 4, v142
	s_cmp_lt_u32 s90, 4
	s_cselect_b32 s92, s14, s12
	s_cselect_b32 s93, s15, s13
	s_nop 3
	global_load_dwordx4 v[176:179], v142, s[92:93]
	v_lshlrev_b32_e32 v143, 4, v212
	v_add_u32_e32 v143, 0x20000, v143
	v_lshlrev_b32_e32 v134, 6, v138
	v_add_u32_e32 v135, 0x22000, v134
	v_lshl_add_u32 v134, v140, 3, v135
	v_lshlrev_b32_e32 v136, 9, v140
	v_lshl_add_u32 v136, v139, 4, v136
	v_add_u32_e32 v136, 0x20000, v136
	s_cmp_lg_u64 s[10:11], 0
	s_cbranch_scc1 .Le1_l1
	s_lshl_b32 s40, s34, 18
	s_lshl_b32 s91, s90, 13
	s_add_u32 s96, s52, s40
	s_addc_u32 s97, s53, 0
	s_add_u32 s96, s96, s91
	s_addc_u32 s97, s97, 0
	s_lshl_b32 s40, s90, 1
	v_xor_b32_e32 v208, s40, v141
	v_lshlrev_b32_e32 v208, 4, v208
	s_add_u32 s40, s40, 1
	v_xor_b32_e32 v209, s40, v141
	v_lshlrev_b32_e32 v209, 4, v209
	v_lshlrev_b32_e32 v133, 12, v138
	v_lshl_add_u32 v133, v140, 9, v133
	v_add_u32_e32 v200, 0, v139
	v_xor_b32_e32 v200, v200, v138
	v_lshl_add_u32 v200, v200, 4, v133
	v_add_u32_e32 v204, 0x10000, v200
	v_add_u32_e32 v201, 4, v139
	v_xor_b32_e32 v201, v201, v138
	v_lshl_add_u32 v201, v201, 4, v133
	v_add_u32_e32 v205, 0x10000, v201
	v_add_u32_e32 v202, 8, v139
	v_xor_b32_e32 v202, v202, v138
	v_lshl_add_u32 v202, v202, 4, v133
	v_add_u32_e32 v206, 0x10000, v202
	v_add_u32_e32 v203, 12, v139
	v_xor_b32_e32 v203, v203, v138
	v_lshl_add_u32 v203, v203, 4, v133
	v_add_u32_e32 v207, 0x10000, v203
	v_and_b32_e32 v137, 1, v139
	v_lshlrev_b32_e32 v137, 5, v137
	v_lshrrev_b32_e32 v130, 1, v139
	v_lshl_or_b32 v137, v130, 4, v137
	v_lshl_or_b32 v137, v138, 6, v137
	v_lshl_or_b32 v137, v140, 15, v137
	s_lshr_b32 s40, s34, 1
	s_lshl_b32 s40, s40, 18
	s_and_b32 s46, s34, 1
	s_lshl_b32 s46, s46, 12
	s_add_u32 s40, s40, s46
	s_add_u32 s78, s56, s40
	s_addc_u32 s79, s57, 0
	s_add_u32 s92, s96, 0x0
	s_addc_u32 s93, s97, 0
	s_add_u32 s40, s91, 0x0
	s_mov_b32 m0, s40
	s_nop 0
	global_load_lds_dwordx4 v208, s[92:93]
	global_load_lds_dwordx4 v208, s[92:93] offset:1024
	global_load_lds_dwordx4 v208, s[92:93] offset:2048
	global_load_lds_dwordx4 v208, s[92:93] offset:3072
	s_add_u32 s92, s96, 0x1000
	s_addc_u32 s93, s97, 0
	s_add_u32 s40, s91, 0x1000
	s_mov_b32 m0, s40
	s_nop 0
	global_load_lds_dwordx4 v209, s[92:93]
	global_load_lds_dwordx4 v209, s[92:93] offset:1024
	global_load_lds_dwordx4 v209, s[92:93] offset:2048
	global_load_lds_dwordx4 v209, s[92:93] offset:3072
	s_add_u32 s92, s96, 0x10000
	s_addc_u32 s93, s97, 0
	s_add_u32 s40, s91, 0x10000
	s_mov_b32 m0, s40
	s_nop 0
	global_load_lds_dwordx4 v208, s[92:93]
	global_load_lds_dwordx4 v208, s[92:93] offset:1024
	global_load_lds_dwordx4 v208, s[92:93] offset:2048
	global_load_lds_dwordx4 v208, s[92:93] offset:3072
	s_add_u32 s92, s96, 0x11000
	s_addc_u32 s93, s97, 0
	s_add_u32 s40, s91, 0x11000
	s_mov_b32 m0, s40
	s_nop 0
	global_load_lds_dwordx4 v209, s[92:93]
	global_load_lds_dwordx4 v209, s[92:93] offset:1024
	global_load_lds_dwordx4 v209, s[92:93] offset:2048
	global_load_lds_dwordx4 v209, s[92:93] offset:3072
	s_waitcnt vmcnt(16)
	ds_write_b128 v143, v[176:179]
	s_waitcnt vmcnt(8) lgkmcnt(0)
	s_barrier
; DI float bf2f(unsigned b) { return __uint_as_float(b << 16); }
; DI void unit_O(const Params& p, char* lds, int l, int tile, int glu_tiles, int tile_b) {
;     ...
;         float s2[2], ss2[2];
; #pragma unroll
;         for (int mh = 0; mh < 2; ++mh) {
;             const int mt = half * 2 + mh, rl = mh * 16 + l15;
;             float s = 0.f, ss = 0.f;
; #pragma unroll
;             for (int nt = 0; nt < 8; ++nt) {
;                 f32x4 xr;
;                 if (l == 0) {
;                     const int chunk = wid * 32 + nt * 4 + quad;
;                     xr = *(const f32x4*)(XR + rl * 4096 + ((chunk ^ l15) << 4));
;                 } else {
;                     const u32x2 hb = *(const u32x2*)(XR + ((wid * 4 + (nt >> 1)) * 32 + rl) * 64 + (nt & 1) * 32 + quad * 8);
;                     xr = (f32x4){bf2f(hb[0] & 0xffffu), bf2f(hb[0] >> 16), bf2f(hb[1] & 0xffffu), bf2f(hb[1] >> 16)};
;                 }
; #pragma unroll
;                 for (int i = 0; i < 4; ++i) { const float v = acc[mt][nt][i] + DN_ALPHA * xr[i]; acc[mt][nt][i] = v; s += v; ss += v * v; }
;             }
;             s2[mh] = s; ss2[mh] = ss;
;         }
; #pragma unroll
;         for (int mh = 0; mh < 2; ++mh) { s2[mh] += __shfl_xor(s2[mh], 16); ss2[mh] += __shfl_xor(ss2[mh], 16); }
; #pragma unroll
;         for (int mh = 0; mh < 2; ++mh) { s2[mh] += __shfl_xor(s2[mh], 32); ss2[mh] += __shfl_xor(ss2[mh], 32); }
;         if (quad == 0) {
; #pragma unroll
;             for (int mh = 0; mh < 2; ++mh) *(f32x2*)&red[((mh * 16 + l15) * 8 + wid) * 2] = (f32x2){s2[mh], ss2[mh]};
;         }
;         __syncthreads();
;         if (half == 0) issue_x(1);
; #pragma unroll
;         for (int mh = 0; mh < 2; ++mh) {
;             const int mt = half * 2 + mh, rl = mh * 16 + l15, row = mt * 16 + l15;
;             float s = 0.f, ss = 0.f;
; #pragma unroll
;             for (int w = 0; w < 4; ++w) { const f32x4 v = *(const f32x4*)&red[rl * 16 + 4 * w]; s += v[0] + v[2]; ss += v[1] + v[3]; }
;             const float mu = s * (1.f / 1024.f);
;             const float var = ss * (1.f / 1024.f) - mu * mu;
;             const float rs = rsqrtf(var + LN_EPS);
	ds_read_b128 v[144:147], v200
	ds_read_b128 v[148:151], v201
	ds_read_b128 v[152:155], v202
	ds_read_b128 v[156:159], v203
	ds_read_b128 v[160:163], v200 offset:256
	ds_read_b128 v[164:167], v201 offset:256
	ds_read_b128 v[168:171], v202 offset:256
	ds_read_b128 v[172:175], v203 offset:256
	s_waitcnt lgkmcnt(7)
	v_fmac_f32_e32 v98, s58, v144
	v_fmac_f32_e32 v99, s58, v145
	v_fmac_f32_e32 v100, s58, v146
	v_fmac_f32_e32 v101, s58, v147
	v_mov_b32_e32 v196, v98
	v_mul_f32_e32 v197, v98, v98
	v_mov_b32_e32 v130, v99
	v_mul_f32_e32 v142, v99, v99
	v_add_f32_e32 v196, v196, v100
	v_fmac_f32_e32 v197, v100, v100
	v_add_f32_e32 v130, v130, v101
	v_fmac_f32_e32 v142, v101, v101
	s_waitcnt lgkmcnt(6)
	v_fmac_f32_e32 v94, s58, v148
	v_fmac_f32_e32 v95, s58, v149
	v_fmac_f32_e32 v96, s58, v150
	v_fmac_f32_e32 v97, s58, v151
	v_add_f32_e32 v196, v196, v94
	v_fmac_f32_e32 v197, v94, v94
	v_add_f32_e32 v130, v130, v95
	v_fmac_f32_e32 v142, v95, v95
	v_add_f32_e32 v196, v196, v96
	v_fmac_f32_e32 v197, v96, v96
	v_add_f32_e32 v130, v130, v97
	v_fmac_f32_e32 v142, v97, v97
	s_waitcnt lgkmcnt(5)
	v_fmac_f32_e32 v90, s58, v152
	v_fmac_f32_e32 v91, s58, v153
	v_fmac_f32_e32 v92, s58, v154
	v_fmac_f32_e32 v93, s58, v155
	v_add_f32_e32 v196, v196, v90
	v_fmac_f32_e32 v197, v90, v90
	v_add_f32_e32 v130, v130, v91
	v_fmac_f32_e32 v142, v91, v91
	v_add_f32_e32 v196, v196, v92
	v_fmac_f32_e32 v197, v92, v92
	v_add_f32_e32 v130, v130, v93
	v_fmac_f32_e32 v142, v93, v93
	s_waitcnt lgkmcnt(4)
	v_fmac_f32_e32 v86, s58, v156
	v_fmac_f32_e32 v87, s58, v157
	v_fmac_f32_e32 v88, s58, v158
	v_fmac_f32_e32 v89, s58, v159
	v_add_f32_e32 v196, v196, v86
	v_fmac_f32_e32 v197, v86, v86
	v_add_f32_e32 v130, v130, v87
	v_fmac_f32_e32 v142, v87, v87
	v_add_f32_e32 v196, v196, v88
	v_fmac_f32_e32 v197, v88, v88
	v_add_f32_e32 v130, v130, v89
	v_fmac_f32_e32 v142, v89, v89
	s_waitcnt lgkmcnt(3)
	v_fmac_f32_e32 v82, s58, v160
	v_fmac_f32_e32 v83, s58, v161
	v_fmac_f32_e32 v84, s58, v162
	v_fmac_f32_e32 v85, s58, v163
	v_add_f32_e32 v196, v196, v82
	v_fmac_f32_e32 v197, v82, v82
	v_add_f32_e32 v130, v130, v83
	v_fmac_f32_e32 v142, v83, v83
	v_add_f32_e32 v196, v196, v84
	v_fmac_f32_e32 v197, v84, v84
	v_add_f32_e32 v130, v130, v85
	v_fmac_f32_e32 v142, v85, v85
	s_waitcnt lgkmcnt(2)
	v_fmac_f32_e32 v78, s58, v164
	v_fmac_f32_e32 v79, s58, v165
	v_fmac_f32_e32 v80, s58, v166
	v_fmac_f32_e32 v81, s58, v167
	v_add_f32_e32 v196, v196, v78
	v_fmac_f32_e32 v197, v78, v78
	v_add_f32_e32 v130, v130, v79
	v_fmac_f32_e32 v142, v79, v79
	v_add_f32_e32 v196, v196, v80
	v_fmac_f32_e32 v197, v80, v80
	v_add_f32_e32 v130, v130, v81
	v_fmac_f32_e32 v142, v81, v81
	s_waitcnt lgkmcnt(1)
	v_fmac_f32_e32 v74, s58, v168
	v_fmac_f32_e32 v75, s58, v169
	v_fmac_f32_e32 v76, s58, v170
	v_fmac_f32_e32 v77, s58, v171
	v_add_f32_e32 v196, v196, v74
	v_fmac_f32_e32 v197, v74, v74
	v_add_f32_e32 v130, v130, v75
	v_fmac_f32_e32 v142, v75, v75
	v_add_f32_e32 v196, v196, v76
	v_fmac_f32_e32 v197, v76, v76
	v_add_f32_e32 v130, v130, v77
	v_fmac_f32_e32 v142, v77, v77
	s_waitcnt lgkmcnt(0)
	v_fmac_f32_e32 v70, s58, v172
	v_fmac_f32_e32 v71, s58, v173
	v_fmac_f32_e32 v72, s58, v174
	v_fmac_f32_e32 v73, s58, v175
	v_add_f32_e32 v196, v196, v70
	v_fmac_f32_e32 v197, v70, v70
	v_add_f32_e32 v130, v130, v71
	v_fmac_f32_e32 v142, v71, v71
	v_add_f32_e32 v196, v196, v72
	v_fmac_f32_e32 v197, v72, v72
	v_add_f32_e32 v130, v130, v73
	v_fmac_f32_e32 v142, v73, v73
	v_add_f32_e32 v196, v196, v130
	v_add_f32_e32 v197, v197, v142
	v_mov_b32_e32 v198, v196
	v_mov_b32_e32 v199, v197
	s_nop 1
	v_permlane16_swap_b32 v198, v196
	v_permlane16_swap_b32 v199, v197
	v_add_f32_e32 v196, v196, v198
	v_add_f32_e32 v197, v197, v199
	v_mov_b32_e32 v198, v196
	v_mov_b32_e32 v199, v197
	s_nop 1
	v_permlane32_swap_b32 v198, v196
	v_permlane32_swap_b32 v199, v197
	v_add_f32_e32 v196, v196, v198
	v_add_f32_e32 v197, v197, v199
	s_mov_b64 exec, 0xffff
	ds_write_b64 v134, v[196:197]
	s_mov_b64 exec, -1
	s_waitcnt lgkmcnt(0)
	s_barrier
	s_add_u32 s92, s96, 0x20000
	s_addc_u32 s93, s97, 0
	s_add_u32 s40, s91, 0x0
	s_mov_b32 m0, s40
	s_nop 0
	global_load_lds_dwordx4 v208, s[92:93]
	global_load_lds_dwordx4 v208, s[92:93] offset:1024
	global_load_lds_dwordx4 v208, s[92:93] offset:2048
	global_load_lds_dwordx4 v208, s[92:93] offset:3072
	s_add_u32 s92, s96, 0x21000
	s_addc_u32 s93, s97, 0
	s_add_u32 s40, s91, 0x1000
	s_mov_b32 m0, s40
	s_nop 0
	global_load_lds_dwordx4 v209, s[92:93]
	global_load_lds_dwordx4 v209, s[92:93] offset:1024
	global_load_lds_dwordx4 v209, s[92:93] offset:2048
	global_load_lds_dwordx4 v209, s[92:93] offset:3072
	ds_read_b128 v[160:163], v135 offset:0
	ds_read_b128 v[164:167], v135 offset:16
	ds_read_b128 v[168:171], v135 offset:32
	ds_read_b128 v[172:175], v135 offset:48
	s_waitcnt lgkmcnt(0)
	v_add_f32_e32 v160, v160, v162
	v_add_f32_e32 v161, v161, v163
	v_add_f32_e32 v164, v164, v166
	v_add_f32_e32 v165, v165, v167
	v_add_f32_e32 v168, v168, v170
	v_add_f32_e32 v169, v169, v171
	v_add_f32_e32 v172, v172, v174
	v_add_f32_e32 v173, v173, v175
	v_add_f32_e32 v160, v160, v164
	v_add_f32_e32 v161, v161, v165
	v_add_f32_e32 v168, v168, v172
	v_add_f32_e32 v169, v169, v173
	v_add_f32_e32 v160, v160, v168
	v_add_f32_e32 v161, v161, v169
	v_mul_f32_e32 v192, 0x3a800000, v160
	v_mul_f32_e32 v193, 0x3a800000, v161
	v_fma_f32 v193, -v192, v192, v193
	v_add_f32_e32 v193, 0x3727c5ac, v193
	v_rsq_f32_e32 v193, v193
	s_nop 0
	s_add_u32 s94, s78, 0x0
	s_addc_u32 s95, s79, 0
	ds_read_b128 v[176:179], v136
	ds_read_b128 v[180:183], v136 offset:4096
	ds_read_b128 v[184:187], v136 offset:64
	ds_read_b128 v[188:191], v136 offset:4160
	s_waitcnt lgkmcnt(2)
; DI unsigned pk2(float lo, float hi) { const f32x2 v = {lo, hi}; const bf16x2_t b = __builtin_convertvector(v, bf16x2_t); return __builtin_bit_cast(unsigned, b); }
; DI size_t xb_off(int tok, int col) { return ((size_t)(((tok >> 7) * 32 + (col >> 5)) * 128 + (tok & 127))) * 32 + (col & 31); }
; DI void unit_O(const Params& p, char* lds, int l, int tile, int glu_tiles, int tile_b) {
;     ...
;             float* orow = xo + (r0 + row) * 1024 + wid * 128 + quad * 4;
;             bf16_t* brow = xbo + xb_off((int)r0 + row, wid * 128) + quad * 4;
;             const float* gp = GB + wid * 128 + quad * 4;
; #pragma unroll
;             for (int nt = 0; nt < 8; ++nt) {
;                 const f32x4 g = *(const f32x4*)(gp + nt * 16), bb = *(const f32x4*)(gp + 1024 + nt * 16);
;                 f32x4 o;
; #pragma unroll
;                 for (int i = 0; i < 4; ++i) o[i] = (acc[mt][nt][i] - mu) * rs * g[i] + bb[i];
;                 if (l == 0) *(u32x2*)(brow + (nt >> 1) * 4096 + (nt & 1) * 16) = (u32x2){pk2(o[0], o[1]), pk2(o[2], o[3])};
;                 else *(f32x4*)(orow + nt * 16) = o;
;             }
	v_sub_f32_e32 v98, v98, v192
	v_mul_f32_e32 v98, v98, v193
	v_fma_f32 v98, v176, v98, v180
	v_sub_f32_e32 v99, v99, v192
	v_mul_f32_e32 v99, v99, v193
	v_fma_f32 v99, v177, v99, v181
	v_sub_f32_e32 v100, v100, v192
	v_mul_f32_e32 v100, v100, v193
	v_fma_f32 v100, v178, v100, v182
	v_sub_f32_e32 v101, v101, v192
	v_mul_f32_e32 v101, v101, v193
	v_fma_f32 v101, v179, v101, v183
	v_cvt_pk_bf16_f32 v144, v98, v99
	v_cvt_pk_bf16_f32 v145, v100, v101
	ds_read_b128 v[176:179], v136 offset:128
	ds_read_b128 v[180:183], v136 offset:4224
	s_waitcnt lgkmcnt(2)
	v_sub_f32_e32 v94, v94, v192
	v_mul_f32_e32 v94, v94, v193
	v_fma_f32 v94, v184, v94, v188
	v_sub_f32_e32 v95, v95, v192
	v_mul_f32_e32 v95, v95, v193
	v_fma_f32 v95, v185, v95, v189
	v_sub_f32_e32 v96, v96, v192
	v_mul_f32_e32 v96, v96, v193
	v_fma_f32 v96, v186, v96, v190
	v_sub_f32_e32 v97, v97, v192
	v_mul_f32_e32 v97, v97, v193
	v_fma_f32 v97, v187, v97, v191
	v_cvt_pk_bf16_f32 v146, v94, v95
	v_cvt_pk_bf16_f32 v147, v96, v97
	s_nop 1
	v_permlane16_swap_b32 v144, v146
	v_permlane16_swap_b32 v145, v147
	global_store_dwordx4 v137, v[144:147], s[94:95]
	s_add_u32 s94, s94, 0x2000
	s_addc_u32 s95, s95, 0
	ds_read_b128 v[184:187], v136 offset:192
	ds_read_b128 v[188:191], v136 offset:4288
	s_waitcnt lgkmcnt(2)
	v_sub_f32_e32 v90, v90, v192
	v_mul_f32_e32 v90, v90, v193
	v_fma_f32 v90, v176, v90, v180
	v_sub_f32_e32 v91, v91, v192
	v_mul_f32_e32 v91, v91, v193
	v_fma_f32 v91, v177, v91, v181
	v_sub_f32_e32 v92, v92, v192
	v_mul_f32_e32 v92, v92, v193
	v_fma_f32 v92, v178, v92, v182
	v_sub_f32_e32 v93, v93, v192
	v_mul_f32_e32 v93, v93, v193
	v_fma_f32 v93, v179, v93, v183
	v_cvt_pk_bf16_f32 v152, v90, v91
	v_cvt_pk_bf16_f32 v153, v92, v93
	ds_read_b128 v[176:179], v136 offset:256
	ds_read_b128 v[180:183], v136 offset:4352
	s_waitcnt lgkmcnt(2)
	v_sub_f32_e32 v86, v86, v192
	v_mul_f32_e32 v86, v86, v193
	v_fma_f32 v86, v184, v86, v188
	v_sub_f32_e32 v87, v87, v192
	v_mul_f32_e32 v87, v87, v193
	v_fma_f32 v87, v185, v87, v189
	v_sub_f32_e32 v88, v88, v192
	v_mul_f32_e32 v88, v88, v193
	v_fma_f32 v88, v186, v88, v190
	v_sub_f32_e32 v89, v89, v192
	v_mul_f32_e32 v89, v89, v193
	v_fma_f32 v89, v187, v89, v191
	v_cvt_pk_bf16_f32 v154, v86, v87
	v_cvt_pk_bf16_f32 v155, v88, v89
	s_nop 1
	v_permlane16_swap_b32 v152, v154
	v_permlane16_swap_b32 v153, v155
	global_store_dwordx4 v137, v[152:155], s[94:95]
	s_add_u32 s94, s94, 0x2000
	s_addc_u32 s95, s95, 0
	ds_read_b128 v[184:187], v136 offset:320
	ds_read_b128 v[188:191], v136 offset:4416
	s_waitcnt lgkmcnt(2)
	v_sub_f32_e32 v82, v82, v192
	v_mul_f32_e32 v82, v82, v193
	v_fma_f32 v82, v176, v82, v180
	v_sub_f32_e32 v83, v83, v192
	v_mul_f32_e32 v83, v83, v193
	v_fma_f32 v83, v177, v83, v181
	v_sub_f32_e32 v84, v84, v192
	v_mul_f32_e32 v84, v84, v193
	v_fma_f32 v84, v178, v84, v182
	v_sub_f32_e32 v85, v85, v192
	v_mul_f32_e32 v85, v85, v193
	v_fma_f32 v85, v179, v85, v183
	v_cvt_pk_bf16_f32 v144, v82, v83
	v_cvt_pk_bf16_f32 v145, v84, v85
	ds_read_b128 v[176:179], v136 offset:384
	ds_read_b128 v[180:183], v136 offset:4480
	s_waitcnt lgkmcnt(2)
	v_sub_f32_e32 v78, v78, v192
	v_mul_f32_e32 v78, v78, v193
	v_fma_f32 v78, v184, v78, v188
	v_sub_f32_e32 v79, v79, v192
	v_mul_f32_e32 v79, v79, v193
	v_fma_f32 v79, v185, v79, v189
	v_sub_f32_e32 v80, v80, v192
	v_mul_f32_e32 v80, v80, v193
	v_fma_f32 v80, v186, v80, v190
	v_sub_f32_e32 v81, v81, v192
	v_mul_f32_e32 v81, v81, v193
	v_fma_f32 v81, v187, v81, v191
	v_cvt_pk_bf16_f32 v146, v78, v79
	v_cvt_pk_bf16_f32 v147, v80, v81
	s_nop 1
	v_permlane16_swap_b32 v144, v146
	v_permlane16_swap_b32 v145, v147
	global_store_dwordx4 v137, v[144:147], s[94:95]
	s_add_u32 s94, s94, 0x2000
	s_addc_u32 s95, s95, 0
	ds_read_b128 v[184:187], v136 offset:448
	ds_read_b128 v[188:191], v136 offset:4544
	s_waitcnt lgkmcnt(2)
	v_sub_f32_e32 v74, v74, v192
	v_mul_f32_e32 v74, v74, v193
	v_fma_f32 v74, v176, v74, v180
	v_sub_f32_e32 v75, v75, v192
	v_mul_f32_e32 v75, v75, v193
	v_fma_f32 v75, v177, v75, v181
	v_sub_f32_e32 v76, v76, v192
	v_mul_f32_e32 v76, v76, v193
	v_fma_f32 v76, v178, v76, v182
	v_sub_f32_e32 v77, v77, v192
	v_mul_f32_e32 v77, v77, v193
	v_fma_f32 v77, v179, v77, v183
	v_cvt_pk_bf16_f32 v152, v74, v75
	v_cvt_pk_bf16_f32 v153, v76, v77
	s_waitcnt lgkmcnt(0)
	v_sub_f32_e32 v70, v70, v192
	v_mul_f32_e32 v70, v70, v193
	v_fma_f32 v70, v184, v70, v188
	v_sub_f32_e32 v71, v71, v192
	v_mul_f32_e32 v71, v71, v193
	v_fma_f32 v71, v185, v71, v189
	v_sub_f32_e32 v72, v72, v192
	v_mul_f32_e32 v72, v72, v193
	v_fma_f32 v72, v186, v72, v190
	v_sub_f32_e32 v73, v73, v192
	v_mul_f32_e32 v73, v73, v193
	v_fma_f32 v73, v187, v73, v191
	v_cvt_pk_bf16_f32 v154, v70, v71
	v_cvt_pk_bf16_f32 v155, v72, v73
	s_nop 1
	v_permlane16_swap_b32 v152, v154
	v_permlane16_swap_b32 v153, v155
	global_store_dwordx4 v137, v[152:155], s[94:95]
	s_waitcnt vmcnt(12) lgkmcnt(0)
	s_barrier
; DI float bf2f(unsigned b) { return __uint_as_float(b << 16); }
; DI void unit_O(const Params& p, char* lds, int l, int tile, int glu_tiles, int tile_b) {
;     ...
;         float s2[2], ss2[2];
; #pragma unroll
;         for (int mh = 0; mh < 2; ++mh) {
;             const int mt = half * 2 + mh, rl = mh * 16 + l15;
;             float s = 0.f, ss = 0.f;
; #pragma unroll
;             for (int nt = 0; nt < 8; ++nt) {
;                 f32x4 xr;
;                 if (l == 0) {
;                     const int chunk = wid * 32 + nt * 4 + quad;
;                     xr = *(const f32x4*)(XR + rl * 4096 + ((chunk ^ l15) << 4));
;                 } else {
;                     const u32x2 hb = *(const u32x2*)(XR + ((wid * 4 + (nt >> 1)) * 32 + rl) * 64 + (nt & 1) * 32 + quad * 8);
;                     xr = (f32x4){bf2f(hb[0] & 0xffffu), bf2f(hb[0] >> 16), bf2f(hb[1] & 0xffffu), bf2f(hb[1] >> 16)};
;                 }
; #pragma unroll
;                 for (int i = 0; i < 4; ++i) { const float v = acc[mt][nt][i] + DN_ALPHA * xr[i]; acc[mt][nt][i] = v; s += v; ss += v * v; }
;             }
;             s2[mh] = s; ss2[mh] = ss;
;         }
; #pragma unroll
;         for (int mh = 0; mh < 2; ++mh) { s2[mh] += __shfl_xor(s2[mh], 16); ss2[mh] += __shfl_xor(ss2[mh], 16); }
; #pragma unroll
;         for (int mh = 0; mh < 2; ++mh) { s2[mh] += __shfl_xor(s2[mh], 32); ss2[mh] += __shfl_xor(ss2[mh], 32); }
;         if (quad == 0) {
; #pragma unroll
;             for (int mh = 0; mh < 2; ++mh) *(f32x2*)&red[((mh * 16 + l15) * 8 + wid) * 2] = (f32x2){s2[mh], ss2[mh]};
;         }
;         __syncthreads();
;         if (half == 0) issue_x(1);
; #pragma unroll
;         for (int mh = 0; mh < 2; ++mh) {
;             const int mt = half * 2 + mh, rl = mh * 16 + l15, row = mt * 16 + l15;
;             float s = 0.f, ss = 0.f;
; #pragma unroll
;             for (int w = 0; w < 4; ++w) { const f32x4 v = *(const f32x4*)&red[rl * 16 + 4 * w]; s += v[0] + v[2]; ss += v[1] + v[3]; }
;             const float mu = s * (1.f / 1024.f);
;             const float var = ss * (1.f / 1024.f) - mu * mu;
;             const float rs = rsqrtf(var + LN_EPS);
	ds_read_b128 v[144:147], v204
	ds_read_b128 v[148:151], v205
	ds_read_b128 v[152:155], v206
	ds_read_b128 v[156:159], v207
	ds_read_b128 v[160:163], v204 offset:256
	ds_read_b128 v[164:167], v205 offset:256
	ds_read_b128 v[168:171], v206 offset:256
	ds_read_b128 v[172:175], v207 offset:256
	s_waitcnt lgkmcnt(7)
	v_fmac_f32_e32 v126, s58, v144
	v_fmac_f32_e32 v127, s58, v145
	v_fmac_f32_e32 v128, s58, v146
	v_fmac_f32_e32 v129, s58, v147
	v_mov_b32_e32 v196, v126
	v_mul_f32_e32 v197, v126, v126
	v_mov_b32_e32 v130, v127
	v_mul_f32_e32 v142, v127, v127
	v_add_f32_e32 v196, v196, v128
	v_fmac_f32_e32 v197, v128, v128
	v_add_f32_e32 v130, v130, v129
	v_fmac_f32_e32 v142, v129, v129
	s_waitcnt lgkmcnt(6)
	v_fmac_f32_e32 v122, s58, v148
	v_fmac_f32_e32 v123, s58, v149
	v_fmac_f32_e32 v124, s58, v150
	v_fmac_f32_e32 v125, s58, v151
	v_add_f32_e32 v196, v196, v122
	v_fmac_f32_e32 v197, v122, v122
	v_add_f32_e32 v130, v130, v123
	v_fmac_f32_e32 v142, v123, v123
	v_add_f32_e32 v196, v196, v124
	v_fmac_f32_e32 v197, v124, v124
	v_add_f32_e32 v130, v130, v125
	v_fmac_f32_e32 v142, v125, v125
	s_waitcnt lgkmcnt(5)
	v_fmac_f32_e32 v118, s58, v152
	v_fmac_f32_e32 v119, s58, v153
	v_fmac_f32_e32 v120, s58, v154
	v_fmac_f32_e32 v121, s58, v155
	v_add_f32_e32 v196, v196, v118
	v_fmac_f32_e32 v197, v118, v118
	v_add_f32_e32 v130, v130, v119
	v_fmac_f32_e32 v142, v119, v119
	v_add_f32_e32 v196, v196, v120
	v_fmac_f32_e32 v197, v120, v120
	v_add_f32_e32 v130, v130, v121
	v_fmac_f32_e32 v142, v121, v121
	s_waitcnt lgkmcnt(4)
	v_fmac_f32_e32 v114, s58, v156
	v_fmac_f32_e32 v115, s58, v157
	v_fmac_f32_e32 v116, s58, v158
	v_fmac_f32_e32 v117, s58, v159
	v_add_f32_e32 v196, v196, v114
	v_fmac_f32_e32 v197, v114, v114
	v_add_f32_e32 v130, v130, v115
	v_fmac_f32_e32 v142, v115, v115
	v_add_f32_e32 v196, v196, v116
	v_fmac_f32_e32 v197, v116, v116
	v_add_f32_e32 v130, v130, v117
	v_fmac_f32_e32 v142, v117, v117
	s_waitcnt lgkmcnt(3)
	v_fmac_f32_e32 v110, s58, v160
	v_fmac_f32_e32 v111, s58, v161
	v_fmac_f32_e32 v112, s58, v162
	v_fmac_f32_e32 v113, s58, v163
	v_add_f32_e32 v196, v196, v110
	v_fmac_f32_e32 v197, v110, v110
	v_add_f32_e32 v130, v130, v111
	v_fmac_f32_e32 v142, v111, v111
	v_add_f32_e32 v196, v196, v112
	v_fmac_f32_e32 v197, v112, v112
	v_add_f32_e32 v130, v130, v113
	v_fmac_f32_e32 v142, v113, v113
	s_waitcnt lgkmcnt(2)
	v_fmac_f32_e32 v106, s58, v164
	v_fmac_f32_e32 v107, s58, v165
	v_fmac_f32_e32 v108, s58, v166
	v_fmac_f32_e32 v109, s58, v167
	v_add_f32_e32 v196, v196, v106
	v_fmac_f32_e32 v197, v106, v106
	v_add_f32_e32 v130, v130, v107
	v_fmac_f32_e32 v142, v107, v107
	v_add_f32_e32 v196, v196, v108
	v_fmac_f32_e32 v197, v108, v108
	v_add_f32_e32 v130, v130, v109
	v_fmac_f32_e32 v142, v109, v109
	s_waitcnt lgkmcnt(1)
	v_fmac_f32_e32 v102, s58, v168
	v_fmac_f32_e32 v103, s58, v169
	v_fmac_f32_e32 v104, s58, v170
	v_fmac_f32_e32 v105, s58, v171
	v_add_f32_e32 v196, v196, v102
	v_fmac_f32_e32 v197, v102, v102
	v_add_f32_e32 v130, v130, v103
	v_fmac_f32_e32 v142, v103, v103
	v_add_f32_e32 v196, v196, v104
	v_fmac_f32_e32 v197, v104, v104
	v_add_f32_e32 v130, v130, v105
	v_fmac_f32_e32 v142, v105, v105
	s_waitcnt lgkmcnt(0)
	v_fmac_f32_e32 v66, s58, v172
	v_fmac_f32_e32 v67, s58, v173
	v_fmac_f32_e32 v68, s58, v174
	v_fmac_f32_e32 v69, s58, v175
	v_add_f32_e32 v196, v196, v66
	v_fmac_f32_e32 v197, v66, v66
	v_add_f32_e32 v130, v130, v67
	v_fmac_f32_e32 v142, v67, v67
	v_add_f32_e32 v196, v196, v68
	v_fmac_f32_e32 v197, v68, v68
	v_add_f32_e32 v130, v130, v69
	v_fmac_f32_e32 v142, v69, v69
	v_add_f32_e32 v196, v196, v130
	v_add_f32_e32 v197, v197, v142
	v_mov_b32_e32 v198, v196
	v_mov_b32_e32 v199, v197
	s_nop 1
	v_permlane16_swap_b32 v198, v196
	v_permlane16_swap_b32 v199, v197
	v_add_f32_e32 v196, v196, v198
	v_add_f32_e32 v197, v197, v199
	v_mov_b32_e32 v198, v196
	v_mov_b32_e32 v199, v197
	s_nop 1
	v_permlane32_swap_b32 v198, v196
	v_permlane32_swap_b32 v199, v197
	v_add_f32_e32 v196, v196, v198
	v_add_f32_e32 v197, v197, v199
	s_mov_b64 exec, 0xffff
	ds_write_b64 v134, v[196:197]
	s_mov_b64 exec, -1
	s_waitcnt lgkmcnt(0)
	s_barrier
	s_add_u32 s92, s96, 0x30000
	s_addc_u32 s93, s97, 0
	s_add_u32 s40, s91, 0x10000
	s_mov_b32 m0, s40
	s_nop 0
	global_load_lds_dwordx4 v208, s[92:93]
	global_load_lds_dwordx4 v208, s[92:93] offset:1024
	global_load_lds_dwordx4 v208, s[92:93] offset:2048
	global_load_lds_dwordx4 v208, s[92:93] offset:3072
	s_add_u32 s92, s96, 0x31000
	s_addc_u32 s93, s97, 0
	s_add_u32 s40, s91, 0x11000
	s_mov_b32 m0, s40
	s_nop 0
	global_load_lds_dwordx4 v209, s[92:93]
	global_load_lds_dwordx4 v209, s[92:93] offset:1024
	global_load_lds_dwordx4 v209, s[92:93] offset:2048
	global_load_lds_dwordx4 v209, s[92:93] offset:3072
	ds_read_b128 v[160:163], v135 offset:0
	ds_read_b128 v[164:167], v135 offset:16
	ds_read_b128 v[168:171], v135 offset:32
	ds_read_b128 v[172:175], v135 offset:48
	s_waitcnt lgkmcnt(0)
	v_add_f32_e32 v160, v160, v162
	v_add_f32_e32 v161, v161, v163
	v_add_f32_e32 v164, v164, v166
	v_add_f32_e32 v165, v165, v167
	v_add_f32_e32 v168, v168, v170
	v_add_f32_e32 v169, v169, v171
	v_add_f32_e32 v172, v172, v174
	v_add_f32_e32 v173, v173, v175
	v_add_f32_e32 v160, v160, v164
	v_add_f32_e32 v161, v161, v165
	v_add_f32_e32 v168, v168, v172
	v_add_f32_e32 v169, v169, v173
	v_add_f32_e32 v160, v160, v168
	v_add_f32_e32 v161, v161, v169
	v_mul_f32_e32 v192, 0x3a800000, v160
	v_mul_f32_e32 v193, 0x3a800000, v161
	v_fma_f32 v193, -v192, v192, v193
	v_add_f32_e32 v193, 0x3727c5ac, v193
	v_rsq_f32_e32 v193, v193
	s_nop 0
	s_add_u32 s94, s78, 0x400
	s_addc_u32 s95, s79, 0
	ds_read_b128 v[176:179], v136
	ds_read_b128 v[180:183], v136 offset:4096
	ds_read_b128 v[184:187], v136 offset:64
	ds_read_b128 v[188:191], v136 offset:4160
	s_waitcnt lgkmcnt(2)
; DI unsigned pk2(float lo, float hi) { const f32x2 v = {lo, hi}; const bf16x2_t b = __builtin_convertvector(v, bf16x2_t); return __builtin_bit_cast(unsigned, b); }
; DI size_t xb_off(int tok, int col) { return ((size_t)(((tok >> 7) * 32 + (col >> 5)) * 128 + (tok & 127))) * 32 + (col & 31); }
; DI void unit_O(const Params& p, char* lds, int l, int tile, int glu_tiles, int tile_b) {
;     ...
;             float* orow = xo + (r0 + row) * 1024 + wid * 128 + quad * 4;
;             bf16_t* brow = xbo + xb_off((int)r0 + row, wid * 128) + quad * 4;
;             const float* gp = GB + wid * 128 + quad * 4;
; #pragma unroll
;             for (int nt = 0; nt < 8; ++nt) {
;                 const f32x4 g = *(const f32x4*)(gp + nt * 16), bb = *(const f32x4*)(gp + 1024 + nt * 16);
;                 f32x4 o;
; #pragma unroll
;                 for (int i = 0; i < 4; ++i) o[i] = (acc[mt][nt][i] - mu) * rs * g[i] + bb[i];
;                 if (l == 0) *(u32x2*)(brow + (nt >> 1) * 4096 + (nt & 1) * 16) = (u32x2){pk2(o[0], o[1]), pk2(o[2], o[3])};
;                 else *(f32x4*)(orow + nt * 16) = o;
;             }
	v_sub_f32_e32 v126, v126, v192
	v_mul_f32_e32 v126, v126, v193
	v_fma_f32 v126, v176, v126, v180
	v_sub_f32_e32 v127, v127, v192
	v_mul_f32_e32 v127, v127, v193
	v_fma_f32 v127, v177, v127, v181
	v_sub_f32_e32 v128, v128, v192
	v_mul_f32_e32 v128, v128, v193
	v_fma_f32 v128, v178, v128, v182
	v_sub_f32_e32 v129, v129, v192
	v_mul_f32_e32 v129, v129, v193
	v_fma_f32 v129, v179, v129, v183
	v_cvt_pk_bf16_f32 v144, v126, v127
	v_cvt_pk_bf16_f32 v145, v128, v129
	ds_read_b128 v[176:179], v136 offset:128
	ds_read_b128 v[180:183], v136 offset:4224
	s_waitcnt lgkmcnt(2)
	v_sub_f32_e32 v122, v122, v192
	v_mul_f32_e32 v122, v122, v193
	v_fma_f32 v122, v184, v122, v188
	v_sub_f32_e32 v123, v123, v192
	v_mul_f32_e32 v123, v123, v193
	v_fma_f32 v123, v185, v123, v189
	v_sub_f32_e32 v124, v124, v192
	v_mul_f32_e32 v124, v124, v193
	v_fma_f32 v124, v186, v124, v190
	v_sub_f32_e32 v125, v125, v192
	v_mul_f32_e32 v125, v125, v193
	v_fma_f32 v125, v187, v125, v191
	v_cvt_pk_bf16_f32 v146, v122, v123
	v_cvt_pk_bf16_f32 v147, v124, v125
	s_nop 1
	v_permlane16_swap_b32 v144, v146
	v_permlane16_swap_b32 v145, v147
	global_store_dwordx4 v137, v[144:147], s[94:95]
	s_add_u32 s94, s94, 0x2000
	s_addc_u32 s95, s95, 0
	ds_read_b128 v[184:187], v136 offset:192
	ds_read_b128 v[188:191], v136 offset:4288
	s_waitcnt lgkmcnt(2)
	v_sub_f32_e32 v118, v118, v192
	v_mul_f32_e32 v118, v118, v193
	v_fma_f32 v118, v176, v118, v180
	v_sub_f32_e32 v119, v119, v192
	v_mul_f32_e32 v119, v119, v193
	v_fma_f32 v119, v177, v119, v181
	v_sub_f32_e32 v120, v120, v192
	v_mul_f32_e32 v120, v120, v193
	v_fma_f32 v120, v178, v120, v182
	v_sub_f32_e32 v121, v121, v192
	v_mul_f32_e32 v121, v121, v193
	v_fma_f32 v121, v179, v121, v183
	v_cvt_pk_bf16_f32 v152, v118, v119
	v_cvt_pk_bf16_f32 v153, v120, v121
	ds_read_b128 v[176:179], v136 offset:256
	ds_read_b128 v[180:183], v136 offset:4352
	s_waitcnt lgkmcnt(2)
	v_sub_f32_e32 v114, v114, v192
	v_mul_f32_e32 v114, v114, v193
	v_fma_f32 v114, v184, v114, v188
	v_sub_f32_e32 v115, v115, v192
	v_mul_f32_e32 v115, v115, v193
	v_fma_f32 v115, v185, v115, v189
	v_sub_f32_e32 v116, v116, v192
	v_mul_f32_e32 v116, v116, v193
	v_fma_f32 v116, v186, v116, v190
	v_sub_f32_e32 v117, v117, v192
	v_mul_f32_e32 v117, v117, v193
	v_fma_f32 v117, v187, v117, v191
	v_cvt_pk_bf16_f32 v154, v114, v115
	v_cvt_pk_bf16_f32 v155, v116, v117
	s_nop 1
	v_permlane16_swap_b32 v152, v154
	v_permlane16_swap_b32 v153, v155
	global_store_dwordx4 v137, v[152:155], s[94:95]
	s_add_u32 s94, s94, 0x2000
	s_addc_u32 s95, s95, 0
	ds_read_b128 v[184:187], v136 offset:320
	ds_read_b128 v[188:191], v136 offset:4416
	s_waitcnt lgkmcnt(2)
	v_sub_f32_e32 v110, v110, v192
	v_mul_f32_e32 v110, v110, v193
	v_fma_f32 v110, v176, v110, v180
	v_sub_f32_e32 v111, v111, v192
	v_mul_f32_e32 v111, v111, v193
	v_fma_f32 v111, v177, v111, v181
	v_sub_f32_e32 v112, v112, v192
	v_mul_f32_e32 v112, v112, v193
	v_fma_f32 v112, v178, v112, v182
	v_sub_f32_e32 v113, v113, v192
	v_mul_f32_e32 v113, v113, v193
	v_fma_f32 v113, v179, v113, v183
	v_cvt_pk_bf16_f32 v144, v110, v111
	v_cvt_pk_bf16_f32 v145, v112, v113
	ds_read_b128 v[176:179], v136 offset:384
	ds_read_b128 v[180:183], v136 offset:4480
	s_waitcnt lgkmcnt(2)
	v_sub_f32_e32 v106, v106, v192
	v_mul_f32_e32 v106, v106, v193
	v_fma_f32 v106, v184, v106, v188
	v_sub_f32_e32 v107, v107, v192
	v_mul_f32_e32 v107, v107, v193
	v_fma_f32 v107, v185, v107, v189
	v_sub_f32_e32 v108, v108, v192
	v_mul_f32_e32 v108, v108, v193
	v_fma_f32 v108, v186, v108, v190
	v_sub_f32_e32 v109, v109, v192
	v_mul_f32_e32 v109, v109, v193
	v_fma_f32 v109, v187, v109, v191
	v_cvt_pk_bf16_f32 v146, v106, v107
	v_cvt_pk_bf16_f32 v147, v108, v109
	s_nop 1
	v_permlane16_swap_b32 v144, v146
	v_permlane16_swap_b32 v145, v147
	global_store_dwordx4 v137, v[144:147], s[94:95]
	s_add_u32 s94, s94, 0x2000
	s_addc_u32 s95, s95, 0
	ds_read_b128 v[184:187], v136 offset:448
	ds_read_b128 v[188:191], v136 offset:4544
	s_waitcnt lgkmcnt(2)
	v_sub_f32_e32 v102, v102, v192
	v_mul_f32_e32 v102, v102, v193
	v_fma_f32 v102, v176, v102, v180
	v_sub_f32_e32 v103, v103, v192
	v_mul_f32_e32 v103, v103, v193
	v_fma_f32 v103, v177, v103, v181
	v_sub_f32_e32 v104, v104, v192
	v_mul_f32_e32 v104, v104, v193
	v_fma_f32 v104, v178, v104, v182
	v_sub_f32_e32 v105, v105, v192
	v_mul_f32_e32 v105, v105, v193
	v_fma_f32 v105, v179, v105, v183
	v_cvt_pk_bf16_f32 v152, v102, v103
	v_cvt_pk_bf16_f32 v153, v104, v105
	s_waitcnt lgkmcnt(0)
	v_sub_f32_e32 v66, v66, v192
	v_mul_f32_e32 v66, v66, v193
	v_fma_f32 v66, v184, v66, v188
	v_sub_f32_e32 v67, v67, v192
	v_mul_f32_e32 v67, v67, v193
	v_fma_f32 v67, v185, v67, v189
	v_sub_f32_e32 v68, v68, v192
	v_mul_f32_e32 v68, v68, v193
	v_fma_f32 v68, v186, v68, v190
	v_sub_f32_e32 v69, v69, v192
	v_mul_f32_e32 v69, v69, v193
	v_fma_f32 v69, v187, v69, v191
	v_cvt_pk_bf16_f32 v154, v66, v67
	v_cvt_pk_bf16_f32 v155, v68, v69
	s_nop 1
	v_permlane16_swap_b32 v152, v154
	v_permlane16_swap_b32 v153, v155
	global_store_dwordx4 v137, v[152:155], s[94:95]
	s_waitcnt vmcnt(16) lgkmcnt(0)
	s_barrier
; DI void unit_O(const Params& p, char* lds, int l, int tile, int glu_tiles, int tile_b) {
;     ...
;         float s2[2], ss2[2];
; #pragma unroll
;         for (int mh = 0; mh < 2; ++mh) {
;             const int mt = half * 2 + mh, rl = mh * 16 + l15;
;             float s = 0.f, ss = 0.f;
; #pragma unroll
;             for (int nt = 0; nt < 8; ++nt) {
;                 f32x4 xr;
;                 if (l == 0) {
;                     const int chunk = wid * 32 + nt * 4 + quad;
;                     xr = *(const f32x4*)(XR + rl * 4096 + ((chunk ^ l15) << 4));
;                 } else {
;                     const u32x2 hb = *(const u32x2*)(XR + ((wid * 4 + (nt >> 1)) * 32 + rl) * 64 + (nt & 1) * 32 + quad * 8);
;                     xr = (f32x4){bf2f(hb[0] & 0xffffu), bf2f(hb[0] >> 16), bf2f(hb[1] & 0xffffu), bf2f(hb[1] >> 16)};
;                 }
; #pragma unroll
;                 for (int i = 0; i < 4; ++i) { const float v = acc[mt][nt][i] + DN_ALPHA * xr[i]; acc[mt][nt][i] = v; s += v; ss += v * v; }
;             }
;             s2[mh] = s; ss2[mh] = ss;
;         }
; #pragma unroll
;         for (int mh = 0; mh < 2; ++mh) { s2[mh] += __shfl_xor(s2[mh], 16); ss2[mh] += __shfl_xor(ss2[mh], 16); }
; #pragma unroll
;         for (int mh = 0; mh < 2; ++mh) { s2[mh] += __shfl_xor(s2[mh], 32); ss2[mh] += __shfl_xor(ss2[mh], 32); }
;         if (quad == 0) {
; #pragma unroll
;             for (int mh = 0; mh < 2; ++mh) *(f32x2*)&red[((mh * 16 + l15) * 8 + wid) * 2] = (f32x2){s2[mh], ss2[mh]};
;         }
;         __syncthreads();
;         if (half == 0) issue_x(1);
; #pragma unroll
;         for (int mh = 0; mh < 2; ++mh) {
;             const int mt = half * 2 + mh, rl = mh * 16 + l15, row = mt * 16 + l15;
;             float s = 0.f, ss = 0.f;
; #pragma unroll
;             for (int w = 0; w < 4; ++w) { const f32x4 v = *(const f32x4*)&red[rl * 16 + 4 * w]; s += v[0] + v[2]; ss += v[1] + v[3]; }
;             const float mu = s * (1.f / 1024.f);
;             const float var = ss * (1.f / 1024.f) - mu * mu;
;             const float rs = rsqrtf(var + LN_EPS);
;             float* orow = xo + (r0 + row) * 1024 + wid * 128 + quad * 4;
;             bf16_t* brow = xbo + xb_off((int)r0 + row, wid * 128) + quad * 4;
;             const float* gp = GB + wid * 128 + quad * 4;
; #pragma unroll
;             for (int nt = 0; nt < 8; ++nt) {
	ds_read_b128 v[144:147], v200
	ds_read_b128 v[148:151], v201
	ds_read_b128 v[152:155], v202
	ds_read_b128 v[156:159], v203
	ds_read_b128 v[160:163], v200 offset:256
	ds_read_b128 v[164:167], v201 offset:256
	ds_read_b128 v[168:171], v202 offset:256
	ds_read_b128 v[172:175], v203 offset:256
	s_waitcnt lgkmcnt(7)
	v_fmac_f32_e32 v34, s58, v144
	v_fmac_f32_e32 v35, s58, v145
	v_fmac_f32_e32 v36, s58, v146
	v_fmac_f32_e32 v37, s58, v147
	v_mov_b32_e32 v196, v34
	v_mul_f32_e32 v197, v34, v34
	v_mov_b32_e32 v130, v35
	v_mul_f32_e32 v142, v35, v35
	v_add_f32_e32 v196, v196, v36
	v_fmac_f32_e32 v197, v36, v36
	v_add_f32_e32 v130, v130, v37
	v_fmac_f32_e32 v142, v37, v37
	s_waitcnt lgkmcnt(6)
	v_fmac_f32_e32 v30, s58, v148
	v_fmac_f32_e32 v31, s58, v149
	v_fmac_f32_e32 v32, s58, v150
	v_fmac_f32_e32 v33, s58, v151
	v_add_f32_e32 v196, v196, v30
	v_fmac_f32_e32 v197, v30, v30
	v_add_f32_e32 v130, v130, v31
	v_fmac_f32_e32 v142, v31, v31
	v_add_f32_e32 v196, v196, v32
	v_fmac_f32_e32 v197, v32, v32
	v_add_f32_e32 v130, v130, v33
	v_fmac_f32_e32 v142, v33, v33
	s_waitcnt lgkmcnt(5)
	v_fmac_f32_e32 v26, s58, v152
	v_fmac_f32_e32 v27, s58, v153
	v_fmac_f32_e32 v28, s58, v154
	v_fmac_f32_e32 v29, s58, v155
	v_add_f32_e32 v196, v196, v26
	v_fmac_f32_e32 v197, v26, v26
	v_add_f32_e32 v130, v130, v27
	v_fmac_f32_e32 v142, v27, v27
	v_add_f32_e32 v196, v196, v28
	v_fmac_f32_e32 v197, v28, v28
	v_add_f32_e32 v130, v130, v29
	v_fmac_f32_e32 v142, v29, v29
	s_waitcnt lgkmcnt(4)
	v_fmac_f32_e32 v22, s58, v156
	v_fmac_f32_e32 v23, s58, v157
	v_fmac_f32_e32 v24, s58, v158
	v_fmac_f32_e32 v25, s58, v159
	v_add_f32_e32 v196, v196, v22
	v_fmac_f32_e32 v197, v22, v22
	v_add_f32_e32 v130, v130, v23
	v_fmac_f32_e32 v142, v23, v23
	v_add_f32_e32 v196, v196, v24
	v_fmac_f32_e32 v197, v24, v24
	v_add_f32_e32 v130, v130, v25
	v_fmac_f32_e32 v142, v25, v25
	s_waitcnt lgkmcnt(3)
	v_fmac_f32_e32 v18, s58, v160
	v_fmac_f32_e32 v19, s58, v161
	v_fmac_f32_e32 v20, s58, v162
	v_fmac_f32_e32 v21, s58, v163
	v_add_f32_e32 v196, v196, v18
	v_fmac_f32_e32 v197, v18, v18
	v_add_f32_e32 v130, v130, v19
	v_fmac_f32_e32 v142, v19, v19
	v_add_f32_e32 v196, v196, v20
	v_fmac_f32_e32 v197, v20, v20
	v_add_f32_e32 v130, v130, v21
	v_fmac_f32_e32 v142, v21, v21
	s_waitcnt lgkmcnt(2)
	v_fmac_f32_e32 v14, s58, v164
	v_fmac_f32_e32 v15, s58, v165
	v_fmac_f32_e32 v16, s58, v166
	v_fmac_f32_e32 v17, s58, v167
	v_add_f32_e32 v196, v196, v14
	v_fmac_f32_e32 v197, v14, v14
	v_add_f32_e32 v130, v130, v15
	v_fmac_f32_e32 v142, v15, v15
	v_add_f32_e32 v196, v196, v16
	v_fmac_f32_e32 v197, v16, v16
	v_add_f32_e32 v130, v130, v17
	v_fmac_f32_e32 v142, v17, v17
	s_waitcnt lgkmcnt(1)
	v_fmac_f32_e32 v10, s58, v168
	v_fmac_f32_e32 v11, s58, v169
	v_fmac_f32_e32 v12, s58, v170
	v_fmac_f32_e32 v13, s58, v171
	v_add_f32_e32 v196, v196, v10
	v_fmac_f32_e32 v197, v10, v10
	v_add_f32_e32 v130, v130, v11
	v_fmac_f32_e32 v142, v11, v11
	v_add_f32_e32 v196, v196, v12
	v_fmac_f32_e32 v197, v12, v12
	v_add_f32_e32 v130, v130, v13
	v_fmac_f32_e32 v142, v13, v13
	s_waitcnt lgkmcnt(0)
	v_fmac_f32_e32 v6, s58, v172
	v_fmac_f32_e32 v7, s58, v173
	v_fmac_f32_e32 v8, s58, v174
	v_fmac_f32_e32 v9, s58, v175
	v_add_f32_e32 v196, v196, v6
	v_fmac_f32_e32 v197, v6, v6
	v_add_f32_e32 v130, v130, v7
	v_fmac_f32_e32 v142, v7, v7
	v_add_f32_e32 v196, v196, v8
	v_fmac_f32_e32 v197, v8, v8
	v_add_f32_e32 v130, v130, v9
	v_fmac_f32_e32 v142, v9, v9
	v_add_f32_e32 v196, v196, v130
	v_add_f32_e32 v197, v197, v142
	v_mov_b32_e32 v198, v196
	v_mov_b32_e32 v199, v197
	s_nop 1
	v_permlane16_swap_b32 v198, v196
	v_permlane16_swap_b32 v199, v197
	v_add_f32_e32 v196, v196, v198
	v_add_f32_e32 v197, v197, v199
	v_mov_b32_e32 v198, v196
	v_mov_b32_e32 v199, v197
	s_nop 1
	v_permlane32_swap_b32 v198, v196
	v_permlane32_swap_b32 v199, v197
	v_add_f32_e32 v196, v196, v198
	v_add_f32_e32 v197, v197, v199
	s_mov_b64 exec, 0xffff
	ds_write_b64 v134, v[196:197]
	s_mov_b64 exec, -1
	s_waitcnt lgkmcnt(0)
	s_barrier
	ds_read_b128 v[160:163], v135 offset:0
	ds_read_b128 v[164:167], v135 offset:16
	ds_read_b128 v[168:171], v135 offset:32
	ds_read_b128 v[172:175], v135 offset:48
	s_waitcnt lgkmcnt(0)
	v_add_f32_e32 v160, v160, v162
	v_add_f32_e32 v161, v161, v163
	v_add_f32_e32 v164, v164, v166
	v_add_f32_e32 v165, v165, v167
	v_add_f32_e32 v168, v168, v170
	v_add_f32_e32 v169, v169, v171
	v_add_f32_e32 v172, v172, v174
	v_add_f32_e32 v173, v173, v175
	v_add_f32_e32 v160, v160, v164
	v_add_f32_e32 v161, v161, v165
	v_add_f32_e32 v168, v168, v172
	v_add_f32_e32 v169, v169, v173
	v_add_f32_e32 v160, v160, v168
	v_add_f32_e32 v161, v161, v169
	v_mul_f32_e32 v192, 0x3a800000, v160
	v_mul_f32_e32 v193, 0x3a800000, v161
	v_fma_f32 v193, -v192, v192, v193
	v_add_f32_e32 v193, 0x3727c5ac, v193
	v_rsq_f32_e32 v193, v193
	s_nop 0
	s_add_u32 s94, s78, 0x800
	s_addc_u32 s95, s79, 0
	ds_read_b128 v[176:179], v136
	ds_read_b128 v[180:183], v136 offset:4096
	ds_read_b128 v[184:187], v136 offset:64
	ds_read_b128 v[188:191], v136 offset:4160
	s_waitcnt lgkmcnt(2)
	v_sub_f32_e32 v34, v34, v192
	v_mul_f32_e32 v34, v34, v193
	v_fma_f32 v34, v176, v34, v180
	v_sub_f32_e32 v35, v35, v192
	v_mul_f32_e32 v35, v35, v193
	v_fma_f32 v35, v177, v35, v181
	v_sub_f32_e32 v36, v36, v192
	v_mul_f32_e32 v36, v36, v193
	v_fma_f32 v36, v178, v36, v182
	v_sub_f32_e32 v37, v37, v192
	v_mul_f32_e32 v37, v37, v193
	v_fma_f32 v37, v179, v37, v183
	v_cvt_pk_bf16_f32 v144, v34, v35
	v_cvt_pk_bf16_f32 v145, v36, v37
	ds_read_b128 v[176:179], v136 offset:128
	ds_read_b128 v[180:183], v136 offset:4224
	s_waitcnt lgkmcnt(2)
; DI unsigned pk2(float lo, float hi) { const f32x2 v = {lo, hi}; const bf16x2_t b = __builtin_convertvector(v, bf16x2_t); return __builtin_bit_cast(unsigned, b); }
; DI size_t xb_off(int tok, int col) { return ((size_t)(((tok >> 7) * 32 + (col >> 5)) * 128 + (tok & 127))) * 32 + (col & 31); }
; DI void unit_O(const Params& p, char* lds, int l, int tile, int glu_tiles, int tile_b) {
;     ...
;             float* orow = xo + (r0 + row) * 1024 + wid * 128 + quad * 4;
;             bf16_t* brow = xbo + xb_off((int)r0 + row, wid * 128) + quad * 4;
;             const float* gp = GB + wid * 128 + quad * 4;
; #pragma unroll
;             for (int nt = 0; nt < 8; ++nt) {
;                 const f32x4 g = *(const f32x4*)(gp + nt * 16), bb = *(const f32x4*)(gp + 1024 + nt * 16);
;                 f32x4 o;
; #pragma unroll
;                 for (int i = 0; i < 4; ++i) o[i] = (acc[mt][nt][i] - mu) * rs * g[i] + bb[i];
;                 if (l == 0) *(u32x2*)(brow + (nt >> 1) * 4096 + (nt & 1) * 16) = (u32x2){pk2(o[0], o[1]), pk2(o[2], o[3])};
;                 else *(f32x4*)(orow + nt * 16) = o;
;             }
	v_sub_f32_e32 v30, v30, v192
	v_mul_f32_e32 v30, v30, v193
	v_fma_f32 v30, v184, v30, v188
	v_sub_f32_e32 v31, v31, v192
	v_mul_f32_e32 v31, v31, v193
	v_fma_f32 v31, v185, v31, v189
	v_sub_f32_e32 v32, v32, v192
	v_mul_f32_e32 v32, v32, v193
	v_fma_f32 v32, v186, v32, v190
	v_sub_f32_e32 v33, v33, v192
	v_mul_f32_e32 v33, v33, v193
	v_fma_f32 v33, v187, v33, v191
	v_cvt_pk_bf16_f32 v146, v30, v31
	v_cvt_pk_bf16_f32 v147, v32, v33
	s_nop 1
	v_permlane16_swap_b32 v144, v146
	v_permlane16_swap_b32 v145, v147
	global_store_dwordx4 v137, v[144:147], s[94:95]
	s_add_u32 s94, s94, 0x2000
	s_addc_u32 s95, s95, 0
	ds_read_b128 v[184:187], v136 offset:192
	ds_read_b128 v[188:191], v136 offset:4288
	s_waitcnt lgkmcnt(2)
	v_sub_f32_e32 v26, v26, v192
	v_mul_f32_e32 v26, v26, v193
	v_fma_f32 v26, v176, v26, v180
	v_sub_f32_e32 v27, v27, v192
	v_mul_f32_e32 v27, v27, v193
	v_fma_f32 v27, v177, v27, v181
	v_sub_f32_e32 v28, v28, v192
	v_mul_f32_e32 v28, v28, v193
	v_fma_f32 v28, v178, v28, v182
	v_sub_f32_e32 v29, v29, v192
	v_mul_f32_e32 v29, v29, v193
	v_fma_f32 v29, v179, v29, v183
	v_cvt_pk_bf16_f32 v152, v26, v27
	v_cvt_pk_bf16_f32 v153, v28, v29
	ds_read_b128 v[176:179], v136 offset:256
	ds_read_b128 v[180:183], v136 offset:4352
	s_waitcnt lgkmcnt(2)
	v_sub_f32_e32 v22, v22, v192
	v_mul_f32_e32 v22, v22, v193
	v_fma_f32 v22, v184, v22, v188
	v_sub_f32_e32 v23, v23, v192
	v_mul_f32_e32 v23, v23, v193
	v_fma_f32 v23, v185, v23, v189
	v_sub_f32_e32 v24, v24, v192
	v_mul_f32_e32 v24, v24, v193
	v_fma_f32 v24, v186, v24, v190
	v_sub_f32_e32 v25, v25, v192
	v_mul_f32_e32 v25, v25, v193
	v_fma_f32 v25, v187, v25, v191
	v_cvt_pk_bf16_f32 v154, v22, v23
	v_cvt_pk_bf16_f32 v155, v24, v25
	s_nop 1
	v_permlane16_swap_b32 v152, v154
	v_permlane16_swap_b32 v153, v155
	global_store_dwordx4 v137, v[152:155], s[94:95]
	s_add_u32 s94, s94, 0x2000
	s_addc_u32 s95, s95, 0
	ds_read_b128 v[184:187], v136 offset:320
	ds_read_b128 v[188:191], v136 offset:4416
	s_waitcnt lgkmcnt(2)
	v_sub_f32_e32 v18, v18, v192
	v_mul_f32_e32 v18, v18, v193
	v_fma_f32 v18, v176, v18, v180
	v_sub_f32_e32 v19, v19, v192
	v_mul_f32_e32 v19, v19, v193
	v_fma_f32 v19, v177, v19, v181
	v_sub_f32_e32 v20, v20, v192
	v_mul_f32_e32 v20, v20, v193
	v_fma_f32 v20, v178, v20, v182
	v_sub_f32_e32 v21, v21, v192
	v_mul_f32_e32 v21, v21, v193
	v_fma_f32 v21, v179, v21, v183
	v_cvt_pk_bf16_f32 v144, v18, v19
	v_cvt_pk_bf16_f32 v145, v20, v21
	ds_read_b128 v[176:179], v136 offset:384
	ds_read_b128 v[180:183], v136 offset:4480
	s_waitcnt lgkmcnt(2)
	v_sub_f32_e32 v14, v14, v192
	v_mul_f32_e32 v14, v14, v193
	v_fma_f32 v14, v184, v14, v188
	v_sub_f32_e32 v15, v15, v192
	v_mul_f32_e32 v15, v15, v193
	v_fma_f32 v15, v185, v15, v189
	v_sub_f32_e32 v16, v16, v192
	v_mul_f32_e32 v16, v16, v193
	v_fma_f32 v16, v186, v16, v190
	v_sub_f32_e32 v17, v17, v192
	v_mul_f32_e32 v17, v17, v193
	v_fma_f32 v17, v187, v17, v191
	v_cvt_pk_bf16_f32 v146, v14, v15
	v_cvt_pk_bf16_f32 v147, v16, v17
	s_nop 1
	v_permlane16_swap_b32 v144, v146
	v_permlane16_swap_b32 v145, v147
	global_store_dwordx4 v137, v[144:147], s[94:95]
	s_add_u32 s94, s94, 0x2000
	s_addc_u32 s95, s95, 0
	ds_read_b128 v[184:187], v136 offset:448
	ds_read_b128 v[188:191], v136 offset:4544
	s_waitcnt lgkmcnt(2)
	v_sub_f32_e32 v10, v10, v192
	v_mul_f32_e32 v10, v10, v193
	v_fma_f32 v10, v176, v10, v180
	v_sub_f32_e32 v11, v11, v192
	v_mul_f32_e32 v11, v11, v193
	v_fma_f32 v11, v177, v11, v181
	v_sub_f32_e32 v12, v12, v192
	v_mul_f32_e32 v12, v12, v193
	v_fma_f32 v12, v178, v12, v182
	v_sub_f32_e32 v13, v13, v192
	v_mul_f32_e32 v13, v13, v193
	v_fma_f32 v13, v179, v13, v183
	v_cvt_pk_bf16_f32 v152, v10, v11
	v_cvt_pk_bf16_f32 v153, v12, v13
	s_waitcnt lgkmcnt(0)
	v_sub_f32_e32 v6, v6, v192
	v_mul_f32_e32 v6, v6, v193
	v_fma_f32 v6, v184, v6, v188
	v_sub_f32_e32 v7, v7, v192
	v_mul_f32_e32 v7, v7, v193
	v_fma_f32 v7, v185, v7, v189
	v_sub_f32_e32 v8, v8, v192
	v_mul_f32_e32 v8, v8, v193
	v_fma_f32 v8, v186, v8, v190
	v_sub_f32_e32 v9, v9, v192
	v_mul_f32_e32 v9, v9, v193
	v_fma_f32 v9, v187, v9, v191
	v_cvt_pk_bf16_f32 v154, v6, v7
	v_cvt_pk_bf16_f32 v155, v8, v9
	s_nop 1
	v_permlane16_swap_b32 v152, v154
	v_permlane16_swap_b32 v153, v155
	global_store_dwordx4 v137, v[152:155], s[94:95]
	s_waitcnt vmcnt(8) lgkmcnt(0)
	s_barrier
; DI void unit_O(const Params& p, char* lds, int l, int tile, int glu_tiles, int tile_b) {
;     ...
;         float s2[2], ss2[2];
; #pragma unroll
;         for (int mh = 0; mh < 2; ++mh) {
;             const int mt = half * 2 + mh, rl = mh * 16 + l15;
;             float s = 0.f, ss = 0.f;
; #pragma unroll
;             for (int nt = 0; nt < 8; ++nt) {
;                 f32x4 xr;
;                 if (l == 0) {
;                     const int chunk = wid * 32 + nt * 4 + quad;
;                     xr = *(const f32x4*)(XR + rl * 4096 + ((chunk ^ l15) << 4));
;                 } else {
;                     const u32x2 hb = *(const u32x2*)(XR + ((wid * 4 + (nt >> 1)) * 32 + rl) * 64 + (nt & 1) * 32 + quad * 8);
;                     xr = (f32x4){bf2f(hb[0] & 0xffffu), bf2f(hb[0] >> 16), bf2f(hb[1] & 0xffffu), bf2f(hb[1] >> 16)};
;                 }
; #pragma unroll
;                 for (int i = 0; i < 4; ++i) { const float v = acc[mt][nt][i] + DN_ALPHA * xr[i]; acc[mt][nt][i] = v; s += v; ss += v * v; }
;             }
;             s2[mh] = s; ss2[mh] = ss;
;         }
; #pragma unroll
;         for (int mh = 0; mh < 2; ++mh) { s2[mh] += __shfl_xor(s2[mh], 16); ss2[mh] += __shfl_xor(ss2[mh], 16); }
; #pragma unroll
;         for (int mh = 0; mh < 2; ++mh) { s2[mh] += __shfl_xor(s2[mh], 32); ss2[mh] += __shfl_xor(ss2[mh], 32); }
;         if (quad == 0) {
; #pragma unroll
;             for (int mh = 0; mh < 2; ++mh) *(f32x2*)&red[((mh * 16 + l15) * 8 + wid) * 2] = (f32x2){s2[mh], ss2[mh]};
;         }
;         __syncthreads();
;         if (half == 0) issue_x(1);
; #pragma unroll
;         for (int mh = 0; mh < 2; ++mh) {
;             const int mt = half * 2 + mh, rl = mh * 16 + l15, row = mt * 16 + l15;
;             float s = 0.f, ss = 0.f;
; #pragma unroll
;             for (int w = 0; w < 4; ++w) { const f32x4 v = *(const f32x4*)&red[rl * 16 + 4 * w]; s += v[0] + v[2]; ss += v[1] + v[3]; }
;             const float mu = s * (1.f / 1024.f);
;             const float var = ss * (1.f / 1024.f) - mu * mu;
;             const float rs = rsqrtf(var + LN_EPS);
;             float* orow = xo + (r0 + row) * 1024 + wid * 128 + quad * 4;
;             bf16_t* brow = xbo + xb_off((int)r0 + row, wid * 128) + quad * 4;
;             const float* gp = GB + wid * 128 + quad * 4;
; #pragma unroll
;             for (int nt = 0; nt < 8; ++nt) {
	ds_read_b128 v[144:147], v204
	ds_read_b128 v[148:151], v205
	ds_read_b128 v[152:155], v206
	ds_read_b128 v[156:159], v207
	ds_read_b128 v[160:163], v204 offset:256
	ds_read_b128 v[164:167], v205 offset:256
	ds_read_b128 v[168:171], v206 offset:256
	ds_read_b128 v[172:175], v207 offset:256
	s_waitcnt lgkmcnt(7)
	v_fmac_f32_e32 v62, s58, v144
	v_fmac_f32_e32 v63, s58, v145
	v_fmac_f32_e32 v64, s58, v146
	v_fmac_f32_e32 v65, s58, v147
	v_mov_b32_e32 v196, v62
	v_mul_f32_e32 v197, v62, v62
	v_mov_b32_e32 v130, v63
	v_mul_f32_e32 v142, v63, v63
	v_add_f32_e32 v196, v196, v64
	v_fmac_f32_e32 v197, v64, v64
	v_add_f32_e32 v130, v130, v65
	v_fmac_f32_e32 v142, v65, v65
	s_waitcnt lgkmcnt(6)
	v_fmac_f32_e32 v58, s58, v148
	v_fmac_f32_e32 v59, s58, v149
	v_fmac_f32_e32 v60, s58, v150
	v_fmac_f32_e32 v61, s58, v151
	v_add_f32_e32 v196, v196, v58
	v_fmac_f32_e32 v197, v58, v58
	v_add_f32_e32 v130, v130, v59
	v_fmac_f32_e32 v142, v59, v59
	v_add_f32_e32 v196, v196, v60
	v_fmac_f32_e32 v197, v60, v60
	v_add_f32_e32 v130, v130, v61
	v_fmac_f32_e32 v142, v61, v61
	s_waitcnt lgkmcnt(5)
	v_fmac_f32_e32 v54, s58, v152
	v_fmac_f32_e32 v55, s58, v153
	v_fmac_f32_e32 v56, s58, v154
	v_fmac_f32_e32 v57, s58, v155
	v_add_f32_e32 v196, v196, v54
	v_fmac_f32_e32 v197, v54, v54
	v_add_f32_e32 v130, v130, v55
	v_fmac_f32_e32 v142, v55, v55
	v_add_f32_e32 v196, v196, v56
	v_fmac_f32_e32 v197, v56, v56
	v_add_f32_e32 v130, v130, v57
	v_fmac_f32_e32 v142, v57, v57
	s_waitcnt lgkmcnt(4)
	v_fmac_f32_e32 v50, s58, v156
	v_fmac_f32_e32 v51, s58, v157
	v_fmac_f32_e32 v52, s58, v158
	v_fmac_f32_e32 v53, s58, v159
	v_add_f32_e32 v196, v196, v50
	v_fmac_f32_e32 v197, v50, v50
	v_add_f32_e32 v130, v130, v51
	v_fmac_f32_e32 v142, v51, v51
	v_add_f32_e32 v196, v196, v52
	v_fmac_f32_e32 v197, v52, v52
	v_add_f32_e32 v130, v130, v53
	v_fmac_f32_e32 v142, v53, v53
	s_waitcnt lgkmcnt(3)
	v_fmac_f32_e32 v46, s58, v160
	v_fmac_f32_e32 v47, s58, v161
	v_fmac_f32_e32 v48, s58, v162
	v_fmac_f32_e32 v49, s58, v163
	v_add_f32_e32 v196, v196, v46
	v_fmac_f32_e32 v197, v46, v46
	v_add_f32_e32 v130, v130, v47
	v_fmac_f32_e32 v142, v47, v47
	v_add_f32_e32 v196, v196, v48
	v_fmac_f32_e32 v197, v48, v48
	v_add_f32_e32 v130, v130, v49
	v_fmac_f32_e32 v142, v49, v49
	s_waitcnt lgkmcnt(2)
	v_fmac_f32_e32 v42, s58, v164
	v_fmac_f32_e32 v43, s58, v165
	v_fmac_f32_e32 v44, s58, v166
	v_fmac_f32_e32 v45, s58, v167
	v_add_f32_e32 v196, v196, v42
	v_fmac_f32_e32 v197, v42, v42
	v_add_f32_e32 v130, v130, v43
	v_fmac_f32_e32 v142, v43, v43
	v_add_f32_e32 v196, v196, v44
	v_fmac_f32_e32 v197, v44, v44
	v_add_f32_e32 v130, v130, v45
	v_fmac_f32_e32 v142, v45, v45
	s_waitcnt lgkmcnt(1)
	v_fmac_f32_e32 v38, s58, v168
	v_fmac_f32_e32 v39, s58, v169
	v_fmac_f32_e32 v40, s58, v170
	v_fmac_f32_e32 v41, s58, v171
	v_add_f32_e32 v196, v196, v38
	v_fmac_f32_e32 v197, v38, v38
	v_add_f32_e32 v130, v130, v39
	v_fmac_f32_e32 v142, v39, v39
	v_add_f32_e32 v196, v196, v40
	v_fmac_f32_e32 v197, v40, v40
	v_add_f32_e32 v130, v130, v41
	v_fmac_f32_e32 v142, v41, v41
	s_waitcnt lgkmcnt(0)
	v_fmac_f32_e32 v2, s58, v172
	v_fmac_f32_e32 v3, s58, v173
	v_fmac_f32_e32 v4, s58, v174
	v_fmac_f32_e32 v5, s58, v175
	v_add_f32_e32 v196, v196, v2
	v_fmac_f32_e32 v197, v2, v2
	v_add_f32_e32 v130, v130, v3
	v_fmac_f32_e32 v142, v3, v3
	v_add_f32_e32 v196, v196, v4
	v_fmac_f32_e32 v197, v4, v4
	v_add_f32_e32 v130, v130, v5
	v_fmac_f32_e32 v142, v5, v5
	v_add_f32_e32 v196, v196, v130
	v_add_f32_e32 v197, v197, v142
	v_mov_b32_e32 v198, v196
	v_mov_b32_e32 v199, v197
	s_nop 1
	v_permlane16_swap_b32 v198, v196
	v_permlane16_swap_b32 v199, v197
	v_add_f32_e32 v196, v196, v198
	v_add_f32_e32 v197, v197, v199
	v_mov_b32_e32 v198, v196
	v_mov_b32_e32 v199, v197
	s_nop 1
	v_permlane32_swap_b32 v198, v196
	v_permlane32_swap_b32 v199, v197
	v_add_f32_e32 v196, v196, v198
	v_add_f32_e32 v197, v197, v199
	s_mov_b64 exec, 0xffff
	ds_write_b64 v134, v[196:197]
	s_mov_b64 exec, -1
	s_waitcnt lgkmcnt(0)
	s_barrier
	ds_read_b128 v[160:163], v135 offset:0
	ds_read_b128 v[164:167], v135 offset:16
	ds_read_b128 v[168:171], v135 offset:32
	ds_read_b128 v[172:175], v135 offset:48
	s_waitcnt lgkmcnt(0)
	v_add_f32_e32 v160, v160, v162
	v_add_f32_e32 v161, v161, v163
	v_add_f32_e32 v164, v164, v166
	v_add_f32_e32 v165, v165, v167
	v_add_f32_e32 v168, v168, v170
	v_add_f32_e32 v169, v169, v171
	v_add_f32_e32 v172, v172, v174
	v_add_f32_e32 v173, v173, v175
	v_add_f32_e32 v160, v160, v164
	v_add_f32_e32 v161, v161, v165
	v_add_f32_e32 v168, v168, v172
	v_add_f32_e32 v169, v169, v173
	v_add_f32_e32 v160, v160, v168
	v_add_f32_e32 v161, v161, v169
	v_mul_f32_e32 v192, 0x3a800000, v160
	v_mul_f32_e32 v193, 0x3a800000, v161
	v_fma_f32 v193, -v192, v192, v193
	v_add_f32_e32 v193, 0x3727c5ac, v193
	v_rsq_f32_e32 v193, v193
	s_nop 0
	s_add_u32 s94, s78, 0xc00
	s_addc_u32 s95, s79, 0
	ds_read_b128 v[176:179], v136
	ds_read_b128 v[180:183], v136 offset:4096
	ds_read_b128 v[184:187], v136 offset:64
	ds_read_b128 v[188:191], v136 offset:4160
	s_waitcnt lgkmcnt(2)
	v_sub_f32_e32 v62, v62, v192
	v_mul_f32_e32 v62, v62, v193
	v_fma_f32 v62, v176, v62, v180
	v_sub_f32_e32 v63, v63, v192
	v_mul_f32_e32 v63, v63, v193
	v_fma_f32 v63, v177, v63, v181
	v_sub_f32_e32 v64, v64, v192
	v_mul_f32_e32 v64, v64, v193
	v_fma_f32 v64, v178, v64, v182
	v_sub_f32_e32 v65, v65, v192
	v_mul_f32_e32 v65, v65, v193
	v_fma_f32 v65, v179, v65, v183
	v_cvt_pk_bf16_f32 v144, v62, v63
	v_cvt_pk_bf16_f32 v145, v64, v65
	ds_read_b128 v[176:179], v136 offset:128
	ds_read_b128 v[180:183], v136 offset:4224
	s_waitcnt lgkmcnt(2)
; DI unsigned pk2(float lo, float hi) { const f32x2 v = {lo, hi}; const bf16x2_t b = __builtin_convertvector(v, bf16x2_t); return __builtin_bit_cast(unsigned, b); }
; DI size_t xb_off(int tok, int col) { return ((size_t)(((tok >> 7) * 32 + (col >> 5)) * 128 + (tok & 127))) * 32 + (col & 31); }
; DI void unit_O(const Params& p, char* lds, int l, int tile, int glu_tiles, int tile_b) {
;     ...
;             float* orow = xo + (r0 + row) * 1024 + wid * 128 + quad * 4;
;             bf16_t* brow = xbo + xb_off((int)r0 + row, wid * 128) + quad * 4;
;             const float* gp = GB + wid * 128 + quad * 4;
; #pragma unroll
;             for (int nt = 0; nt < 8; ++nt) {
;                 const f32x4 g = *(const f32x4*)(gp + nt * 16), bb = *(const f32x4*)(gp + 1024 + nt * 16);
;                 f32x4 o;
; #pragma unroll
;                 for (int i = 0; i < 4; ++i) o[i] = (acc[mt][nt][i] - mu) * rs * g[i] + bb[i];
;                 if (l == 0) *(u32x2*)(brow + (nt >> 1) * 4096 + (nt & 1) * 16) = (u32x2){pk2(o[0], o[1]), pk2(o[2], o[3])};
;                 else *(f32x4*)(orow + nt * 16) = o;
;             }
	v_sub_f32_e32 v58, v58, v192
	v_mul_f32_e32 v58, v58, v193
	v_fma_f32 v58, v184, v58, v188
	v_sub_f32_e32 v59, v59, v192
	v_mul_f32_e32 v59, v59, v193
	v_fma_f32 v59, v185, v59, v189
	v_sub_f32_e32 v60, v60, v192
	v_mul_f32_e32 v60, v60, v193
	v_fma_f32 v60, v186, v60, v190
	v_sub_f32_e32 v61, v61, v192
	v_mul_f32_e32 v61, v61, v193
	v_fma_f32 v61, v187, v61, v191
	v_cvt_pk_bf16_f32 v146, v58, v59
	v_cvt_pk_bf16_f32 v147, v60, v61
	s_nop 1
	v_permlane16_swap_b32 v144, v146
	v_permlane16_swap_b32 v145, v147
	global_store_dwordx4 v137, v[144:147], s[94:95]
	s_add_u32 s94, s94, 0x2000
	s_addc_u32 s95, s95, 0
	ds_read_b128 v[184:187], v136 offset:192
	ds_read_b128 v[188:191], v136 offset:4288
	s_waitcnt lgkmcnt(2)
	v_sub_f32_e32 v54, v54, v192
	v_mul_f32_e32 v54, v54, v193
	v_fma_f32 v54, v176, v54, v180
	v_sub_f32_e32 v55, v55, v192
	v_mul_f32_e32 v55, v55, v193
	v_fma_f32 v55, v177, v55, v181
	v_sub_f32_e32 v56, v56, v192
	v_mul_f32_e32 v56, v56, v193
	v_fma_f32 v56, v178, v56, v182
	v_sub_f32_e32 v57, v57, v192
	v_mul_f32_e32 v57, v57, v193
	v_fma_f32 v57, v179, v57, v183
	v_cvt_pk_bf16_f32 v152, v54, v55
	v_cvt_pk_bf16_f32 v153, v56, v57
	ds_read_b128 v[176:179], v136 offset:256
	ds_read_b128 v[180:183], v136 offset:4352
	s_waitcnt lgkmcnt(2)
	v_sub_f32_e32 v50, v50, v192
	v_mul_f32_e32 v50, v50, v193
	v_fma_f32 v50, v184, v50, v188
	v_sub_f32_e32 v51, v51, v192
	v_mul_f32_e32 v51, v51, v193
	v_fma_f32 v51, v185, v51, v189
	v_sub_f32_e32 v52, v52, v192
	v_mul_f32_e32 v52, v52, v193
	v_fma_f32 v52, v186, v52, v190
	v_sub_f32_e32 v53, v53, v192
	v_mul_f32_e32 v53, v53, v193
	v_fma_f32 v53, v187, v53, v191
	v_cvt_pk_bf16_f32 v154, v50, v51
	v_cvt_pk_bf16_f32 v155, v52, v53
	s_nop 1
	v_permlane16_swap_b32 v152, v154
	v_permlane16_swap_b32 v153, v155
	global_store_dwordx4 v137, v[152:155], s[94:95]
	s_add_u32 s94, s94, 0x2000
	s_addc_u32 s95, s95, 0
	ds_read_b128 v[184:187], v136 offset:320
	ds_read_b128 v[188:191], v136 offset:4416
	s_waitcnt lgkmcnt(2)
	v_sub_f32_e32 v46, v46, v192
	v_mul_f32_e32 v46, v46, v193
	v_fma_f32 v46, v176, v46, v180
	v_sub_f32_e32 v47, v47, v192
	v_mul_f32_e32 v47, v47, v193
	v_fma_f32 v47, v177, v47, v181
	v_sub_f32_e32 v48, v48, v192
	v_mul_f32_e32 v48, v48, v193
	v_fma_f32 v48, v178, v48, v182
	v_sub_f32_e32 v49, v49, v192
	v_mul_f32_e32 v49, v49, v193
	v_fma_f32 v49, v179, v49, v183
	v_cvt_pk_bf16_f32 v144, v46, v47
	v_cvt_pk_bf16_f32 v145, v48, v49
	ds_read_b128 v[176:179], v136 offset:384
	ds_read_b128 v[180:183], v136 offset:4480
	s_waitcnt lgkmcnt(2)
	v_sub_f32_e32 v42, v42, v192
	v_mul_f32_e32 v42, v42, v193
	v_fma_f32 v42, v184, v42, v188
	v_sub_f32_e32 v43, v43, v192
	v_mul_f32_e32 v43, v43, v193
	v_fma_f32 v43, v185, v43, v189
	v_sub_f32_e32 v44, v44, v192
	v_mul_f32_e32 v44, v44, v193
	v_fma_f32 v44, v186, v44, v190
	v_sub_f32_e32 v45, v45, v192
	v_mul_f32_e32 v45, v45, v193
	v_fma_f32 v45, v187, v45, v191
	v_cvt_pk_bf16_f32 v146, v42, v43
	v_cvt_pk_bf16_f32 v147, v44, v45
	s_nop 1
	v_permlane16_swap_b32 v144, v146
	v_permlane16_swap_b32 v145, v147
	global_store_dwordx4 v137, v[144:147], s[94:95]
	s_add_u32 s94, s94, 0x2000
	s_addc_u32 s95, s95, 0
	ds_read_b128 v[184:187], v136 offset:448
	ds_read_b128 v[188:191], v136 offset:4544
	s_waitcnt lgkmcnt(2)
	v_sub_f32_e32 v38, v38, v192
	v_mul_f32_e32 v38, v38, v193
	v_fma_f32 v38, v176, v38, v180
	v_sub_f32_e32 v39, v39, v192
	v_mul_f32_e32 v39, v39, v193
	v_fma_f32 v39, v177, v39, v181
	v_sub_f32_e32 v40, v40, v192
	v_mul_f32_e32 v40, v40, v193
	v_fma_f32 v40, v178, v40, v182
	v_sub_f32_e32 v41, v41, v192
	v_mul_f32_e32 v41, v41, v193
	v_fma_f32 v41, v179, v41, v183
	v_cvt_pk_bf16_f32 v152, v38, v39
	v_cvt_pk_bf16_f32 v153, v40, v41
	s_waitcnt lgkmcnt(0)
	v_sub_f32_e32 v2, v2, v192
	v_mul_f32_e32 v2, v2, v193
	v_fma_f32 v2, v184, v2, v188
	v_sub_f32_e32 v3, v3, v192
	v_mul_f32_e32 v3, v3, v193
	v_fma_f32 v3, v185, v3, v189
	v_sub_f32_e32 v4, v4, v192
	v_mul_f32_e32 v4, v4, v193
	v_fma_f32 v4, v186, v4, v190
	v_sub_f32_e32 v5, v5, v192
	v_mul_f32_e32 v5, v5, v193
	v_fma_f32 v5, v187, v5, v191
	v_cvt_pk_bf16_f32 v154, v2, v3
	v_cvt_pk_bf16_f32 v155, v4, v5
	s_nop 1
	v_permlane16_swap_b32 v152, v154
	v_permlane16_swap_b32 v153, v155
	global_store_dwordx4 v137, v[152:155], s[94:95]
	s_branch .Le1_done
; DI void unit_O(const Params& p, char* lds, int l, int tile, int glu_tiles, int tile_b) {
;     ...
; #pragma unroll 1
;             for (int i = 0; i < 8; ++i) {
;                 const int pc = (wid * 8 + i + (xrot >> 1)) & 63, kt = pc >> 1, sub = pc & 1;
;                 __builtin_amdgcn_global_load_lds((const unsigned*)(xbres + ((size_t)kt * 128 + half * 32) * 32 + sub * 512 + lane * 8), (unsigned*)(XR + pc * 1024 + lane * 16), 16, 0, 0);
;             }
;         }
;     };
;     issue_x(0);
;     {
;         const float* gsrc = (tid < 256) ? (p.ln_g + l * 1024 + tid * 4) : (p.ln_b + l * 1024 + (tid - 256) * 4);
;         *(f32x4*)(GB + tid * 4) = *(const f32x4*)gsrc;
;     }
;     float* xo = (l == 0) ? WS_PTR(float, OFF_X1) : p.out;
;     bf16_t* xbo = WS_PTR(bf16_t, OFF_XB1);
; #pragma unroll
;     for (int half = 0; half < 2; ++half) {
;         if (half == 0) wait_vm<0>();
;         else wait_vm<8>();
;         __syncthreads();
;         float s2[2], ss2[2];
; #pragma unroll
;         for (int mh = 0; mh < 2; ++mh) {
;             const int mt = half * 2 + mh, rl = mh * 16 + l15;
;             float s = 0.f, ss = 0.f;
; #pragma unroll
;             for (int nt = 0; nt < 8; ++nt) {
;                 f32x4 xr;
;                 if (l == 0) {
;                     const int chunk = wid * 32 + nt * 4 + quad;
;                     xr = *(const f32x4*)(XR + rl * 4096 + ((chunk ^ l15) << 4));
;                 } else {
;                     const u32x2 hb = *(const u32x2*)(XR + ((wid * 4 + (nt >> 1)) * 32 + rl) * 64 + (nt & 1) * 32 + quad * 8);
;                     xr = (f32x4){bf2f(hb[0] & 0xffffu), bf2f(hb[0] >> 16), bf2f(hb[1] & 0xffffu), bf2f(hb[1] >> 16)};
;                 }
; #pragma unroll
;                 for (int i = 0; i < 4; ++i) { const float v = acc[mt][nt][i] + DN_ALPHA * xr[i]; acc[mt][nt][i] = v; s += v; ss += v * v; }
;             }
;             s2[mh] = s; ss2[mh] = ss;
;         }
; #pragma unroll
;         for (int mh = 0; mh < 2; ++mh) { s2[mh] += __shfl_xor(s2[mh], 16); ss2[mh] += __shfl_xor(ss2[mh], 16); }
; #pragma unroll
;         for (int mh = 0; mh < 2; ++mh) { s2[mh] += __shfl_xor(s2[mh], 32); ss2[mh] += __shfl_xor(ss2[mh], 32); }
;         if (quad == 0) {
; #pragma unroll
;             for (int mh = 0; mh < 2; ++mh) *(f32x2*)&red[((mh * 16 + l15) * 8 + wid) * 2] = (f32x2){s2[mh], ss2[mh]};
;         }
.Le1_l1:
	s_lshr_b32 s40, s34, 1
	s_lshl_b32 s40, s40, 18
	s_and_b32 s94, s34, 1
	s_lshl_b32 s94, s94, 12
	s_add_u32 s40, s40, s94
	s_lshl_b32 s91, s90, 12
	s_lshl_b32 s94, s90, 15
	s_add_u32 s96, s56, s40
	s_addc_u32 s97, s57, 0
	s_add_u32 s96, s96, s94
	s_addc_u32 s97, s97, 0
	v_lshlrev_b32_e32 v208, 4, v141
	v_lshlrev_b32_e32 v133, 12, v140
	v_lshl_add_u32 v133, v138, 6, v133
	v_lshl_add_u32 v133, v139, 3, v133
	v_lshlrev_b32_e32 v137, 12, v138
	v_lshl_add_u32 v137, v140, 9, v137
	v_lshl_add_u32 v137, v139, 4, v137
	s_lshl_b32 s40, s34, 18
	s_add_u32 s78, s16, s40
	s_addc_u32 s79, s17, 0
	s_add_u32 s92, s96, 0x0
	s_addc_u32 s93, s97, 0
	s_add_u32 s40, s91, 0x0
	s_mov_b32 m0, s40
	s_nop 0
	global_load_lds_dwordx4 v208, s[92:93]
	s_add_u32 s92, s92, 0x2000
	s_addc_u32 s93, s93, 0
	s_add_u32 m0, m0, 0x400
	s_nop 0
	global_load_lds_dwordx4 v208, s[92:93]
	s_add_u32 s92, s92, 0x2000
	s_addc_u32 s93, s93, 0
	s_add_u32 m0, m0, 0x400
	s_nop 0
	global_load_lds_dwordx4 v208, s[92:93]
	s_add_u32 s92, s92, 0x2000
	s_addc_u32 s93, s93, 0
	s_add_u32 m0, m0, 0x400
	s_nop 0
	global_load_lds_dwordx4 v208, s[92:93]
	s_add_u32 s92, s96, 0x400
	s_addc_u32 s93, s97, 0
	s_add_u32 s40, s91, 0x8000
	s_mov_b32 m0, s40
	s_nop 0
	global_load_lds_dwordx4 v208, s[92:93]
	s_add_u32 s92, s92, 0x2000
	s_addc_u32 s93, s93, 0
	s_add_u32 m0, m0, 0x400
	s_nop 0
	global_load_lds_dwordx4 v208, s[92:93]
	s_add_u32 s92, s92, 0x2000
	s_addc_u32 s93, s93, 0
	s_add_u32 m0, m0, 0x400
	s_nop 0
	global_load_lds_dwordx4 v208, s[92:93]
	s_add_u32 s92, s92, 0x2000
	s_addc_u32 s93, s93, 0
	s_add_u32 m0, m0, 0x400
	s_nop 0
	global_load_lds_dwordx4 v208, s[92:93]
	s_waitcnt vmcnt(8)
	ds_write_b128 v143, v[176:179]
	s_waitcnt vmcnt(4) lgkmcnt(0)
	s_barrier
	ds_read_b64 v[180:181], v133 offset:0
	ds_read_b64 v[182:183], v133 offset:32
	ds_read_b64 v[184:185], v133 offset:1024
	ds_read_b64 v[186:187], v133 offset:1056
	ds_read_b64 v[188:189], v133 offset:2048
	ds_read_b64 v[190:191], v133 offset:2080
	ds_read_b64 v[192:193], v133 offset:3072
	ds_read_b64 v[194:195], v133 offset:3104
	s_waitcnt lgkmcnt(7)
	v_lshlrev_b32_e32 v144, 16, v180
	v_and_b32_e32 v145, 0xffff0000, v180
	v_lshlrev_b32_e32 v146, 16, v181
	v_and_b32_e32 v147, 0xffff0000, v181
	v_fmac_f32_e32 v98, s58, v144
	v_fmac_f32_e32 v99, s58, v145
	v_fmac_f32_e32 v100, s58, v146
	v_fmac_f32_e32 v101, s58, v147
	v_mov_b32_e32 v196, v98
	v_mul_f32_e32 v197, v98, v98
	v_mov_b32_e32 v130, v99
	v_mul_f32_e32 v142, v99, v99
	v_add_f32_e32 v196, v196, v100
	v_fmac_f32_e32 v197, v100, v100
	v_add_f32_e32 v130, v130, v101
	v_fmac_f32_e32 v142, v101, v101
	s_waitcnt lgkmcnt(6)
	v_lshlrev_b32_e32 v148, 16, v182
	v_and_b32_e32 v149, 0xffff0000, v182
	v_lshlrev_b32_e32 v150, 16, v183
	v_and_b32_e32 v151, 0xffff0000, v183
	v_fmac_f32_e32 v94, s58, v148
	v_fmac_f32_e32 v95, s58, v149
	v_fmac_f32_e32 v96, s58, v150
	v_fmac_f32_e32 v97, s58, v151
	v_add_f32_e32 v196, v196, v94
	v_fmac_f32_e32 v197, v94, v94
	v_add_f32_e32 v130, v130, v95
	v_fmac_f32_e32 v142, v95, v95
	v_add_f32_e32 v196, v196, v96
	v_fmac_f32_e32 v197, v96, v96
	v_add_f32_e32 v130, v130, v97
	v_fmac_f32_e32 v142, v97, v97
	s_waitcnt lgkmcnt(5)
	v_lshlrev_b32_e32 v152, 16, v184
	v_and_b32_e32 v153, 0xffff0000, v184
	v_lshlrev_b32_e32 v154, 16, v185
	v_and_b32_e32 v155, 0xffff0000, v185
	v_fmac_f32_e32 v90, s58, v152
	v_fmac_f32_e32 v91, s58, v153
	v_fmac_f32_e32 v92, s58, v154
	v_fmac_f32_e32 v93, s58, v155
	v_add_f32_e32 v196, v196, v90
	v_fmac_f32_e32 v197, v90, v90
	v_add_f32_e32 v130, v130, v91
	v_fmac_f32_e32 v142, v91, v91
	v_add_f32_e32 v196, v196, v92
	v_fmac_f32_e32 v197, v92, v92
	v_add_f32_e32 v130, v130, v93
	v_fmac_f32_e32 v142, v93, v93
	s_waitcnt lgkmcnt(4)
	v_lshlrev_b32_e32 v156, 16, v186
	v_and_b32_e32 v157, 0xffff0000, v186
	v_lshlrev_b32_e32 v158, 16, v187
	v_and_b32_e32 v159, 0xffff0000, v187
	v_fmac_f32_e32 v86, s58, v156
	v_fmac_f32_e32 v87, s58, v157
	v_fmac_f32_e32 v88, s58, v158
	v_fmac_f32_e32 v89, s58, v159
	v_add_f32_e32 v196, v196, v86
	v_fmac_f32_e32 v197, v86, v86
	v_add_f32_e32 v130, v130, v87
	v_fmac_f32_e32 v142, v87, v87
	v_add_f32_e32 v196, v196, v88
	v_fmac_f32_e32 v197, v88, v88
	v_add_f32_e32 v130, v130, v89
	v_fmac_f32_e32 v142, v89, v89
	s_waitcnt lgkmcnt(3)
	v_lshlrev_b32_e32 v160, 16, v188
	v_and_b32_e32 v161, 0xffff0000, v188
	v_lshlrev_b32_e32 v162, 16, v189
	v_and_b32_e32 v163, 0xffff0000, v189
	v_fmac_f32_e32 v82, s58, v160
	v_fmac_f32_e32 v83, s58, v161
	v_fmac_f32_e32 v84, s58, v162
	v_fmac_f32_e32 v85, s58, v163
	v_add_f32_e32 v196, v196, v82
	v_fmac_f32_e32 v197, v82, v82
	v_add_f32_e32 v130, v130, v83
	v_fmac_f32_e32 v142, v83, v83
	v_add_f32_e32 v196, v196, v84
	v_fmac_f32_e32 v197, v84, v84
	v_add_f32_e32 v130, v130, v85
	v_fmac_f32_e32 v142, v85, v85
	s_waitcnt lgkmcnt(2)
	v_lshlrev_b32_e32 v164, 16, v190
	v_and_b32_e32 v165, 0xffff0000, v190
	v_lshlrev_b32_e32 v166, 16, v191
	v_and_b32_e32 v167, 0xffff0000, v191
	v_fmac_f32_e32 v78, s58, v164
	v_fmac_f32_e32 v79, s58, v165
	v_fmac_f32_e32 v80, s58, v166
	v_fmac_f32_e32 v81, s58, v167
	v_add_f32_e32 v196, v196, v78
	v_fmac_f32_e32 v197, v78, v78
	v_add_f32_e32 v130, v130, v79
	v_fmac_f32_e32 v142, v79, v79
	v_add_f32_e32 v196, v196, v80
	v_fmac_f32_e32 v197, v80, v80
	v_add_f32_e32 v130, v130, v81
	v_fmac_f32_e32 v142, v81, v81
	s_waitcnt lgkmcnt(1)
	v_lshlrev_b32_e32 v168, 16, v192
	v_and_b32_e32 v169, 0xffff0000, v192
	v_lshlrev_b32_e32 v170, 16, v193
	v_and_b32_e32 v171, 0xffff0000, v193
	v_fmac_f32_e32 v74, s58, v168
	v_fmac_f32_e32 v75, s58, v169
	v_fmac_f32_e32 v76, s58, v170
	v_fmac_f32_e32 v77, s58, v171
	v_add_f32_e32 v196, v196, v74
	v_fmac_f32_e32 v197, v74, v74
	v_add_f32_e32 v130, v130, v75
	v_fmac_f32_e32 v142, v75, v75
	v_add_f32_e32 v196, v196, v76
	v_fmac_f32_e32 v197, v76, v76
	v_add_f32_e32 v130, v130, v77
	v_fmac_f32_e32 v142, v77, v77
	s_waitcnt lgkmcnt(0)
	v_lshlrev_b32_e32 v172, 16, v194
	v_and_b32_e32 v173, 0xffff0000, v194
	v_lshlrev_b32_e32 v174, 16, v195
	v_and_b32_e32 v175, 0xffff0000, v195
	v_fmac_f32_e32 v70, s58, v172
	v_fmac_f32_e32 v71, s58, v173
	v_fmac_f32_e32 v72, s58, v174
	v_fmac_f32_e32 v73, s58, v175
	v_add_f32_e32 v196, v196, v70
	v_fmac_f32_e32 v197, v70, v70
	v_add_f32_e32 v130, v130, v71
	v_fmac_f32_e32 v142, v71, v71
	v_add_f32_e32 v196, v196, v72
	v_fmac_f32_e32 v197, v72, v72
	v_add_f32_e32 v130, v130, v73
	v_fmac_f32_e32 v142, v73, v73
	v_add_f32_e32 v196, v196, v130
	v_add_f32_e32 v197, v197, v142
	v_mov_b32_e32 v198, v196
	v_mov_b32_e32 v199, v197
	s_nop 1
	v_permlane16_swap_b32 v198, v196
	v_permlane16_swap_b32 v199, v197
	v_add_f32_e32 v196, v196, v198
	v_add_f32_e32 v197, v197, v199
	v_mov_b32_e32 v198, v196
	v_mov_b32_e32 v199, v197
	s_nop 1
	v_permlane32_swap_b32 v198, v196
	v_permlane32_swap_b32 v199, v197
	v_add_f32_e32 v196, v196, v198
	v_add_f32_e32 v197, v197, v199
	s_mov_b64 exec, 0xffff
	ds_write_b64 v134, v[196:197]
	s_mov_b64 exec, -1
	s_waitcnt lgkmcnt(0)
	s_barrier
; DI unsigned pk2(float lo, float hi) { const f32x2 v = {lo, hi}; const bf16x2_t b = __builtin_convertvector(v, bf16x2_t); return __builtin_bit_cast(unsigned, b); }
; DI size_t xb_off(int tok, int col) { return ((size_t)(((tok >> 7) * 32 + (col >> 5)) * 128 + (tok & 127))) * 32 + (col & 31); }
; DI void unit_O(const Params& p, char* lds, int l, int tile, int glu_tiles, int tile_b) {
;     ...
;         if (half == 0) issue_x(1);
; #pragma unroll
;         for (int mh = 0; mh < 2; ++mh) {
;             const int mt = half * 2 + mh, rl = mh * 16 + l15, row = mt * 16 + l15;
;             float s = 0.f, ss = 0.f;
; #pragma unroll
;             for (int w = 0; w < 4; ++w) { const f32x4 v = *(const f32x4*)&red[rl * 16 + 4 * w]; s += v[0] + v[2]; ss += v[1] + v[3]; }
;             const float mu = s * (1.f / 1024.f);
;             const float var = ss * (1.f / 1024.f) - mu * mu;
;             const float rs = rsqrtf(var + LN_EPS);
;             float* orow = xo + (r0 + row) * 1024 + wid * 128 + quad * 4;
;             bf16_t* brow = xbo + xb_off((int)r0 + row, wid * 128) + quad * 4;
;             const float* gp = GB + wid * 128 + quad * 4;
; #pragma unroll
;             for (int nt = 0; nt < 8; ++nt) {
;                 const f32x4 g = *(const f32x4*)(gp + nt * 16), bb = *(const f32x4*)(gp + 1024 + nt * 16);
;                 f32x4 o;
; #pragma unroll
;                 for (int i = 0; i < 4; ++i) o[i] = (acc[mt][nt][i] - mu) * rs * g[i] + bb[i];
;                 if (l == 0) *(u32x2*)(brow + (nt >> 1) * 4096 + (nt & 1) * 16) = (u32x2){pk2(o[0], o[1]), pk2(o[2], o[3])};
;                 else *(f32x4*)(orow + nt * 16) = o;
;             }
;         }
	s_add_u32 s92, s96, 0x800
	s_addc_u32 s93, s97, 0
	s_add_u32 s40, s91, 0x0
	s_mov_b32 m0, s40
	s_nop 0
	global_load_lds_dwordx4 v208, s[92:93]
	s_add_u32 s92, s92, 0x2000
	s_addc_u32 s93, s93, 0
	s_add_u32 m0, m0, 0x400
	s_nop 0
	global_load_lds_dwordx4 v208, s[92:93]
	s_add_u32 s92, s92, 0x2000
	s_addc_u32 s93, s93, 0
	s_add_u32 m0, m0, 0x400
	s_nop 0
	global_load_lds_dwordx4 v208, s[92:93]
	s_add_u32 s92, s92, 0x2000
	s_addc_u32 s93, s93, 0
	s_add_u32 m0, m0, 0x400
	s_nop 0
	global_load_lds_dwordx4 v208, s[92:93]
	ds_read_b128 v[160:163], v135 offset:0
	ds_read_b128 v[164:167], v135 offset:16
	ds_read_b128 v[168:171], v135 offset:32
	ds_read_b128 v[172:175], v135 offset:48
	s_waitcnt lgkmcnt(0)
	v_add_f32_e32 v160, v160, v162
	v_add_f32_e32 v161, v161, v163
	v_add_f32_e32 v164, v164, v166
	v_add_f32_e32 v165, v165, v167
	v_add_f32_e32 v168, v168, v170
	v_add_f32_e32 v169, v169, v171
	v_add_f32_e32 v172, v172, v174
	v_add_f32_e32 v173, v173, v175
	v_add_f32_e32 v160, v160, v164
	v_add_f32_e32 v161, v161, v165
	v_add_f32_e32 v168, v168, v172
	v_add_f32_e32 v169, v169, v173
	v_add_f32_e32 v160, v160, v168
	v_add_f32_e32 v161, v161, v169
	v_mul_f32_e32 v192, 0x3a800000, v160
	v_mul_f32_e32 v193, 0x3a800000, v161
	v_fma_f32 v193, -v192, v192, v193
	v_add_f32_e32 v193, 0x3727c5ac, v193
	v_rsq_f32_e32 v193, v193
	s_nop 0
	s_add_u32 s94, s78, 0x0
	s_addc_u32 s95, s79, 0
	ds_read_b128 v[176:179], v136
	ds_read_b128 v[180:183], v136 offset:4096
	ds_read_b128 v[184:187], v136 offset:64
	ds_read_b128 v[188:191], v136 offset:4160
	s_waitcnt lgkmcnt(2)
	v_sub_f32_e32 v98, v98, v192
	v_mul_f32_e32 v98, v98, v193
	v_fma_f32 v98, v176, v98, v180
	v_sub_f32_e32 v99, v99, v192
	v_mul_f32_e32 v99, v99, v193
	v_fma_f32 v99, v177, v99, v181
	v_sub_f32_e32 v100, v100, v192
	v_mul_f32_e32 v100, v100, v193
	v_fma_f32 v100, v178, v100, v182
	v_sub_f32_e32 v101, v101, v192
	v_mul_f32_e32 v101, v101, v193
	v_fma_f32 v101, v179, v101, v183
	global_store_dwordx4 v137, v[98:101], s[94:95]
	ds_read_b128 v[176:179], v136 offset:128
	ds_read_b128 v[180:183], v136 offset:4224
	s_waitcnt lgkmcnt(2)
	v_sub_f32_e32 v94, v94, v192
	v_mul_f32_e32 v94, v94, v193
	v_fma_f32 v94, v184, v94, v188
	v_sub_f32_e32 v95, v95, v192
	v_mul_f32_e32 v95, v95, v193
	v_fma_f32 v95, v185, v95, v189
	v_sub_f32_e32 v96, v96, v192
	v_mul_f32_e32 v96, v96, v193
	v_fma_f32 v96, v186, v96, v190
	v_sub_f32_e32 v97, v97, v192
	v_mul_f32_e32 v97, v97, v193
	v_fma_f32 v97, v187, v97, v191
	global_store_dwordx4 v137, v[94:97], s[94:95] offset:64
	ds_read_b128 v[184:187], v136 offset:192
	ds_read_b128 v[188:191], v136 offset:4288
	s_waitcnt lgkmcnt(2)
	v_sub_f32_e32 v90, v90, v192
	v_mul_f32_e32 v90, v90, v193
	v_fma_f32 v90, v176, v90, v180
	v_sub_f32_e32 v91, v91, v192
	v_mul_f32_e32 v91, v91, v193
	v_fma_f32 v91, v177, v91, v181
	v_sub_f32_e32 v92, v92, v192
	v_mul_f32_e32 v92, v92, v193
	v_fma_f32 v92, v178, v92, v182
	v_sub_f32_e32 v93, v93, v192
	v_mul_f32_e32 v93, v93, v193
	v_fma_f32 v93, v179, v93, v183
	global_store_dwordx4 v137, v[90:93], s[94:95] offset:128
	ds_read_b128 v[176:179], v136 offset:256
	ds_read_b128 v[180:183], v136 offset:4352
	s_waitcnt lgkmcnt(2)
	v_sub_f32_e32 v86, v86, v192
	v_mul_f32_e32 v86, v86, v193
	v_fma_f32 v86, v184, v86, v188
	v_sub_f32_e32 v87, v87, v192
	v_mul_f32_e32 v87, v87, v193
	v_fma_f32 v87, v185, v87, v189
	v_sub_f32_e32 v88, v88, v192
	v_mul_f32_e32 v88, v88, v193
	v_fma_f32 v88, v186, v88, v190
	v_sub_f32_e32 v89, v89, v192
	v_mul_f32_e32 v89, v89, v193
	v_fma_f32 v89, v187, v89, v191
	global_store_dwordx4 v137, v[86:89], s[94:95] offset:192
	ds_read_b128 v[184:187], v136 offset:320
	ds_read_b128 v[188:191], v136 offset:4416
	s_waitcnt lgkmcnt(2)
	v_sub_f32_e32 v82, v82, v192
	v_mul_f32_e32 v82, v82, v193
	v_fma_f32 v82, v176, v82, v180
	v_sub_f32_e32 v83, v83, v192
	v_mul_f32_e32 v83, v83, v193
	v_fma_f32 v83, v177, v83, v181
	v_sub_f32_e32 v84, v84, v192
	v_mul_f32_e32 v84, v84, v193
	v_fma_f32 v84, v178, v84, v182
	v_sub_f32_e32 v85, v85, v192
	v_mul_f32_e32 v85, v85, v193
	v_fma_f32 v85, v179, v85, v183
	global_store_dwordx4 v137, v[82:85], s[94:95] offset:256
	ds_read_b128 v[176:179], v136 offset:384
	ds_read_b128 v[180:183], v136 offset:4480
	s_waitcnt lgkmcnt(2)
	v_sub_f32_e32 v78, v78, v192
	v_mul_f32_e32 v78, v78, v193
	v_fma_f32 v78, v184, v78, v188
	v_sub_f32_e32 v79, v79, v192
	v_mul_f32_e32 v79, v79, v193
	v_fma_f32 v79, v185, v79, v189
	v_sub_f32_e32 v80, v80, v192
	v_mul_f32_e32 v80, v80, v193
	v_fma_f32 v80, v186, v80, v190
	v_sub_f32_e32 v81, v81, v192
	v_mul_f32_e32 v81, v81, v193
	v_fma_f32 v81, v187, v81, v191
	global_store_dwordx4 v137, v[78:81], s[94:95] offset:320
	ds_read_b128 v[184:187], v136 offset:448
	ds_read_b128 v[188:191], v136 offset:4544
	s_waitcnt lgkmcnt(2)
	v_sub_f32_e32 v74, v74, v192
	v_mul_f32_e32 v74, v74, v193
	v_fma_f32 v74, v176, v74, v180
	v_sub_f32_e32 v75, v75, v192
	v_mul_f32_e32 v75, v75, v193
	v_fma_f32 v75, v177, v75, v181
	v_sub_f32_e32 v76, v76, v192
	v_mul_f32_e32 v76, v76, v193
	v_fma_f32 v76, v178, v76, v182
	v_sub_f32_e32 v77, v77, v192
	v_mul_f32_e32 v77, v77, v193
	v_fma_f32 v77, v179, v77, v183
	global_store_dwordx4 v137, v[74:77], s[94:95] offset:384
	s_waitcnt lgkmcnt(0)
	v_sub_f32_e32 v70, v70, v192
	v_mul_f32_e32 v70, v70, v193
	v_fma_f32 v70, v184, v70, v188
	v_sub_f32_e32 v71, v71, v192
	v_mul_f32_e32 v71, v71, v193
	v_fma_f32 v71, v185, v71, v189
	v_sub_f32_e32 v72, v72, v192
	v_mul_f32_e32 v72, v72, v193
	v_fma_f32 v72, v186, v72, v190
	v_sub_f32_e32 v73, v73, v192
	v_mul_f32_e32 v73, v73, v193
	v_fma_f32 v73, v187, v73, v191
	global_store_dwordx4 v137, v[70:73], s[94:95] offset:448
	s_waitcnt vmcnt(12) lgkmcnt(0)
	s_barrier
; DI float bf2f(unsigned b) { return __uint_as_float(b << 16); }
; DI void unit_O(const Params& p, char* lds, int l, int tile, int glu_tiles, int tile_b) {
;     ...
;         float s2[2], ss2[2];
; #pragma unroll
;         for (int mh = 0; mh < 2; ++mh) {
;             const int mt = half * 2 + mh, rl = mh * 16 + l15;
;             float s = 0.f, ss = 0.f;
; #pragma unroll
;             for (int nt = 0; nt < 8; ++nt) {
;                 f32x4 xr;
;                 if (l == 0) {
;                     const int chunk = wid * 32 + nt * 4 + quad;
;                     xr = *(const f32x4*)(XR + rl * 4096 + ((chunk ^ l15) << 4));
;                 } else {
;                     const u32x2 hb = *(const u32x2*)(XR + ((wid * 4 + (nt >> 1)) * 32 + rl) * 64 + (nt & 1) * 32 + quad * 8);
;                     xr = (f32x4){bf2f(hb[0] & 0xffffu), bf2f(hb[0] >> 16), bf2f(hb[1] & 0xffffu), bf2f(hb[1] >> 16)};
;                 }
; #pragma unroll
;                 for (int i = 0; i < 4; ++i) { const float v = acc[mt][nt][i] + DN_ALPHA * xr[i]; acc[mt][nt][i] = v; s += v; ss += v * v; }
;             }
;             s2[mh] = s; ss2[mh] = ss;
;         }
; #pragma unroll
;         for (int mh = 0; mh < 2; ++mh) { s2[mh] += __shfl_xor(s2[mh], 16); ss2[mh] += __shfl_xor(ss2[mh], 16); }
; #pragma unroll
;         for (int mh = 0; mh < 2; ++mh) { s2[mh] += __shfl_xor(s2[mh], 32); ss2[mh] += __shfl_xor(ss2[mh], 32); }
;         if (quad == 0) {
; #pragma unroll
;             for (int mh = 0; mh < 2; ++mh) *(f32x2*)&red[((mh * 16 + l15) * 8 + wid) * 2] = (f32x2){s2[mh], ss2[mh]};
;         }
	ds_read_b64 v[180:181], v133 offset:32768
	ds_read_b64 v[182:183], v133 offset:32800
	ds_read_b64 v[184:185], v133 offset:33792
	ds_read_b64 v[186:187], v133 offset:33824
	ds_read_b64 v[188:189], v133 offset:34816
	ds_read_b64 v[190:191], v133 offset:34848
	ds_read_b64 v[192:193], v133 offset:35840
	ds_read_b64 v[194:195], v133 offset:35872
	s_waitcnt lgkmcnt(7)
	v_lshlrev_b32_e32 v144, 16, v180
	v_and_b32_e32 v145, 0xffff0000, v180
	v_lshlrev_b32_e32 v146, 16, v181
	v_and_b32_e32 v147, 0xffff0000, v181
	v_fmac_f32_e32 v126, s58, v144
	v_fmac_f32_e32 v127, s58, v145
	v_fmac_f32_e32 v128, s58, v146
	v_fmac_f32_e32 v129, s58, v147
	v_mov_b32_e32 v196, v126
	v_mul_f32_e32 v197, v126, v126
	v_mov_b32_e32 v130, v127
	v_mul_f32_e32 v142, v127, v127
	v_add_f32_e32 v196, v196, v128
	v_fmac_f32_e32 v197, v128, v128
	v_add_f32_e32 v130, v130, v129
	v_fmac_f32_e32 v142, v129, v129
	s_waitcnt lgkmcnt(6)
	v_lshlrev_b32_e32 v148, 16, v182
	v_and_b32_e32 v149, 0xffff0000, v182
	v_lshlrev_b32_e32 v150, 16, v183
	v_and_b32_e32 v151, 0xffff0000, v183
	v_fmac_f32_e32 v122, s58, v148
	v_fmac_f32_e32 v123, s58, v149
	v_fmac_f32_e32 v124, s58, v150
	v_fmac_f32_e32 v125, s58, v151
	v_add_f32_e32 v196, v196, v122
	v_fmac_f32_e32 v197, v122, v122
	v_add_f32_e32 v130, v130, v123
	v_fmac_f32_e32 v142, v123, v123
	v_add_f32_e32 v196, v196, v124
	v_fmac_f32_e32 v197, v124, v124
	v_add_f32_e32 v130, v130, v125
	v_fmac_f32_e32 v142, v125, v125
	s_waitcnt lgkmcnt(5)
	v_lshlrev_b32_e32 v152, 16, v184
	v_and_b32_e32 v153, 0xffff0000, v184
	v_lshlrev_b32_e32 v154, 16, v185
	v_and_b32_e32 v155, 0xffff0000, v185
	v_fmac_f32_e32 v118, s58, v152
	v_fmac_f32_e32 v119, s58, v153
	v_fmac_f32_e32 v120, s58, v154
	v_fmac_f32_e32 v121, s58, v155
	v_add_f32_e32 v196, v196, v118
	v_fmac_f32_e32 v197, v118, v118
	v_add_f32_e32 v130, v130, v119
	v_fmac_f32_e32 v142, v119, v119
	v_add_f32_e32 v196, v196, v120
	v_fmac_f32_e32 v197, v120, v120
	v_add_f32_e32 v130, v130, v121
	v_fmac_f32_e32 v142, v121, v121
	s_waitcnt lgkmcnt(4)
	v_lshlrev_b32_e32 v156, 16, v186
	v_and_b32_e32 v157, 0xffff0000, v186
	v_lshlrev_b32_e32 v158, 16, v187
	v_and_b32_e32 v159, 0xffff0000, v187
	v_fmac_f32_e32 v114, s58, v156
	v_fmac_f32_e32 v115, s58, v157
	v_fmac_f32_e32 v116, s58, v158
	v_fmac_f32_e32 v117, s58, v159
	v_add_f32_e32 v196, v196, v114
	v_fmac_f32_e32 v197, v114, v114
	v_add_f32_e32 v130, v130, v115
	v_fmac_f32_e32 v142, v115, v115
	v_add_f32_e32 v196, v196, v116
	v_fmac_f32_e32 v197, v116, v116
	v_add_f32_e32 v130, v130, v117
	v_fmac_f32_e32 v142, v117, v117
	s_waitcnt lgkmcnt(3)
	v_lshlrev_b32_e32 v160, 16, v188
	v_and_b32_e32 v161, 0xffff0000, v188
	v_lshlrev_b32_e32 v162, 16, v189
	v_and_b32_e32 v163, 0xffff0000, v189
	v_fmac_f32_e32 v110, s58, v160
	v_fmac_f32_e32 v111, s58, v161
	v_fmac_f32_e32 v112, s58, v162
	v_fmac_f32_e32 v113, s58, v163
	v_add_f32_e32 v196, v196, v110
	v_fmac_f32_e32 v197, v110, v110
	v_add_f32_e32 v130, v130, v111
	v_fmac_f32_e32 v142, v111, v111
	v_add_f32_e32 v196, v196, v112
	v_fmac_f32_e32 v197, v112, v112
	v_add_f32_e32 v130, v130, v113
	v_fmac_f32_e32 v142, v113, v113
	s_waitcnt lgkmcnt(2)
	v_lshlrev_b32_e32 v164, 16, v190
	v_and_b32_e32 v165, 0xffff0000, v190
	v_lshlrev_b32_e32 v166, 16, v191
	v_and_b32_e32 v167, 0xffff0000, v191
	v_fmac_f32_e32 v106, s58, v164
	v_fmac_f32_e32 v107, s58, v165
	v_fmac_f32_e32 v108, s58, v166
	v_fmac_f32_e32 v109, s58, v167
	v_add_f32_e32 v196, v196, v106
	v_fmac_f32_e32 v197, v106, v106
	v_add_f32_e32 v130, v130, v107
	v_fmac_f32_e32 v142, v107, v107
	v_add_f32_e32 v196, v196, v108
	v_fmac_f32_e32 v197, v108, v108
	v_add_f32_e32 v130, v130, v109
	v_fmac_f32_e32 v142, v109, v109
	s_waitcnt lgkmcnt(1)
	v_lshlrev_b32_e32 v168, 16, v192
	v_and_b32_e32 v169, 0xffff0000, v192
	v_lshlrev_b32_e32 v170, 16, v193
	v_and_b32_e32 v171, 0xffff0000, v193
	v_fmac_f32_e32 v102, s58, v168
	v_fmac_f32_e32 v103, s58, v169
	v_fmac_f32_e32 v104, s58, v170
	v_fmac_f32_e32 v105, s58, v171
	v_add_f32_e32 v196, v196, v102
	v_fmac_f32_e32 v197, v102, v102
	v_add_f32_e32 v130, v130, v103
	v_fmac_f32_e32 v142, v103, v103
	v_add_f32_e32 v196, v196, v104
	v_fmac_f32_e32 v197, v104, v104
	v_add_f32_e32 v130, v130, v105
	v_fmac_f32_e32 v142, v105, v105
	s_waitcnt lgkmcnt(0)
	v_lshlrev_b32_e32 v172, 16, v194
	v_and_b32_e32 v173, 0xffff0000, v194
	v_lshlrev_b32_e32 v174, 16, v195
	v_and_b32_e32 v175, 0xffff0000, v195
	v_fmac_f32_e32 v66, s58, v172
	v_fmac_f32_e32 v67, s58, v173
	v_fmac_f32_e32 v68, s58, v174
	v_fmac_f32_e32 v69, s58, v175
	v_add_f32_e32 v196, v196, v66
	v_fmac_f32_e32 v197, v66, v66
	v_add_f32_e32 v130, v130, v67
	v_fmac_f32_e32 v142, v67, v67
	v_add_f32_e32 v196, v196, v68
	v_fmac_f32_e32 v197, v68, v68
	v_add_f32_e32 v130, v130, v69
	v_fmac_f32_e32 v142, v69, v69
	v_add_f32_e32 v196, v196, v130
	v_add_f32_e32 v197, v197, v142
	v_mov_b32_e32 v198, v196
	v_mov_b32_e32 v199, v197
	s_nop 1
	v_permlane16_swap_b32 v198, v196
	v_permlane16_swap_b32 v199, v197
	v_add_f32_e32 v196, v196, v198
	v_add_f32_e32 v197, v197, v199
	v_mov_b32_e32 v198, v196
	v_mov_b32_e32 v199, v197
	s_nop 1
	v_permlane32_swap_b32 v198, v196
	v_permlane32_swap_b32 v199, v197
	v_add_f32_e32 v196, v196, v198
	v_add_f32_e32 v197, v197, v199
	s_mov_b64 exec, 0xffff
	ds_write_b64 v134, v[196:197]
	s_mov_b64 exec, -1
	s_waitcnt lgkmcnt(0)
	s_barrier
; DI unsigned pk2(float lo, float hi) { const f32x2 v = {lo, hi}; const bf16x2_t b = __builtin_convertvector(v, bf16x2_t); return __builtin_bit_cast(unsigned, b); }
; DI size_t xb_off(int tok, int col) { return ((size_t)(((tok >> 7) * 32 + (col >> 5)) * 128 + (tok & 127))) * 32 + (col & 31); }
; DI void unit_O(const Params& p, char* lds, int l, int tile, int glu_tiles, int tile_b) {
;     ...
;         if (half == 0) issue_x(1);
; #pragma unroll
;         for (int mh = 0; mh < 2; ++mh) {
;             const int mt = half * 2 + mh, rl = mh * 16 + l15, row = mt * 16 + l15;
;             float s = 0.f, ss = 0.f;
; #pragma unroll
;             for (int w = 0; w < 4; ++w) { const f32x4 v = *(const f32x4*)&red[rl * 16 + 4 * w]; s += v[0] + v[2]; ss += v[1] + v[3]; }
;             const float mu = s * (1.f / 1024.f);
;             const float var = ss * (1.f / 1024.f) - mu * mu;
;             const float rs = rsqrtf(var + LN_EPS);
;             float* orow = xo + (r0 + row) * 1024 + wid * 128 + quad * 4;
;             bf16_t* brow = xbo + xb_off((int)r0 + row, wid * 128) + quad * 4;
;             const float* gp = GB + wid * 128 + quad * 4;
; #pragma unroll
;             for (int nt = 0; nt < 8; ++nt) {
;                 const f32x4 g = *(const f32x4*)(gp + nt * 16), bb = *(const f32x4*)(gp + 1024 + nt * 16);
;                 f32x4 o;
; #pragma unroll
;                 for (int i = 0; i < 4; ++i) o[i] = (acc[mt][nt][i] - mu) * rs * g[i] + bb[i];
;                 if (l == 0) *(u32x2*)(brow + (nt >> 1) * 4096 + (nt & 1) * 16) = (u32x2){pk2(o[0], o[1]), pk2(o[2], o[3])};
;                 else *(f32x4*)(orow + nt * 16) = o;
;             }
;         }
	s_add_u32 s92, s96, 0xc00
	s_addc_u32 s93, s97, 0
	s_add_u32 s40, s91, 0x8000
	s_mov_b32 m0, s40
	s_nop 0
	global_load_lds_dwordx4 v208, s[92:93]
	s_add_u32 s92, s92, 0x2000
	s_addc_u32 s93, s93, 0
	s_add_u32 m0, m0, 0x400
	s_nop 0
	global_load_lds_dwordx4 v208, s[92:93]
	s_add_u32 s92, s92, 0x2000
	s_addc_u32 s93, s93, 0
	s_add_u32 m0, m0, 0x400
	s_nop 0
	global_load_lds_dwordx4 v208, s[92:93]
	s_add_u32 s92, s92, 0x2000
	s_addc_u32 s93, s93, 0
	s_add_u32 m0, m0, 0x400
	s_nop 0
	global_load_lds_dwordx4 v208, s[92:93]
	ds_read_b128 v[160:163], v135 offset:0
	ds_read_b128 v[164:167], v135 offset:16
	ds_read_b128 v[168:171], v135 offset:32
	ds_read_b128 v[172:175], v135 offset:48
	s_waitcnt lgkmcnt(0)
	v_add_f32_e32 v160, v160, v162
	v_add_f32_e32 v161, v161, v163
	v_add_f32_e32 v164, v164, v166
	v_add_f32_e32 v165, v165, v167
	v_add_f32_e32 v168, v168, v170
	v_add_f32_e32 v169, v169, v171
	v_add_f32_e32 v172, v172, v174
	v_add_f32_e32 v173, v173, v175
	v_add_f32_e32 v160, v160, v164
	v_add_f32_e32 v161, v161, v165
	v_add_f32_e32 v168, v168, v172
	v_add_f32_e32 v169, v169, v173
	v_add_f32_e32 v160, v160, v168
	v_add_f32_e32 v161, v161, v169
	v_mul_f32_e32 v192, 0x3a800000, v160
	v_mul_f32_e32 v193, 0x3a800000, v161
	v_fma_f32 v193, -v192, v192, v193
	v_add_f32_e32 v193, 0x3727c5ac, v193
	v_rsq_f32_e32 v193, v193
	s_nop 0
	s_add_u32 s94, s78, 0x10000
	s_addc_u32 s95, s79, 0
	ds_read_b128 v[176:179], v136
	ds_read_b128 v[180:183], v136 offset:4096
	ds_read_b128 v[184:187], v136 offset:64
	ds_read_b128 v[188:191], v136 offset:4160
	s_waitcnt lgkmcnt(2)
	v_sub_f32_e32 v126, v126, v192
	v_mul_f32_e32 v126, v126, v193
	v_fma_f32 v126, v176, v126, v180
	v_sub_f32_e32 v127, v127, v192
	v_mul_f32_e32 v127, v127, v193
	v_fma_f32 v127, v177, v127, v181
	v_sub_f32_e32 v128, v128, v192
	v_mul_f32_e32 v128, v128, v193
	v_fma_f32 v128, v178, v128, v182
	v_sub_f32_e32 v129, v129, v192
	v_mul_f32_e32 v129, v129, v193
	v_fma_f32 v129, v179, v129, v183
	global_store_dwordx4 v137, v[126:129], s[94:95]
	ds_read_b128 v[176:179], v136 offset:128
	ds_read_b128 v[180:183], v136 offset:4224
	s_waitcnt lgkmcnt(2)
	v_sub_f32_e32 v122, v122, v192
	v_mul_f32_e32 v122, v122, v193
	v_fma_f32 v122, v184, v122, v188
	v_sub_f32_e32 v123, v123, v192
	v_mul_f32_e32 v123, v123, v193
	v_fma_f32 v123, v185, v123, v189
	v_sub_f32_e32 v124, v124, v192
	v_mul_f32_e32 v124, v124, v193
	v_fma_f32 v124, v186, v124, v190
	v_sub_f32_e32 v125, v125, v192
	v_mul_f32_e32 v125, v125, v193
	v_fma_f32 v125, v187, v125, v191
	global_store_dwordx4 v137, v[122:125], s[94:95] offset:64
	ds_read_b128 v[184:187], v136 offset:192
	ds_read_b128 v[188:191], v136 offset:4288
	s_waitcnt lgkmcnt(2)
	v_sub_f32_e32 v118, v118, v192
	v_mul_f32_e32 v118, v118, v193
	v_fma_f32 v118, v176, v118, v180
	v_sub_f32_e32 v119, v119, v192
	v_mul_f32_e32 v119, v119, v193
	v_fma_f32 v119, v177, v119, v181
	v_sub_f32_e32 v120, v120, v192
	v_mul_f32_e32 v120, v120, v193
	v_fma_f32 v120, v178, v120, v182
	v_sub_f32_e32 v121, v121, v192
	v_mul_f32_e32 v121, v121, v193
	v_fma_f32 v121, v179, v121, v183
	global_store_dwordx4 v137, v[118:121], s[94:95] offset:128
	ds_read_b128 v[176:179], v136 offset:256
	ds_read_b128 v[180:183], v136 offset:4352
	s_waitcnt lgkmcnt(2)
	v_sub_f32_e32 v114, v114, v192
	v_mul_f32_e32 v114, v114, v193
	v_fma_f32 v114, v184, v114, v188
	v_sub_f32_e32 v115, v115, v192
	v_mul_f32_e32 v115, v115, v193
	v_fma_f32 v115, v185, v115, v189
	v_sub_f32_e32 v116, v116, v192
	v_mul_f32_e32 v116, v116, v193
	v_fma_f32 v116, v186, v116, v190
	v_sub_f32_e32 v117, v117, v192
	v_mul_f32_e32 v117, v117, v193
	v_fma_f32 v117, v187, v117, v191
	global_store_dwordx4 v137, v[114:117], s[94:95] offset:192
	ds_read_b128 v[184:187], v136 offset:320
	ds_read_b128 v[188:191], v136 offset:4416
	s_waitcnt lgkmcnt(2)
	v_sub_f32_e32 v110, v110, v192
	v_mul_f32_e32 v110, v110, v193
	v_fma_f32 v110, v176, v110, v180
	v_sub_f32_e32 v111, v111, v192
	v_mul_f32_e32 v111, v111, v193
	v_fma_f32 v111, v177, v111, v181
	v_sub_f32_e32 v112, v112, v192
	v_mul_f32_e32 v112, v112, v193
	v_fma_f32 v112, v178, v112, v182
	v_sub_f32_e32 v113, v113, v192
	v_mul_f32_e32 v113, v113, v193
	v_fma_f32 v113, v179, v113, v183
	global_store_dwordx4 v137, v[110:113], s[94:95] offset:256
	ds_read_b128 v[176:179], v136 offset:384
	ds_read_b128 v[180:183], v136 offset:4480
	s_waitcnt lgkmcnt(2)
	v_sub_f32_e32 v106, v106, v192
	v_mul_f32_e32 v106, v106, v193
	v_fma_f32 v106, v184, v106, v188
	v_sub_f32_e32 v107, v107, v192
	v_mul_f32_e32 v107, v107, v193
	v_fma_f32 v107, v185, v107, v189
	v_sub_f32_e32 v108, v108, v192
	v_mul_f32_e32 v108, v108, v193
	v_fma_f32 v108, v186, v108, v190
	v_sub_f32_e32 v109, v109, v192
	v_mul_f32_e32 v109, v109, v193
	v_fma_f32 v109, v187, v109, v191
	global_store_dwordx4 v137, v[106:109], s[94:95] offset:320
	ds_read_b128 v[184:187], v136 offset:448
	ds_read_b128 v[188:191], v136 offset:4544
	s_waitcnt lgkmcnt(2)
	v_sub_f32_e32 v102, v102, v192
	v_mul_f32_e32 v102, v102, v193
	v_fma_f32 v102, v176, v102, v180
	v_sub_f32_e32 v103, v103, v192
	v_mul_f32_e32 v103, v103, v193
	v_fma_f32 v103, v177, v103, v181
	v_sub_f32_e32 v104, v104, v192
	v_mul_f32_e32 v104, v104, v193
	v_fma_f32 v104, v178, v104, v182
	v_sub_f32_e32 v105, v105, v192
	v_mul_f32_e32 v105, v105, v193
	v_fma_f32 v105, v179, v105, v183
	global_store_dwordx4 v137, v[102:105], s[94:95] offset:384
	s_waitcnt lgkmcnt(0)
	v_sub_f32_e32 v66, v66, v192
	v_mul_f32_e32 v66, v66, v193
	v_fma_f32 v66, v184, v66, v188
	v_sub_f32_e32 v67, v67, v192
	v_mul_f32_e32 v67, v67, v193
	v_fma_f32 v67, v185, v67, v189
	v_sub_f32_e32 v68, v68, v192
	v_mul_f32_e32 v68, v68, v193
	v_fma_f32 v68, v186, v68, v190
	v_sub_f32_e32 v69, v69, v192
	v_mul_f32_e32 v69, v69, v193
	v_fma_f32 v69, v187, v69, v191
	global_store_dwordx4 v137, v[66:69], s[94:95] offset:448
	s_waitcnt vmcnt(20) lgkmcnt(0)
	s_barrier
; DI float bf2f(unsigned b) { return __uint_as_float(b << 16); }
; DI void unit_O(const Params& p, char* lds, int l, int tile, int glu_tiles, int tile_b) {
;     ...
;         float s2[2], ss2[2];
; #pragma unroll
;         for (int mh = 0; mh < 2; ++mh) {
;             const int mt = half * 2 + mh, rl = mh * 16 + l15;
;             float s = 0.f, ss = 0.f;
; #pragma unroll
;             for (int nt = 0; nt < 8; ++nt) {
;                 f32x4 xr;
;                 if (l == 0) {
;                     const int chunk = wid * 32 + nt * 4 + quad;
;                     xr = *(const f32x4*)(XR + rl * 4096 + ((chunk ^ l15) << 4));
;                 } else {
;                     const u32x2 hb = *(const u32x2*)(XR + ((wid * 4 + (nt >> 1)) * 32 + rl) * 64 + (nt & 1) * 32 + quad * 8);
;                     xr = (f32x4){bf2f(hb[0] & 0xffffu), bf2f(hb[0] >> 16), bf2f(hb[1] & 0xffffu), bf2f(hb[1] >> 16)};
;                 }
; #pragma unroll
;                 for (int i = 0; i < 4; ++i) { const float v = acc[mt][nt][i] + DN_ALPHA * xr[i]; acc[mt][nt][i] = v; s += v; ss += v * v; }
;             }
;             s2[mh] = s; ss2[mh] = ss;
;         }
; #pragma unroll
;         for (int mh = 0; mh < 2; ++mh) { s2[mh] += __shfl_xor(s2[mh], 16); ss2[mh] += __shfl_xor(ss2[mh], 16); }
; #pragma unroll
;         for (int mh = 0; mh < 2; ++mh) { s2[mh] += __shfl_xor(s2[mh], 32); ss2[mh] += __shfl_xor(ss2[mh], 32); }
;         if (quad == 0) {
; #pragma unroll
;             for (int mh = 0; mh < 2; ++mh) *(f32x2*)&red[((mh * 16 + l15) * 8 + wid) * 2] = (f32x2){s2[mh], ss2[mh]};
;         }
	ds_read_b64 v[180:181], v133 offset:0
	ds_read_b64 v[182:183], v133 offset:32
	ds_read_b64 v[184:185], v133 offset:1024
	ds_read_b64 v[186:187], v133 offset:1056
	ds_read_b64 v[188:189], v133 offset:2048
	ds_read_b64 v[190:191], v133 offset:2080
	ds_read_b64 v[192:193], v133 offset:3072
	ds_read_b64 v[194:195], v133 offset:3104
	s_waitcnt lgkmcnt(7)
	v_lshlrev_b32_e32 v144, 16, v180
	v_and_b32_e32 v145, 0xffff0000, v180
	v_lshlrev_b32_e32 v146, 16, v181
	v_and_b32_e32 v147, 0xffff0000, v181
	v_fmac_f32_e32 v34, s58, v144
	v_fmac_f32_e32 v35, s58, v145
	v_fmac_f32_e32 v36, s58, v146
	v_fmac_f32_e32 v37, s58, v147
	v_mov_b32_e32 v196, v34
	v_mul_f32_e32 v197, v34, v34
	v_mov_b32_e32 v130, v35
	v_mul_f32_e32 v142, v35, v35
	v_add_f32_e32 v196, v196, v36
	v_fmac_f32_e32 v197, v36, v36
	v_add_f32_e32 v130, v130, v37
	v_fmac_f32_e32 v142, v37, v37
	s_waitcnt lgkmcnt(6)
	v_lshlrev_b32_e32 v148, 16, v182
	v_and_b32_e32 v149, 0xffff0000, v182
	v_lshlrev_b32_e32 v150, 16, v183
	v_and_b32_e32 v151, 0xffff0000, v183
	v_fmac_f32_e32 v30, s58, v148
	v_fmac_f32_e32 v31, s58, v149
	v_fmac_f32_e32 v32, s58, v150
	v_fmac_f32_e32 v33, s58, v151
	v_add_f32_e32 v196, v196, v30
	v_fmac_f32_e32 v197, v30, v30
	v_add_f32_e32 v130, v130, v31
	v_fmac_f32_e32 v142, v31, v31
	v_add_f32_e32 v196, v196, v32
	v_fmac_f32_e32 v197, v32, v32
	v_add_f32_e32 v130, v130, v33
	v_fmac_f32_e32 v142, v33, v33
	s_waitcnt lgkmcnt(5)
	v_lshlrev_b32_e32 v152, 16, v184
	v_and_b32_e32 v153, 0xffff0000, v184
	v_lshlrev_b32_e32 v154, 16, v185
	v_and_b32_e32 v155, 0xffff0000, v185
	v_fmac_f32_e32 v26, s58, v152
	v_fmac_f32_e32 v27, s58, v153
	v_fmac_f32_e32 v28, s58, v154
	v_fmac_f32_e32 v29, s58, v155
	v_add_f32_e32 v196, v196, v26
	v_fmac_f32_e32 v197, v26, v26
	v_add_f32_e32 v130, v130, v27
	v_fmac_f32_e32 v142, v27, v27
	v_add_f32_e32 v196, v196, v28
	v_fmac_f32_e32 v197, v28, v28
	v_add_f32_e32 v130, v130, v29
	v_fmac_f32_e32 v142, v29, v29
	s_waitcnt lgkmcnt(4)
	v_lshlrev_b32_e32 v156, 16, v186
	v_and_b32_e32 v157, 0xffff0000, v186
	v_lshlrev_b32_e32 v158, 16, v187
	v_and_b32_e32 v159, 0xffff0000, v187
	v_fmac_f32_e32 v22, s58, v156
	v_fmac_f32_e32 v23, s58, v157
	v_fmac_f32_e32 v24, s58, v158
	v_fmac_f32_e32 v25, s58, v159
	v_add_f32_e32 v196, v196, v22
	v_fmac_f32_e32 v197, v22, v22
	v_add_f32_e32 v130, v130, v23
	v_fmac_f32_e32 v142, v23, v23
	v_add_f32_e32 v196, v196, v24
	v_fmac_f32_e32 v197, v24, v24
	v_add_f32_e32 v130, v130, v25
	v_fmac_f32_e32 v142, v25, v25
	s_waitcnt lgkmcnt(3)
	v_lshlrev_b32_e32 v160, 16, v188
	v_and_b32_e32 v161, 0xffff0000, v188
	v_lshlrev_b32_e32 v162, 16, v189
	v_and_b32_e32 v163, 0xffff0000, v189
	v_fmac_f32_e32 v18, s58, v160
	v_fmac_f32_e32 v19, s58, v161
	v_fmac_f32_e32 v20, s58, v162
	v_fmac_f32_e32 v21, s58, v163
	v_add_f32_e32 v196, v196, v18
	v_fmac_f32_e32 v197, v18, v18
	v_add_f32_e32 v130, v130, v19
	v_fmac_f32_e32 v142, v19, v19
	v_add_f32_e32 v196, v196, v20
	v_fmac_f32_e32 v197, v20, v20
	v_add_f32_e32 v130, v130, v21
	v_fmac_f32_e32 v142, v21, v21
	s_waitcnt lgkmcnt(2)
	v_lshlrev_b32_e32 v164, 16, v190
	v_and_b32_e32 v165, 0xffff0000, v190
	v_lshlrev_b32_e32 v166, 16, v191
	v_and_b32_e32 v167, 0xffff0000, v191
	v_fmac_f32_e32 v14, s58, v164
	v_fmac_f32_e32 v15, s58, v165
	v_fmac_f32_e32 v16, s58, v166
	v_fmac_f32_e32 v17, s58, v167
	v_add_f32_e32 v196, v196, v14
	v_fmac_f32_e32 v197, v14, v14
	v_add_f32_e32 v130, v130, v15
	v_fmac_f32_e32 v142, v15, v15
	v_add_f32_e32 v196, v196, v16
	v_fmac_f32_e32 v197, v16, v16
	v_add_f32_e32 v130, v130, v17
	v_fmac_f32_e32 v142, v17, v17
	s_waitcnt lgkmcnt(1)
	v_lshlrev_b32_e32 v168, 16, v192
	v_and_b32_e32 v169, 0xffff0000, v192
	v_lshlrev_b32_e32 v170, 16, v193
	v_and_b32_e32 v171, 0xffff0000, v193
	v_fmac_f32_e32 v10, s58, v168
	v_fmac_f32_e32 v11, s58, v169
	v_fmac_f32_e32 v12, s58, v170
	v_fmac_f32_e32 v13, s58, v171
	v_add_f32_e32 v196, v196, v10
	v_fmac_f32_e32 v197, v10, v10
	v_add_f32_e32 v130, v130, v11
	v_fmac_f32_e32 v142, v11, v11
	v_add_f32_e32 v196, v196, v12
	v_fmac_f32_e32 v197, v12, v12
	v_add_f32_e32 v130, v130, v13
	v_fmac_f32_e32 v142, v13, v13
	s_waitcnt lgkmcnt(0)
	v_lshlrev_b32_e32 v172, 16, v194
	v_and_b32_e32 v173, 0xffff0000, v194
	v_lshlrev_b32_e32 v174, 16, v195
	v_and_b32_e32 v175, 0xffff0000, v195
	v_fmac_f32_e32 v6, s58, v172
	v_fmac_f32_e32 v7, s58, v173
	v_fmac_f32_e32 v8, s58, v174
	v_fmac_f32_e32 v9, s58, v175
	v_add_f32_e32 v196, v196, v6
	v_fmac_f32_e32 v197, v6, v6
	v_add_f32_e32 v130, v130, v7
	v_fmac_f32_e32 v142, v7, v7
	v_add_f32_e32 v196, v196, v8
	v_fmac_f32_e32 v197, v8, v8
	v_add_f32_e32 v130, v130, v9
	v_fmac_f32_e32 v142, v9, v9
	v_add_f32_e32 v196, v196, v130
	v_add_f32_e32 v197, v197, v142
	v_mov_b32_e32 v198, v196
	v_mov_b32_e32 v199, v197
	s_nop 1
	v_permlane16_swap_b32 v198, v196
	v_permlane16_swap_b32 v199, v197
	v_add_f32_e32 v196, v196, v198
	v_add_f32_e32 v197, v197, v199
	v_mov_b32_e32 v198, v196
	v_mov_b32_e32 v199, v197
	s_nop 1
	v_permlane32_swap_b32 v198, v196
	v_permlane32_swap_b32 v199, v197
	v_add_f32_e32 v196, v196, v198
	v_add_f32_e32 v197, v197, v199
	s_mov_b64 exec, 0xffff
	ds_write_b64 v134, v[196:197]
	s_mov_b64 exec, -1
	s_waitcnt lgkmcnt(0)
	s_barrier
; DI unsigned pk2(float lo, float hi) { const f32x2 v = {lo, hi}; const bf16x2_t b = __builtin_convertvector(v, bf16x2_t); return __builtin_bit_cast(unsigned, b); }
; DI size_t xb_off(int tok, int col) { return ((size_t)(((tok >> 7) * 32 + (col >> 5)) * 128 + (tok & 127))) * 32 + (col & 31); }
; DI void unit_O(const Params& p, char* lds, int l, int tile, int glu_tiles, int tile_b) {
;     ...
;         for (int mh = 0; mh < 2; ++mh) {
;             const int mt = half * 2 + mh, rl = mh * 16 + l15, row = mt * 16 + l15;
;             float s = 0.f, ss = 0.f;
; #pragma unroll
;             for (int w = 0; w < 4; ++w) { const f32x4 v = *(const f32x4*)&red[rl * 16 + 4 * w]; s += v[0] + v[2]; ss += v[1] + v[3]; }
;             const float mu = s * (1.f / 1024.f);
;             const float var = ss * (1.f / 1024.f) - mu * mu;
;             const float rs = rsqrtf(var + LN_EPS);
;             float* orow = xo + (r0 + row) * 1024 + wid * 128 + quad * 4;
;             bf16_t* brow = xbo + xb_off((int)r0 + row, wid * 128) + quad * 4;
;             const float* gp = GB + wid * 128 + quad * 4;
; #pragma unroll
;             for (int nt = 0; nt < 8; ++nt) {
;                 const f32x4 g = *(const f32x4*)(gp + nt * 16), bb = *(const f32x4*)(gp + 1024 + nt * 16);
;                 f32x4 o;
; #pragma unroll
;                 for (int i = 0; i < 4; ++i) o[i] = (acc[mt][nt][i] - mu) * rs * g[i] + bb[i];
;                 if (l == 0) *(u32x2*)(brow + (nt >> 1) * 4096 + (nt & 1) * 16) = (u32x2){pk2(o[0], o[1]), pk2(o[2], o[3])};
;                 else *(f32x4*)(orow + nt * 16) = o;
;             }
;         }
	ds_read_b128 v[160:163], v135 offset:0
	ds_read_b128 v[164:167], v135 offset:16
	ds_read_b128 v[168:171], v135 offset:32
	ds_read_b128 v[172:175], v135 offset:48
	s_waitcnt lgkmcnt(0)
	v_add_f32_e32 v160, v160, v162
	v_add_f32_e32 v161, v161, v163
	v_add_f32_e32 v164, v164, v166
	v_add_f32_e32 v165, v165, v167
	v_add_f32_e32 v168, v168, v170
	v_add_f32_e32 v169, v169, v171
	v_add_f32_e32 v172, v172, v174
	v_add_f32_e32 v173, v173, v175
	v_add_f32_e32 v160, v160, v164
	v_add_f32_e32 v161, v161, v165
	v_add_f32_e32 v168, v168, v172
	v_add_f32_e32 v169, v169, v173
	v_add_f32_e32 v160, v160, v168
	v_add_f32_e32 v161, v161, v169
	v_mul_f32_e32 v192, 0x3a800000, v160
	v_mul_f32_e32 v193, 0x3a800000, v161
	v_fma_f32 v193, -v192, v192, v193
	v_add_f32_e32 v193, 0x3727c5ac, v193
	v_rsq_f32_e32 v193, v193
	s_nop 0
	s_add_u32 s94, s78, 0x20000
	s_addc_u32 s95, s79, 0
	ds_read_b128 v[176:179], v136
	ds_read_b128 v[180:183], v136 offset:4096
	ds_read_b128 v[184:187], v136 offset:64
	ds_read_b128 v[188:191], v136 offset:4160
	s_waitcnt lgkmcnt(2)
	v_sub_f32_e32 v34, v34, v192
	v_mul_f32_e32 v34, v34, v193
	v_fma_f32 v34, v176, v34, v180
	v_sub_f32_e32 v35, v35, v192
	v_mul_f32_e32 v35, v35, v193
	v_fma_f32 v35, v177, v35, v181
	v_sub_f32_e32 v36, v36, v192
	v_mul_f32_e32 v36, v36, v193
	v_fma_f32 v36, v178, v36, v182
	v_sub_f32_e32 v37, v37, v192
	v_mul_f32_e32 v37, v37, v193
	v_fma_f32 v37, v179, v37, v183
	global_store_dwordx4 v137, v[34:37], s[94:95]
	ds_read_b128 v[176:179], v136 offset:128
	ds_read_b128 v[180:183], v136 offset:4224
	s_waitcnt lgkmcnt(2)
	v_sub_f32_e32 v30, v30, v192
	v_mul_f32_e32 v30, v30, v193
	v_fma_f32 v30, v184, v30, v188
	v_sub_f32_e32 v31, v31, v192
	v_mul_f32_e32 v31, v31, v193
	v_fma_f32 v31, v185, v31, v189
	v_sub_f32_e32 v32, v32, v192
	v_mul_f32_e32 v32, v32, v193
	v_fma_f32 v32, v186, v32, v190
	v_sub_f32_e32 v33, v33, v192
	v_mul_f32_e32 v33, v33, v193
	v_fma_f32 v33, v187, v33, v191
	global_store_dwordx4 v137, v[30:33], s[94:95] offset:64
	ds_read_b128 v[184:187], v136 offset:192
	ds_read_b128 v[188:191], v136 offset:4288
	s_waitcnt lgkmcnt(2)
	v_sub_f32_e32 v26, v26, v192
	v_mul_f32_e32 v26, v26, v193
	v_fma_f32 v26, v176, v26, v180
	v_sub_f32_e32 v27, v27, v192
	v_mul_f32_e32 v27, v27, v193
	v_fma_f32 v27, v177, v27, v181
	v_sub_f32_e32 v28, v28, v192
	v_mul_f32_e32 v28, v28, v193
	v_fma_f32 v28, v178, v28, v182
	v_sub_f32_e32 v29, v29, v192
	v_mul_f32_e32 v29, v29, v193
	v_fma_f32 v29, v179, v29, v183
	global_store_dwordx4 v137, v[26:29], s[94:95] offset:128
	ds_read_b128 v[176:179], v136 offset:256
	ds_read_b128 v[180:183], v136 offset:4352
	s_waitcnt lgkmcnt(2)
	v_sub_f32_e32 v22, v22, v192
	v_mul_f32_e32 v22, v22, v193
	v_fma_f32 v22, v184, v22, v188
	v_sub_f32_e32 v23, v23, v192
	v_mul_f32_e32 v23, v23, v193
	v_fma_f32 v23, v185, v23, v189
	v_sub_f32_e32 v24, v24, v192
	v_mul_f32_e32 v24, v24, v193
	v_fma_f32 v24, v186, v24, v190
	v_sub_f32_e32 v25, v25, v192
	v_mul_f32_e32 v25, v25, v193
	v_fma_f32 v25, v187, v25, v191
	global_store_dwordx4 v137, v[22:25], s[94:95] offset:192
	ds_read_b128 v[184:187], v136 offset:320
	ds_read_b128 v[188:191], v136 offset:4416
	s_waitcnt lgkmcnt(2)
	v_sub_f32_e32 v18, v18, v192
	v_mul_f32_e32 v18, v18, v193
	v_fma_f32 v18, v176, v18, v180
	v_sub_f32_e32 v19, v19, v192
	v_mul_f32_e32 v19, v19, v193
	v_fma_f32 v19, v177, v19, v181
	v_sub_f32_e32 v20, v20, v192
	v_mul_f32_e32 v20, v20, v193
	v_fma_f32 v20, v178, v20, v182
	v_sub_f32_e32 v21, v21, v192
	v_mul_f32_e32 v21, v21, v193
	v_fma_f32 v21, v179, v21, v183
	global_store_dwordx4 v137, v[18:21], s[94:95] offset:256
	ds_read_b128 v[176:179], v136 offset:384
	ds_read_b128 v[180:183], v136 offset:4480
	s_waitcnt lgkmcnt(2)
	v_sub_f32_e32 v14, v14, v192
	v_mul_f32_e32 v14, v14, v193
	v_fma_f32 v14, v184, v14, v188
	v_sub_f32_e32 v15, v15, v192
	v_mul_f32_e32 v15, v15, v193
	v_fma_f32 v15, v185, v15, v189
	v_sub_f32_e32 v16, v16, v192
	v_mul_f32_e32 v16, v16, v193
	v_fma_f32 v16, v186, v16, v190
	v_sub_f32_e32 v17, v17, v192
	v_mul_f32_e32 v17, v17, v193
	v_fma_f32 v17, v187, v17, v191
	global_store_dwordx4 v137, v[14:17], s[94:95] offset:320
	ds_read_b128 v[184:187], v136 offset:448
	ds_read_b128 v[188:191], v136 offset:4544
	s_waitcnt lgkmcnt(2)
	v_sub_f32_e32 v10, v10, v192
	v_mul_f32_e32 v10, v10, v193
	v_fma_f32 v10, v176, v10, v180
	v_sub_f32_e32 v11, v11, v192
	v_mul_f32_e32 v11, v11, v193
	v_fma_f32 v11, v177, v11, v181
	v_sub_f32_e32 v12, v12, v192
	v_mul_f32_e32 v12, v12, v193
	v_fma_f32 v12, v178, v12, v182
	v_sub_f32_e32 v13, v13, v192
	v_mul_f32_e32 v13, v13, v193
	v_fma_f32 v13, v179, v13, v183
	global_store_dwordx4 v137, v[10:13], s[94:95] offset:384
	s_waitcnt lgkmcnt(0)
	v_sub_f32_e32 v6, v6, v192
	v_mul_f32_e32 v6, v6, v193
	v_fma_f32 v6, v184, v6, v188
	v_sub_f32_e32 v7, v7, v192
	v_mul_f32_e32 v7, v7, v193
	v_fma_f32 v7, v185, v7, v189
	v_sub_f32_e32 v8, v8, v192
	v_mul_f32_e32 v8, v8, v193
	v_fma_f32 v8, v186, v8, v190
	v_sub_f32_e32 v9, v9, v192
	v_mul_f32_e32 v9, v9, v193
	v_fma_f32 v9, v187, v9, v191
	global_store_dwordx4 v137, v[6:9], s[94:95] offset:448
	s_waitcnt vmcnt(16) lgkmcnt(0)
	s_barrier
; DI float bf2f(unsigned b) { return __uint_as_float(b << 16); }
; DI void unit_O(const Params& p, char* lds, int l, int tile, int glu_tiles, int tile_b) {
;     ...
;         float s2[2], ss2[2];
; #pragma unroll
;         for (int mh = 0; mh < 2; ++mh) {
;             const int mt = half * 2 + mh, rl = mh * 16 + l15;
;             float s = 0.f, ss = 0.f;
; #pragma unroll
;             for (int nt = 0; nt < 8; ++nt) {
;                 f32x4 xr;
;                 if (l == 0) {
;                     const int chunk = wid * 32 + nt * 4 + quad;
;                     xr = *(const f32x4*)(XR + rl * 4096 + ((chunk ^ l15) << 4));
;                 } else {
;                     const u32x2 hb = *(const u32x2*)(XR + ((wid * 4 + (nt >> 1)) * 32 + rl) * 64 + (nt & 1) * 32 + quad * 8);
;                     xr = (f32x4){bf2f(hb[0] & 0xffffu), bf2f(hb[0] >> 16), bf2f(hb[1] & 0xffffu), bf2f(hb[1] >> 16)};
;                 }
; #pragma unroll
;                 for (int i = 0; i < 4; ++i) { const float v = acc[mt][nt][i] + DN_ALPHA * xr[i]; acc[mt][nt][i] = v; s += v; ss += v * v; }
;             }
;             s2[mh] = s; ss2[mh] = ss;
;         }
; #pragma unroll
;         for (int mh = 0; mh < 2; ++mh) { s2[mh] += __shfl_xor(s2[mh], 16); ss2[mh] += __shfl_xor(ss2[mh], 16); }
; #pragma unroll
;         for (int mh = 0; mh < 2; ++mh) { s2[mh] += __shfl_xor(s2[mh], 32); ss2[mh] += __shfl_xor(ss2[mh], 32); }
;         if (quad == 0) {
; #pragma unroll
;             for (int mh = 0; mh < 2; ++mh) *(f32x2*)&red[((mh * 16 + l15) * 8 + wid) * 2] = (f32x2){s2[mh], ss2[mh]};
;         }
	ds_read_b64 v[180:181], v133 offset:32768
	ds_read_b64 v[182:183], v133 offset:32800
	ds_read_b64 v[184:185], v133 offset:33792
	ds_read_b64 v[186:187], v133 offset:33824
	ds_read_b64 v[188:189], v133 offset:34816
	ds_read_b64 v[190:191], v133 offset:34848
	ds_read_b64 v[192:193], v133 offset:35840
	ds_read_b64 v[194:195], v133 offset:35872
	s_waitcnt lgkmcnt(7)
	v_lshlrev_b32_e32 v144, 16, v180
	v_and_b32_e32 v145, 0xffff0000, v180
	v_lshlrev_b32_e32 v146, 16, v181
	v_and_b32_e32 v147, 0xffff0000, v181
	v_fmac_f32_e32 v62, s58, v144
	v_fmac_f32_e32 v63, s58, v145
	v_fmac_f32_e32 v64, s58, v146
	v_fmac_f32_e32 v65, s58, v147
	v_mov_b32_e32 v196, v62
	v_mul_f32_e32 v197, v62, v62
	v_mov_b32_e32 v130, v63
	v_mul_f32_e32 v142, v63, v63
	v_add_f32_e32 v196, v196, v64
	v_fmac_f32_e32 v197, v64, v64
	v_add_f32_e32 v130, v130, v65
	v_fmac_f32_e32 v142, v65, v65
	s_waitcnt lgkmcnt(6)
	v_lshlrev_b32_e32 v148, 16, v182
	v_and_b32_e32 v149, 0xffff0000, v182
	v_lshlrev_b32_e32 v150, 16, v183
	v_and_b32_e32 v151, 0xffff0000, v183
	v_fmac_f32_e32 v58, s58, v148
	v_fmac_f32_e32 v59, s58, v149
	v_fmac_f32_e32 v60, s58, v150
	v_fmac_f32_e32 v61, s58, v151
	v_add_f32_e32 v196, v196, v58
	v_fmac_f32_e32 v197, v58, v58
	v_add_f32_e32 v130, v130, v59
	v_fmac_f32_e32 v142, v59, v59
	v_add_f32_e32 v196, v196, v60
	v_fmac_f32_e32 v197, v60, v60
	v_add_f32_e32 v130, v130, v61
	v_fmac_f32_e32 v142, v61, v61
	s_waitcnt lgkmcnt(5)
	v_lshlrev_b32_e32 v152, 16, v184
	v_and_b32_e32 v153, 0xffff0000, v184
	v_lshlrev_b32_e32 v154, 16, v185
	v_and_b32_e32 v155, 0xffff0000, v185
	v_fmac_f32_e32 v54, s58, v152
	v_fmac_f32_e32 v55, s58, v153
	v_fmac_f32_e32 v56, s58, v154
	v_fmac_f32_e32 v57, s58, v155
	v_add_f32_e32 v196, v196, v54
	v_fmac_f32_e32 v197, v54, v54
	v_add_f32_e32 v130, v130, v55
	v_fmac_f32_e32 v142, v55, v55
	v_add_f32_e32 v196, v196, v56
	v_fmac_f32_e32 v197, v56, v56
	v_add_f32_e32 v130, v130, v57
	v_fmac_f32_e32 v142, v57, v57
	s_waitcnt lgkmcnt(4)
	v_lshlrev_b32_e32 v156, 16, v186
	v_and_b32_e32 v157, 0xffff0000, v186
	v_lshlrev_b32_e32 v158, 16, v187
	v_and_b32_e32 v159, 0xffff0000, v187
	v_fmac_f32_e32 v50, s58, v156
	v_fmac_f32_e32 v51, s58, v157
	v_fmac_f32_e32 v52, s58, v158
	v_fmac_f32_e32 v53, s58, v159
	v_add_f32_e32 v196, v196, v50
	v_fmac_f32_e32 v197, v50, v50
	v_add_f32_e32 v130, v130, v51
	v_fmac_f32_e32 v142, v51, v51
	v_add_f32_e32 v196, v196, v52
	v_fmac_f32_e32 v197, v52, v52
	v_add_f32_e32 v130, v130, v53
	v_fmac_f32_e32 v142, v53, v53
	s_waitcnt lgkmcnt(3)
	v_lshlrev_b32_e32 v160, 16, v188
	v_and_b32_e32 v161, 0xffff0000, v188
	v_lshlrev_b32_e32 v162, 16, v189
	v_and_b32_e32 v163, 0xffff0000, v189
	v_fmac_f32_e32 v46, s58, v160
	v_fmac_f32_e32 v47, s58, v161
	v_fmac_f32_e32 v48, s58, v162
	v_fmac_f32_e32 v49, s58, v163
	v_add_f32_e32 v196, v196, v46
	v_fmac_f32_e32 v197, v46, v46
	v_add_f32_e32 v130, v130, v47
	v_fmac_f32_e32 v142, v47, v47
	v_add_f32_e32 v196, v196, v48
	v_fmac_f32_e32 v197, v48, v48
	v_add_f32_e32 v130, v130, v49
	v_fmac_f32_e32 v142, v49, v49
	s_waitcnt lgkmcnt(2)
	v_lshlrev_b32_e32 v164, 16, v190
	v_and_b32_e32 v165, 0xffff0000, v190
	v_lshlrev_b32_e32 v166, 16, v191
	v_and_b32_e32 v167, 0xffff0000, v191
	v_fmac_f32_e32 v42, s58, v164
	v_fmac_f32_e32 v43, s58, v165
	v_fmac_f32_e32 v44, s58, v166
	v_fmac_f32_e32 v45, s58, v167
	v_add_f32_e32 v196, v196, v42
	v_fmac_f32_e32 v197, v42, v42
	v_add_f32_e32 v130, v130, v43
	v_fmac_f32_e32 v142, v43, v43
	v_add_f32_e32 v196, v196, v44
	v_fmac_f32_e32 v197, v44, v44
	v_add_f32_e32 v130, v130, v45
	v_fmac_f32_e32 v142, v45, v45
	s_waitcnt lgkmcnt(1)
	v_lshlrev_b32_e32 v168, 16, v192
	v_and_b32_e32 v169, 0xffff0000, v192
	v_lshlrev_b32_e32 v170, 16, v193
	v_and_b32_e32 v171, 0xffff0000, v193
	v_fmac_f32_e32 v38, s58, v168
	v_fmac_f32_e32 v39, s58, v169
	v_fmac_f32_e32 v40, s58, v170
	v_fmac_f32_e32 v41, s58, v171
	v_add_f32_e32 v196, v196, v38
	v_fmac_f32_e32 v197, v38, v38
	v_add_f32_e32 v130, v130, v39
	v_fmac_f32_e32 v142, v39, v39
	v_add_f32_e32 v196, v196, v40
	v_fmac_f32_e32 v197, v40, v40
	v_add_f32_e32 v130, v130, v41
	v_fmac_f32_e32 v142, v41, v41
	s_waitcnt lgkmcnt(0)
	v_lshlrev_b32_e32 v172, 16, v194
	v_and_b32_e32 v173, 0xffff0000, v194
	v_lshlrev_b32_e32 v174, 16, v195
	v_and_b32_e32 v175, 0xffff0000, v195
	v_fmac_f32_e32 v2, s58, v172
	v_fmac_f32_e32 v3, s58, v173
	v_fmac_f32_e32 v4, s58, v174
	v_fmac_f32_e32 v5, s58, v175
	v_add_f32_e32 v196, v196, v2
	v_fmac_f32_e32 v197, v2, v2
	v_add_f32_e32 v130, v130, v3
	v_fmac_f32_e32 v142, v3, v3
	v_add_f32_e32 v196, v196, v4
	v_fmac_f32_e32 v197, v4, v4
	v_add_f32_e32 v130, v130, v5
	v_fmac_f32_e32 v142, v5, v5
	v_add_f32_e32 v196, v196, v130
	v_add_f32_e32 v197, v197, v142
	v_mov_b32_e32 v198, v196
	v_mov_b32_e32 v199, v197
	s_nop 1
	v_permlane16_swap_b32 v198, v196
	v_permlane16_swap_b32 v199, v197
	v_add_f32_e32 v196, v196, v198
	v_add_f32_e32 v197, v197, v199
	v_mov_b32_e32 v198, v196
	v_mov_b32_e32 v199, v197
	s_nop 1
	v_permlane32_swap_b32 v198, v196
	v_permlane32_swap_b32 v199, v197
	v_add_f32_e32 v196, v196, v198
	v_add_f32_e32 v197, v197, v199
	s_mov_b64 exec, 0xffff
	ds_write_b64 v134, v[196:197]
	s_mov_b64 exec, -1
	s_waitcnt lgkmcnt(0)
	s_barrier
; DI unsigned pk2(float lo, float hi) { const f32x2 v = {lo, hi}; const bf16x2_t b = __builtin_convertvector(v, bf16x2_t); return __builtin_bit_cast(unsigned, b); }
; DI size_t xb_off(int tok, int col) { return ((size_t)(((tok >> 7) * 32 + (col >> 5)) * 128 + (tok & 127))) * 32 + (col & 31); }
; DI void unit_O(const Params& p, char* lds, int l, int tile, int glu_tiles, int tile_b) {
;     ...
;         for (int mh = 0; mh < 2; ++mh) {
;             const int mt = half * 2 + mh, rl = mh * 16 + l15, row = mt * 16 + l15;
;             float s = 0.f, ss = 0.f;
; #pragma unroll
;             for (int w = 0; w < 4; ++w) { const f32x4 v = *(const f32x4*)&red[rl * 16 + 4 * w]; s += v[0] + v[2]; ss += v[1] + v[3]; }
;             const float mu = s * (1.f / 1024.f);
;             const float var = ss * (1.f / 1024.f) - mu * mu;
;             const float rs = rsqrtf(var + LN_EPS);
;             float* orow = xo + (r0 + row) * 1024 + wid * 128 + quad * 4;
;             bf16_t* brow = xbo + xb_off((int)r0 + row, wid * 128) + quad * 4;
;             const float* gp = GB + wid * 128 + quad * 4;
; #pragma unroll
;             for (int nt = 0; nt < 8; ++nt) {
;                 const f32x4 g = *(const f32x4*)(gp + nt * 16), bb = *(const f32x4*)(gp + 1024 + nt * 16);
;                 f32x4 o;
; #pragma unroll
;                 for (int i = 0; i < 4; ++i) o[i] = (acc[mt][nt][i] - mu) * rs * g[i] + bb[i];
;                 if (l == 0) *(u32x2*)(brow + (nt >> 1) * 4096 + (nt & 1) * 16) = (u32x2){pk2(o[0], o[1]), pk2(o[2], o[3])};
;                 else *(f32x4*)(orow + nt * 16) = o;
;             }
;         }
	ds_read_b128 v[160:163], v135 offset:0
	ds_read_b128 v[164:167], v135 offset:16
	ds_read_b128 v[168:171], v135 offset:32
	ds_read_b128 v[172:175], v135 offset:48
	s_waitcnt lgkmcnt(0)
	v_add_f32_e32 v160, v160, v162
	v_add_f32_e32 v161, v161, v163
	v_add_f32_e32 v164, v164, v166
	v_add_f32_e32 v165, v165, v167
	v_add_f32_e32 v168, v168, v170
	v_add_f32_e32 v169, v169, v171
	v_add_f32_e32 v172, v172, v174
	v_add_f32_e32 v173, v173, v175
	v_add_f32_e32 v160, v160, v164
	v_add_f32_e32 v161, v161, v165
	v_add_f32_e32 v168, v168, v172
	v_add_f32_e32 v169, v169, v173
	v_add_f32_e32 v160, v160, v168
	v_add_f32_e32 v161, v161, v169
	v_mul_f32_e32 v192, 0x3a800000, v160
	v_mul_f32_e32 v193, 0x3a800000, v161
	v_fma_f32 v193, -v192, v192, v193
	v_add_f32_e32 v193, 0x3727c5ac, v193
	v_rsq_f32_e32 v193, v193
	s_nop 0
	s_add_u32 s94, s78, 0x30000
	s_addc_u32 s95, s79, 0
	ds_read_b128 v[176:179], v136
	ds_read_b128 v[180:183], v136 offset:4096
	ds_read_b128 v[184:187], v136 offset:64
	ds_read_b128 v[188:191], v136 offset:4160
	s_waitcnt lgkmcnt(2)
	v_sub_f32_e32 v62, v62, v192
	v_mul_f32_e32 v62, v62, v193
	v_fma_f32 v62, v176, v62, v180
	v_sub_f32_e32 v63, v63, v192
	v_mul_f32_e32 v63, v63, v193
	v_fma_f32 v63, v177, v63, v181
	v_sub_f32_e32 v64, v64, v192
	v_mul_f32_e32 v64, v64, v193
	v_fma_f32 v64, v178, v64, v182
	v_sub_f32_e32 v65, v65, v192
	v_mul_f32_e32 v65, v65, v193
	v_fma_f32 v65, v179, v65, v183
	global_store_dwordx4 v137, v[62:65], s[94:95]
	ds_read_b128 v[176:179], v136 offset:128
	ds_read_b128 v[180:183], v136 offset:4224
	s_waitcnt lgkmcnt(2)
	v_sub_f32_e32 v58, v58, v192
	v_mul_f32_e32 v58, v58, v193
	v_fma_f32 v58, v184, v58, v188
	v_sub_f32_e32 v59, v59, v192
	v_mul_f32_e32 v59, v59, v193
	v_fma_f32 v59, v185, v59, v189
	v_sub_f32_e32 v60, v60, v192
	v_mul_f32_e32 v60, v60, v193
	v_fma_f32 v60, v186, v60, v190
	v_sub_f32_e32 v61, v61, v192
	v_mul_f32_e32 v61, v61, v193
	v_fma_f32 v61, v187, v61, v191
	global_store_dwordx4 v137, v[58:61], s[94:95] offset:64
	ds_read_b128 v[184:187], v136 offset:192
	ds_read_b128 v[188:191], v136 offset:4288
	s_waitcnt lgkmcnt(2)
	v_sub_f32_e32 v54, v54, v192
	v_mul_f32_e32 v54, v54, v193
	v_fma_f32 v54, v176, v54, v180
	v_sub_f32_e32 v55, v55, v192
	v_mul_f32_e32 v55, v55, v193
	v_fma_f32 v55, v177, v55, v181
	v_sub_f32_e32 v56, v56, v192
	v_mul_f32_e32 v56, v56, v193
	v_fma_f32 v56, v178, v56, v182
	v_sub_f32_e32 v57, v57, v192
	v_mul_f32_e32 v57, v57, v193
	v_fma_f32 v57, v179, v57, v183
	global_store_dwordx4 v137, v[54:57], s[94:95] offset:128
	ds_read_b128 v[176:179], v136 offset:256
	ds_read_b128 v[180:183], v136 offset:4352
	s_waitcnt lgkmcnt(2)
	v_sub_f32_e32 v50, v50, v192
	v_mul_f32_e32 v50, v50, v193
	v_fma_f32 v50, v184, v50, v188
	v_sub_f32_e32 v51, v51, v192
	v_mul_f32_e32 v51, v51, v193
	v_fma_f32 v51, v185, v51, v189
	v_sub_f32_e32 v52, v52, v192
	v_mul_f32_e32 v52, v52, v193
	v_fma_f32 v52, v186, v52, v190
	v_sub_f32_e32 v53, v53, v192
	v_mul_f32_e32 v53, v53, v193
	v_fma_f32 v53, v187, v53, v191
	global_store_dwordx4 v137, v[50:53], s[94:95] offset:192
	ds_read_b128 v[184:187], v136 offset:320
	ds_read_b128 v[188:191], v136 offset:4416
	s_waitcnt lgkmcnt(2)
	v_sub_f32_e32 v46, v46, v192
	v_mul_f32_e32 v46, v46, v193
	v_fma_f32 v46, v176, v46, v180
	v_sub_f32_e32 v47, v47, v192
	v_mul_f32_e32 v47, v47, v193
	v_fma_f32 v47, v177, v47, v181
	v_sub_f32_e32 v48, v48, v192
	v_mul_f32_e32 v48, v48, v193
	v_fma_f32 v48, v178, v48, v182
	v_sub_f32_e32 v49, v49, v192
	v_mul_f32_e32 v49, v49, v193
	v_fma_f32 v49, v179, v49, v183
	global_store_dwordx4 v137, v[46:49], s[94:95] offset:256
	ds_read_b128 v[176:179], v136 offset:384
	ds_read_b128 v[180:183], v136 offset:4480
	s_waitcnt lgkmcnt(2)
	v_sub_f32_e32 v42, v42, v192
	v_mul_f32_e32 v42, v42, v193
	v_fma_f32 v42, v184, v42, v188
	v_sub_f32_e32 v43, v43, v192
	v_mul_f32_e32 v43, v43, v193
	v_fma_f32 v43, v185, v43, v189
	v_sub_f32_e32 v44, v44, v192
	v_mul_f32_e32 v44, v44, v193
	v_fma_f32 v44, v186, v44, v190
	v_sub_f32_e32 v45, v45, v192
	v_mul_f32_e32 v45, v45, v193
	v_fma_f32 v45, v187, v45, v191
	global_store_dwordx4 v137, v[42:45], s[94:95] offset:320
	ds_read_b128 v[184:187], v136 offset:448
	ds_read_b128 v[188:191], v136 offset:4544
	s_waitcnt lgkmcnt(2)
	v_sub_f32_e32 v38, v38, v192
	v_mul_f32_e32 v38, v38, v193
	v_fma_f32 v38, v176, v38, v180
	v_sub_f32_e32 v39, v39, v192
	v_mul_f32_e32 v39, v39, v193
	v_fma_f32 v39, v177, v39, v181
	v_sub_f32_e32 v40, v40, v192
	v_mul_f32_e32 v40, v40, v193
	v_fma_f32 v40, v178, v40, v182
	v_sub_f32_e32 v41, v41, v192
	v_mul_f32_e32 v41, v41, v193
	v_fma_f32 v41, v179, v41, v183
	global_store_dwordx4 v137, v[38:41], s[94:95] offset:384
	s_waitcnt lgkmcnt(0)
	v_sub_f32_e32 v2, v2, v192
	v_mul_f32_e32 v2, v2, v193
	v_fma_f32 v2, v184, v2, v188
	v_sub_f32_e32 v3, v3, v192
	v_mul_f32_e32 v3, v3, v193
	v_fma_f32 v3, v185, v3, v189
	v_sub_f32_e32 v4, v4, v192
	v_mul_f32_e32 v4, v4, v193
	v_fma_f32 v4, v186, v4, v190
	v_sub_f32_e32 v5, v5, v192
	v_mul_f32_e32 v5, v5, v193
	v_fma_f32 v5, v187, v5, v191
	global_store_dwordx4 v137, v[2:5], s[94:95] offset:448

; DI f32x4 mfma16(bf16x8 a, bf16x8 b, f32x4 c) { return __builtin_amdgcn_mfma_f32_16x16x32_bf16(a, b, c, 0, 0, 0); }
; template <int N> DI void wait_vm() { asm volatile("s_waitcnt vmcnt(%0)" ::"n"(N) : "memory"); }
; DI void raw_barrier() { asm volatile("" ::: "memory"); __builtin_amdgcn_s_barrier(); asm volatile("" ::: "memory"); }
;     ...
;     auto compute = [&](int cb, bool do_issue, int ikt, int ib) {
;         const char* base = lds + cb * BUF;
;         bf16x8 af[MT], bfr[NT];
; #pragma unroll
;         for (int nt = 0; nt < NT; ++nt) {
;             const int br = BM + (nt / NTS) * (BN / NSEG) + wc * (NTS * 16) + (nt % NTS) * 16;
;             bfr[nt] = *(const bf16x8*)(base + (br + l15) * 64 + rsw);
;         }
; #pragma unroll
;         for (int mt = 0; mt < MT; ++mt) af[mt] = *(const bf16x8*)(base + (wr * WM + mt * 16 + l15) * 64 + rsw);
;         constexpr int TOT = MT * NT, PER = (TOT + NIT - 1) / NIT;
; #pragma unroll
;         for (int part = 0; part < NIT; ++part) {
; #pragma unroll
;             for (int q = 0; q < PER; ++q) {
;                 const int idx = part * PER + q;
;                 if (idx < TOT) {
;                     const int mt = idx / NT, nt = idx % NT;
;                     acc[mt][nt] = SWAP ? mfma16(bfr[nt], af[mt], acc[mt][nt]) : mfma16(af[mt], bfr[nt], acc[mt][nt]);
;                 }
;             }
;             __builtin_amdgcn_sched_barrier(0);
;             if (do_issue) issue_one(ikt, ib, part);
;             __builtin_amdgcn_sched_barrier(0);
;         }
;     };
;     __syncthreads();
; #pragma unroll
;     for (int d = 0; d < D; ++d) issue(d, d);
;     int cb = 0, ib = D;
;     for (int kt = 0; kt < KT; ++kt) {
;         if (D > 1 && kt + D - 1 < KT) wait_vm<(D - 1) * NIT>(); else wait_vm<0>();
;         raw_barrier();
;         compute(cb, kt + D < KT, kt + D, ib);
;         cb = (cb + 1 == NST) ? 0 : cb + 1;
;         ib = (ib + 1 == NST) ? 0 : ib + 1;
;     }
.Lpo2_c_entry:
	v_subrev_u32_e32 v246, 0x100, v212
	v_readfirstlane_b32 s96, v130
	v_readfirstlane_b32 s97, v131
	v_readfirstlane_b32 s94, v0
	s_nop 3
	s_sub_u32 s96, s96, s94
	s_subb_u32 s97, s97, 0
	s_add_i32 s94, s33, 2
	v_lshrrev_b32_e32 v247, 5, v246
	v_add_u32_e32 v247, s94, v247
	v_and_b32_e32 v247, 31, v247
	v_and_b32_e32 v199, 31, v246
	v_lshlrev_b32_e32 v199, 7, v199
	v_lshl_or_b32 v247, v247, 12, v199
	s_nop 1
	global_load_dword v247, v247, s[96:97]
	s_mov_b32 s29, 2
	s_waitcnt vmcnt(1)
	s_barrier
	v_add_u32_e32 v197, v140, v141
	v_add_u32_e32 v196, v140, v139
	ds_read_b128 v[146:149], v196
	ds_read_b128 v[154:157], v196 offset:1024
	ds_read_b128 v[182:185], v196 offset:2048
	ds_read_b128 v[142:145], v197 offset:4096
	ds_read_b128 v[150:153], v197 offset:5120
	ds_read_b128 v[158:161], v197 offset:6144
	ds_read_b128 v[162:165], v197 offset:7168
	ds_read_b128 v[166:169], v197 offset:8192
	ds_read_b128 v[170:173], v197 offset:9216
	ds_read_b128 v[174:177], v197 offset:10240
	ds_read_b128 v[178:181], v197 offset:11264
	ds_read_b128 v[186:189], v196 offset:3072
.Lpo2_c_loop:
	s_bitcmp1_b32 s29, 0
	s_cselect_b32 s46, 0, 0x11000
	v_add_u32_e32 v198, s46, v140
	v_add_u32_e32 v197, v198, v141
	v_add_u32_e32 v196, v198, v139
	s_waitcnt lgkmcnt(8)
	v_mfma_f32_16x16x32_bf16 v[98:101], v[142:145], v[146:149], v[98:101]
	s_waitcnt lgkmcnt(7)
	v_mfma_f32_16x16x32_bf16 v[94:97], v[150:153], v[146:149], v[94:97]
	s_waitcnt lgkmcnt(6)
	v_mfma_f32_16x16x32_bf16 v[90:93], v[158:161], v[146:149], v[90:93]
	s_waitcnt lgkmcnt(5)
	v_mfma_f32_16x16x32_bf16 v[86:89], v[162:165], v[146:149], v[86:89]
	s_waitcnt lgkmcnt(4)
	v_mfma_f32_16x16x32_bf16 v[82:85], v[166:169], v[146:149], v[82:85]
	s_waitcnt lgkmcnt(3)
	v_mfma_f32_16x16x32_bf16 v[78:81], v[170:173], v[146:149], v[78:81]
	s_waitcnt lgkmcnt(2)
	v_mfma_f32_16x16x32_bf16 v[74:77], v[174:177], v[146:149], v[74:77]
	s_waitcnt lgkmcnt(1)
	v_mfma_f32_16x16x32_bf16 v[70:73], v[178:181], v[146:149], v[70:73]
	s_waitcnt lgkmcnt(0)
	s_barrier
	ds_read_b128 v[146:149], v196
	s_and_b32 s94, s29, 7
	s_cmp_lg_u32 s94, 6
	s_cbranch_scc1 .Lpo2_ypf_skip
	s_add_i32 s94, s33, s29
	s_add_i32 s94, s94, 4
	v_lshrrev_b32_e32 v247, 5, v246
	v_add_u32_e32 v247, s94, v247
	v_and_b32_e32 v247, 31, v247
	v_and_b32_e32 v199, 31, v246
	v_lshlrev_b32_e32 v199, 7, v199
	v_lshl_or_b32 v247, v247, 12, v199
	global_load_dword v247, v247, s[96:97]

;     ...
;     auto compute = [&](int cb, bool do_issue, int ikt, int ib) {
;         const char* base = lds + cb * BUF;
;         bf16x8 af[MT], bfr[NT];
; #pragma unroll
;         for (int nt = 0; nt < NT; ++nt) {
;             const int br = BM + (nt / NTS) * (BN / NSEG) + wc * (NTS * 16) + (nt % NTS) * 16;
;             bfr[nt] = *(const bf16x8*)(base + (br + l15) * 64 + rsw);
;         }
; #pragma unroll
;         for (int mt = 0; mt < MT; ++mt) af[mt] = *(const bf16x8*)(base + (wr * WM + mt * 16 + l15) * 64 + rsw);
;         constexpr int TOT = MT * NT, PER = (TOT + NIT - 1) / NIT;
; #pragma unroll
;         for (int part = 0; part < NIT; ++part) {
; #pragma unroll
;             for (int q = 0; q < PER; ++q) {
;                 const int idx = part * PER + q;
;                 if (idx < TOT) {
;                     const int mt = idx / NT, nt = idx % NT;
;                     acc[mt][nt] = SWAP ? mfma16(bfr[nt], af[mt], acc[mt][nt]) : mfma16(af[mt], bfr[nt], acc[mt][nt]);
;                 }
;             }
;             __builtin_amdgcn_sched_barrier(0);
;             if (do_issue) issue_one(ikt, ib, part);
;             __builtin_amdgcn_sched_barrier(0);
;         }
; DI void unit_O(const Params& p, char* lds, int l, int tile, int glu_tiles, int tile_b) {
;     ...
;     auto issue_x = [&](int half) {
;         if (l == 0) {
; #pragma unroll 1
;             for (int i = 0; i < 16; ++i) {
;                 const int pc = (wid * 16 + i + xrot) & 127, row = pc >> 2, phys = (pc & 3) * 64 + lane, logical = phys ^ (row & 15);
;                 __builtin_amdgcn_global_load_lds((const unsigned*)(xres + (r0 + half * 32 + row) * 1024 + logical * 4), (unsigned*)(XR + pc * 1024 + lane * 16), 16, 0, 0);
;             }
;         } else {
; #pragma unroll 1
;             for (int i = 0; i < 8; ++i) {
;                 const int pc = (wid * 8 + i + (xrot >> 1)) & 63, kt = pc >> 1, sub = pc & 1;
;                 __builtin_amdgcn_global_load_lds((const unsigned*)(xbres + ((size_t)kt * 128 + half * 32) * 32 + sub * 512 + lane * 8), (unsigned*)(XR + pc * 1024 + lane * 16), 16, 0, 0);
;             }
;         }
;     };
;     issue_x(0);
;     {
;         const float* gsrc = (tid < 256) ? (p.ln_g + l * 1024 + tid * 4) : (p.ln_b + l * 1024 + (tid - 256) * 4);
;         *(f32x4*)(GB + tid * 4) = *(const f32x4*)gsrc;
;     }
.Lpo2_join:
.LBB0_382:
	s_waitcnt vmcnt(0)
	v_add_u32_e32 v0, 0x11000, v140
	s_barrier
	v_add_u32_e32 v134, v0, v141
	v_add_u32_e32 v0, v0, v139
	ds_read_b128 v[130:133], v134 offset:4096
	ds_read_b128 v[138:141], v0
	ds_read_b128 v[142:145], v134 offset:5120
	ds_read_b128 v[146:149], v0 offset:1024
	ds_read_b128 v[150:153], v134 offset:6144
	ds_read_b128 v[154:157], v134 offset:7168
	ds_read_b128 v[158:161], v134 offset:8192
	ds_read_b128 v[162:165], v134 offset:9216
	ds_read_b128 v[166:169], v134 offset:10240
	ds_read_b128 v[170:173], v134 offset:11264
	ds_read_b128 v[174:177], v0 offset:2048
	ds_read_b128 v[178:181], v0 offset:3072
	s_waitcnt lgkmcnt(0)
	v_mfma_f32_16x16x32_bf16 v[98:101], v[130:133], v[138:141], v[98:101]
	v_and_b32_e32 v197, 63, v136
	v_ashrrev_i32_e32 v236, 6, v136
	v_mfma_f32_16x16x32_bf16 v[94:97], v[142:145], v[138:141], v[94:97]
	v_mfma_f32_16x16x32_bf16 v[90:93], v[150:153], v[138:141], v[90:93]
	v_mfma_f32_16x16x32_bf16 v[86:89], v[154:157], v[138:141], v[86:89]
	v_mfma_f32_16x16x32_bf16 v[82:85], v[158:161], v[138:141], v[82:85]
	v_mfma_f32_16x16x32_bf16 v[78:81], v[162:165], v[138:141], v[78:81]
	v_mfma_f32_16x16x32_bf16 v[74:77], v[166:169], v[138:141], v[74:77]
	v_mfma_f32_16x16x32_bf16 v[70:73], v[170:173], v[138:141], v[70:73]
	v_mfma_f32_16x16x32_bf16 v[126:129], v[130:133], v[146:149], v[126:129]
	v_mfma_f32_16x16x32_bf16 v[122:125], v[142:145], v[146:149], v[122:125]
	v_mfma_f32_16x16x32_bf16 v[118:121], v[150:153], v[146:149], v[118:121]
	v_mfma_f32_16x16x32_bf16 v[114:117], v[154:157], v[146:149], v[114:117]
	v_mfma_f32_16x16x32_bf16 v[110:113], v[158:161], v[146:149], v[110:113]
	v_mfma_f32_16x16x32_bf16 v[106:109], v[162:165], v[146:149], v[106:109]
	v_mfma_f32_16x16x32_bf16 v[102:105], v[166:169], v[146:149], v[102:105]
	v_mfma_f32_16x16x32_bf16 v[66:69], v[170:173], v[146:149], v[66:69]
	v_mfma_f32_16x16x32_bf16 v[34:37], v[130:133], v[174:177], v[34:37]
	v_mfma_f32_16x16x32_bf16 v[30:33], v[142:145], v[174:177], v[30:33]
	v_mfma_f32_16x16x32_bf16 v[26:29], v[150:153], v[174:177], v[26:29]
	v_mfma_f32_16x16x32_bf16 v[22:25], v[154:157], v[174:177], v[22:25]
	v_mfma_f32_16x16x32_bf16 v[18:21], v[158:161], v[174:177], v[18:21]
	v_mfma_f32_16x16x32_bf16 v[14:17], v[162:165], v[174:177], v[14:17]
	v_mfma_f32_16x16x32_bf16 v[10:13], v[166:169], v[174:177], v[10:13]
	v_mfma_f32_16x16x32_bf16 v[6:9], v[170:173], v[174:177], v[6:9]
	v_mfma_f32_16x16x32_bf16 v[62:65], v[130:133], v[178:181], v[62:65]
	v_mfma_f32_16x16x32_bf16 v[58:61], v[142:145], v[178:181], v[58:61]
	v_mfma_f32_16x16x32_bf16 v[54:57], v[150:153], v[178:181], v[54:57]
	v_mfma_f32_16x16x32_bf16 v[50:53], v[154:157], v[178:181], v[50:53]
	v_mfma_f32_16x16x32_bf16 v[46:49], v[158:161], v[178:181], v[46:49]
	v_mfma_f32_16x16x32_bf16 v[42:45], v[162:165], v[178:181], v[42:45]
	v_mfma_f32_16x16x32_bf16 v[38:41], v[166:169], v[178:181], v[38:41]
	v_mfma_f32_16x16x32_bf16 v[2:5], v[170:173], v[178:181], v[2:5]
	s_barrier
	s_not_b64 s[6:7], s[10:11]
	v_and_b32_e32 v138, 15, v212
	v_bfe_u32 v139, v212, 4, 2
	v_lshrrev_b32_e32 v140, 6, v212
	v_and_b32_e32 v141, 63, v212
	v_readfirstlane_b32 s90, v140
	v_and_b32_e32 v142, 0xff, v212
	v_lshlrev_b32_e32 v142, 4, v142
	s_cmp_lt_u32 s90, 4
	s_cselect_b32 s92, s14, s12
	s_cselect_b32 s93, s15, s13
	s_nop 3
	global_load_dwordx4 v[176:179], v142, s[92:93]
	v_lshlrev_b32_e32 v143, 4, v212
	v_add_u32_e32 v143, 0x20000, v143
	v_lshlrev_b32_e32 v134, 6, v138
	v_add_u32_e32 v135, 0x22000, v134
	v_lshl_add_u32 v134, v140, 3, v135
	v_lshlrev_b32_e32 v136, 9, v140
	v_lshl_add_u32 v136, v139, 4, v136
	v_add_u32_e32 v136, 0x20000, v136
	s_cmp_lg_u64 s[10:11], 0
	s_cbranch_scc1 .Le2_l1
	s_lshl_b32 s40, s48, 18
	s_lshl_b32 s91, s90, 13
	s_add_u32 s96, s52, s40
	s_addc_u32 s97, s53, 0
	s_add_u32 s96, s96, s91
	s_addc_u32 s97, s97, 0
	s_lshl_b32 s40, s90, 1
	v_xor_b32_e32 v208, s40, v141
	v_lshlrev_b32_e32 v208, 4, v208
	s_add_u32 s40, s40, 1
	v_xor_b32_e32 v209, s40, v141
	v_lshlrev_b32_e32 v209, 4, v209
	v_lshlrev_b32_e32 v133, 12, v138
	v_lshl_add_u32 v133, v140, 9, v133
	v_add_u32_e32 v200, 0, v139
	v_xor_b32_e32 v200, v200, v138
	v_lshl_add_u32 v200, v200, 4, v133
	v_add_u32_e32 v204, 0x10000, v200
	v_add_u32_e32 v201, 4, v139
	v_xor_b32_e32 v201, v201, v138
	v_lshl_add_u32 v201, v201, 4, v133
	v_add_u32_e32 v205, 0x10000, v201
	v_add_u32_e32 v202, 8, v139
	v_xor_b32_e32 v202, v202, v138
	v_lshl_add_u32 v202, v202, 4, v133
	v_add_u32_e32 v206, 0x10000, v202
	v_add_u32_e32 v203, 12, v139
	v_xor_b32_e32 v203, v203, v138
	v_lshl_add_u32 v203, v203, 4, v133
	v_add_u32_e32 v207, 0x10000, v203
	v_and_b32_e32 v137, 1, v139
	v_lshlrev_b32_e32 v137, 5, v137
	v_lshrrev_b32_e32 v130, 1, v139
	v_lshl_or_b32 v137, v130, 4, v137
	v_lshl_or_b32 v137, v138, 6, v137
	v_lshl_or_b32 v137, v140, 15, v137
	s_lshr_b32 s40, s48, 1
	s_lshl_b32 s40, s40, 18
	s_and_b32 s46, s48, 1
	s_lshl_b32 s46, s46, 12
	s_add_u32 s40, s40, s46
	s_add_u32 s78, s56, s40
	s_addc_u32 s79, s57, 0
	s_add_u32 s92, s96, 0x0
	s_addc_u32 s93, s97, 0
	s_add_u32 s40, s91, 0x0
	s_mov_b32 m0, s40
	s_nop 0
	global_load_lds_dwordx4 v208, s[92:93]
	global_load_lds_dwordx4 v208, s[92:93] offset:1024
	global_load_lds_dwordx4 v208, s[92:93] offset:2048
	global_load_lds_dwordx4 v208, s[92:93] offset:3072
	s_add_u32 s92, s96, 0x1000
	s_addc_u32 s93, s97, 0
	s_add_u32 s40, s91, 0x1000
	s_mov_b32 m0, s40
	s_nop 0
	global_load_lds_dwordx4 v209, s[92:93]
	global_load_lds_dwordx4 v209, s[92:93] offset:1024
	global_load_lds_dwordx4 v209, s[92:93] offset:2048
	global_load_lds_dwordx4 v209, s[92:93] offset:3072
	s_add_u32 s92, s96, 0x10000
	s_addc_u32 s93, s97, 0
	s_add_u32 s40, s91, 0x10000
	s_mov_b32 m0, s40
	s_nop 0
	global_load_lds_dwordx4 v208, s[92:93]
	global_load_lds_dwordx4 v208, s[92:93] offset:1024
	global_load_lds_dwordx4 v208, s[92:93] offset:2048
	global_load_lds_dwordx4 v208, s[92:93] offset:3072
	s_add_u32 s92, s96, 0x11000
	s_addc_u32 s93, s97, 0
	s_add_u32 s40, s91, 0x11000
	s_mov_b32 m0, s40
	s_nop 0
	global_load_lds_dwordx4 v209, s[92:93]
	global_load_lds_dwordx4 v209, s[92:93] offset:1024
	global_load_lds_dwordx4 v209, s[92:93] offset:2048
	global_load_lds_dwordx4 v209, s[92:93] offset:3072
	s_waitcnt vmcnt(16)
	ds_write_b128 v143, v[176:179]
	s_waitcnt vmcnt(8) lgkmcnt(0)
	s_barrier
; DI float bf2f(unsigned b) { return __uint_as_float(b << 16); }
; DI void unit_O(const Params& p, char* lds, int l, int tile, int glu_tiles, int tile_b) {
;     ...
;         float s2[2], ss2[2];
; #pragma unroll
;         for (int mh = 0; mh < 2; ++mh) {
;             const int mt = half * 2 + mh, rl = mh * 16 + l15;
;             float s = 0.f, ss = 0.f;
; #pragma unroll
;             for (int nt = 0; nt < 8; ++nt) {
;                 f32x4 xr;
;                 if (l == 0) {
;                     const int chunk = wid * 32 + nt * 4 + quad;
;                     xr = *(const f32x4*)(XR + rl * 4096 + ((chunk ^ l15) << 4));
;                 } else {
;                     const u32x2 hb = *(const u32x2*)(XR + ((wid * 4 + (nt >> 1)) * 32 + rl) * 64 + (nt & 1) * 32 + quad * 8);
;                     xr = (f32x4){bf2f(hb[0] & 0xffffu), bf2f(hb[0] >> 16), bf2f(hb[1] & 0xffffu), bf2f(hb[1] >> 16)};
;                 }
; #pragma unroll
;                 for (int i = 0; i < 4; ++i) { const float v = acc[mt][nt][i] + DN_ALPHA * xr[i]; acc[mt][nt][i] = v; s += v; ss += v * v; }
;             }
;             s2[mh] = s; ss2[mh] = ss;
;         }
; #pragma unroll
;         for (int mh = 0; mh < 2; ++mh) { s2[mh] += __shfl_xor(s2[mh], 16); ss2[mh] += __shfl_xor(ss2[mh], 16); }
; #pragma unroll
;         for (int mh = 0; mh < 2; ++mh) { s2[mh] += __shfl_xor(s2[mh], 32); ss2[mh] += __shfl_xor(ss2[mh], 32); }
;         if (quad == 0) {
; #pragma unroll
;             for (int mh = 0; mh < 2; ++mh) *(f32x2*)&red[((mh * 16 + l15) * 8 + wid) * 2] = (f32x2){s2[mh], ss2[mh]};
;         }
;         __syncthreads();
;         if (half == 0) issue_x(1);
; #pragma unroll
;         for (int mh = 0; mh < 2; ++mh) {
;             const int mt = half * 2 + mh, rl = mh * 16 + l15, row = mt * 16 + l15;
;             float s = 0.f, ss = 0.f;
; #pragma unroll
;             for (int w = 0; w < 4; ++w) { const f32x4 v = *(const f32x4*)&red[rl * 16 + 4 * w]; s += v[0] + v[2]; ss += v[1] + v[3]; }
;             const float mu = s * (1.f / 1024.f);
;             const float var = ss * (1.f / 1024.f) - mu * mu;
;             const float rs = rsqrtf(var + LN_EPS);
	ds_read_b128 v[144:147], v200
	ds_read_b128 v[148:151], v201
	ds_read_b128 v[152:155], v202
	ds_read_b128 v[156:159], v203
	ds_read_b128 v[160:163], v200 offset:256
	ds_read_b128 v[164:167], v201 offset:256
	ds_read_b128 v[168:171], v202 offset:256
	ds_read_b128 v[172:175], v203 offset:256
	s_waitcnt lgkmcnt(7)
	v_fmac_f32_e32 v98, s58, v144
	v_fmac_f32_e32 v99, s58, v145
	v_fmac_f32_e32 v100, s58, v146
	v_fmac_f32_e32 v101, s58, v147
	v_mov_b32_e32 v196, v98
	v_mul_f32_e32 v197, v98, v98
	v_mov_b32_e32 v130, v99
	v_mul_f32_e32 v142, v99, v99
	v_add_f32_e32 v196, v196, v100
	v_fmac_f32_e32 v197, v100, v100
	v_add_f32_e32 v130, v130, v101
	v_fmac_f32_e32 v142, v101, v101
	s_waitcnt lgkmcnt(6)
	v_fmac_f32_e32 v94, s58, v148
	v_fmac_f32_e32 v95, s58, v149
	v_fmac_f32_e32 v96, s58, v150
	v_fmac_f32_e32 v97, s58, v151
	v_add_f32_e32 v196, v196, v94
	v_fmac_f32_e32 v197, v94, v94
	v_add_f32_e32 v130, v130, v95
	v_fmac_f32_e32 v142, v95, v95
	v_add_f32_e32 v196, v196, v96
	v_fmac_f32_e32 v197, v96, v96
	v_add_f32_e32 v130, v130, v97
	v_fmac_f32_e32 v142, v97, v97
	s_waitcnt lgkmcnt(5)
	v_fmac_f32_e32 v90, s58, v152
	v_fmac_f32_e32 v91, s58, v153
	v_fmac_f32_e32 v92, s58, v154
	v_fmac_f32_e32 v93, s58, v155
	v_add_f32_e32 v196, v196, v90
	v_fmac_f32_e32 v197, v90, v90
	v_add_f32_e32 v130, v130, v91
	v_fmac_f32_e32 v142, v91, v91
	v_add_f32_e32 v196, v196, v92
	v_fmac_f32_e32 v197, v92, v92
	v_add_f32_e32 v130, v130, v93
	v_fmac_f32_e32 v142, v93, v93
	s_waitcnt lgkmcnt(4)
	v_fmac_f32_e32 v86, s58, v156
	v_fmac_f32_e32 v87, s58, v157
	v_fmac_f32_e32 v88, s58, v158
	v_fmac_f32_e32 v89, s58, v159
	v_add_f32_e32 v196, v196, v86
	v_fmac_f32_e32 v197, v86, v86
	v_add_f32_e32 v130, v130, v87
	v_fmac_f32_e32 v142, v87, v87
	v_add_f32_e32 v196, v196, v88
	v_fmac_f32_e32 v197, v88, v88
	v_add_f32_e32 v130, v130, v89
	v_fmac_f32_e32 v142, v89, v89
	s_waitcnt lgkmcnt(3)
	v_fmac_f32_e32 v82, s58, v160
	v_fmac_f32_e32 v83, s58, v161
	v_fmac_f32_e32 v84, s58, v162
	v_fmac_f32_e32 v85, s58, v163
	v_add_f32_e32 v196, v196, v82
	v_fmac_f32_e32 v197, v82, v82
	v_add_f32_e32 v130, v130, v83
	v_fmac_f32_e32 v142, v83, v83
	v_add_f32_e32 v196, v196, v84
	v_fmac_f32_e32 v197, v84, v84
	v_add_f32_e32 v130, v130, v85
	v_fmac_f32_e32 v142, v85, v85
	s_waitcnt lgkmcnt(2)
	v_fmac_f32_e32 v78, s58, v164
	v_fmac_f32_e32 v79, s58, v165
	v_fmac_f32_e32 v80, s58, v166
	v_fmac_f32_e32 v81, s58, v167
	v_add_f32_e32 v196, v196, v78
	v_fmac_f32_e32 v197, v78, v78
	v_add_f32_e32 v130, v130, v79
	v_fmac_f32_e32 v142, v79, v79
	v_add_f32_e32 v196, v196, v80
	v_fmac_f32_e32 v197, v80, v80
	v_add_f32_e32 v130, v130, v81
	v_fmac_f32_e32 v142, v81, v81
	s_waitcnt lgkmcnt(1)
	v_fmac_f32_e32 v74, s58, v168
	v_fmac_f32_e32 v75, s58, v169
	v_fmac_f32_e32 v76, s58, v170
	v_fmac_f32_e32 v77, s58, v171
	v_add_f32_e32 v196, v196, v74
	v_fmac_f32_e32 v197, v74, v74
	v_add_f32_e32 v130, v130, v75
	v_fmac_f32_e32 v142, v75, v75
	v_add_f32_e32 v196, v196, v76
	v_fmac_f32_e32 v197, v76, v76
	v_add_f32_e32 v130, v130, v77
	v_fmac_f32_e32 v142, v77, v77
	s_waitcnt lgkmcnt(0)
	v_fmac_f32_e32 v70, s58, v172
	v_fmac_f32_e32 v71, s58, v173
	v_fmac_f32_e32 v72, s58, v174
	v_fmac_f32_e32 v73, s58, v175
	v_add_f32_e32 v196, v196, v70
	v_fmac_f32_e32 v197, v70, v70
	v_add_f32_e32 v130, v130, v71
	v_fmac_f32_e32 v142, v71, v71
	v_add_f32_e32 v196, v196, v72
	v_fmac_f32_e32 v197, v72, v72
	v_add_f32_e32 v130, v130, v73
	v_fmac_f32_e32 v142, v73, v73
	v_add_f32_e32 v196, v196, v130
	v_add_f32_e32 v197, v197, v142
	v_mov_b32_e32 v198, v196
	v_mov_b32_e32 v199, v197
	s_nop 1
	v_permlane16_swap_b32 v198, v196
	v_permlane16_swap_b32 v199, v197
	v_add_f32_e32 v196, v196, v198
	v_add_f32_e32 v197, v197, v199
	v_mov_b32_e32 v198, v196
	v_mov_b32_e32 v199, v197
	s_nop 1
	v_permlane32_swap_b32 v198, v196
	v_permlane32_swap_b32 v199, v197
	v_add_f32_e32 v196, v196, v198
	v_add_f32_e32 v197, v197, v199
	s_mov_b64 exec, 0xffff
	ds_write_b64 v134, v[196:197]
	s_mov_b64 exec, -1
	s_waitcnt lgkmcnt(0)
	s_barrier
	s_add_u32 s92, s96, 0x20000
	s_addc_u32 s93, s97, 0
	s_add_u32 s40, s91, 0x0
	s_mov_b32 m0, s40
	s_nop 0
	global_load_lds_dwordx4 v208, s[92:93]
	global_load_lds_dwordx4 v208, s[92:93] offset:1024
	global_load_lds_dwordx4 v208, s[92:93] offset:2048
	global_load_lds_dwordx4 v208, s[92:93] offset:3072
	s_add_u32 s92, s96, 0x21000
	s_addc_u32 s93, s97, 0
	s_add_u32 s40, s91, 0x1000
	s_mov_b32 m0, s40
	s_nop 0
	global_load_lds_dwordx4 v209, s[92:93]
	global_load_lds_dwordx4 v209, s[92:93] offset:1024
	global_load_lds_dwordx4 v209, s[92:93] offset:2048
	global_load_lds_dwordx4 v209, s[92:93] offset:3072
	ds_read_b128 v[160:163], v135 offset:0
	ds_read_b128 v[164:167], v135 offset:16
	ds_read_b128 v[168:171], v135 offset:32
	ds_read_b128 v[172:175], v135 offset:48
	s_waitcnt lgkmcnt(0)
	v_add_f32_e32 v160, v160, v162
	v_add_f32_e32 v161, v161, v163
	v_add_f32_e32 v164, v164, v166
	v_add_f32_e32 v165, v165, v167
	v_add_f32_e32 v168, v168, v170
	v_add_f32_e32 v169, v169, v171
	v_add_f32_e32 v172, v172, v174
	v_add_f32_e32 v173, v173, v175
	v_add_f32_e32 v160, v160, v164
	v_add_f32_e32 v161, v161, v165
	v_add_f32_e32 v168, v168, v172
	v_add_f32_e32 v169, v169, v173
	v_add_f32_e32 v160, v160, v168
	v_add_f32_e32 v161, v161, v169
	v_mul_f32_e32 v192, 0x3a800000, v160
	v_mul_f32_e32 v193, 0x3a800000, v161
	v_fma_f32 v193, -v192, v192, v193
	v_add_f32_e32 v193, 0x3727c5ac, v193
	v_rsq_f32_e32 v193, v193
	s_nop 0
	s_add_u32 s94, s78, 0x0
	s_addc_u32 s95, s79, 0
	ds_read_b128 v[176:179], v136
	ds_read_b128 v[180:183], v136 offset:4096
	ds_read_b128 v[184:187], v136 offset:64
	ds_read_b128 v[188:191], v136 offset:4160
	s_waitcnt lgkmcnt(2)
; DI unsigned pk2(float lo, float hi) { const f32x2 v = {lo, hi}; const bf16x2_t b = __builtin_convertvector(v, bf16x2_t); return __builtin_bit_cast(unsigned, b); }
; DI size_t xb_off(int tok, int col) { return ((size_t)(((tok >> 7) * 32 + (col >> 5)) * 128 + (tok & 127))) * 32 + (col & 31); }
; DI void unit_O(const Params& p, char* lds, int l, int tile, int glu_tiles, int tile_b) {
;     ...
;         for (int mh = 0; mh < 2; ++mh) {
;             const int mt = half * 2 + mh, rl = mh * 16 + l15, row = mt * 16 + l15;
;             float s = 0.f, ss = 0.f;
; #pragma unroll
;             for (int w = 0; w < 4; ++w) { const f32x4 v = *(const f32x4*)&red[rl * 16 + 4 * w]; s += v[0] + v[2]; ss += v[1] + v[3]; }
;             const float mu = s * (1.f / 1024.f);
;             const float var = ss * (1.f / 1024.f) - mu * mu;
;             const float rs = rsqrtf(var + LN_EPS);
;             float* orow = xo + (r0 + row) * 1024 + wid * 128 + quad * 4;
;             bf16_t* brow = xbo + xb_off((int)r0 + row, wid * 128) + quad * 4;
;             const float* gp = GB + wid * 128 + quad * 4;
; #pragma unroll
;             for (int nt = 0; nt < 8; ++nt) {
;                 const f32x4 g = *(const f32x4*)(gp + nt * 16), bb = *(const f32x4*)(gp + 1024 + nt * 16);
;                 f32x4 o;
; #pragma unroll
;                 for (int i = 0; i < 4; ++i) o[i] = (acc[mt][nt][i] - mu) * rs * g[i] + bb[i];
;                 if (l == 0) *(u32x2*)(brow + (nt >> 1) * 4096 + (nt & 1) * 16) = (u32x2){pk2(o[0], o[1]), pk2(o[2], o[3])};
;                 else *(f32x4*)(orow + nt * 16) = o;
;             }
	v_sub_f32_e32 v98, v98, v192
	v_mul_f32_e32 v98, v98, v193
	v_fma_f32 v98, v176, v98, v180
	v_sub_f32_e32 v99, v99, v192
	v_mul_f32_e32 v99, v99, v193
	v_fma_f32 v99, v177, v99, v181
	v_sub_f32_e32 v100, v100, v192
	v_mul_f32_e32 v100, v100, v193
	v_fma_f32 v100, v178, v100, v182
	v_sub_f32_e32 v101, v101, v192
	v_mul_f32_e32 v101, v101, v193
	v_fma_f32 v101, v179, v101, v183
	v_cvt_pk_bf16_f32 v144, v98, v99
	v_cvt_pk_bf16_f32 v145, v100, v101
	ds_read_b128 v[176:179], v136 offset:128
	ds_read_b128 v[180:183], v136 offset:4224
	s_waitcnt lgkmcnt(2)
	v_sub_f32_e32 v94, v94, v192
	v_mul_f32_e32 v94, v94, v193
	v_fma_f32 v94, v184, v94, v188
	v_sub_f32_e32 v95, v95, v192
	v_mul_f32_e32 v95, v95, v193
	v_fma_f32 v95, v185, v95, v189
	v_sub_f32_e32 v96, v96, v192
	v_mul_f32_e32 v96, v96, v193
	v_fma_f32 v96, v186, v96, v190
	v_sub_f32_e32 v97, v97, v192
	v_mul_f32_e32 v97, v97, v193
	v_fma_f32 v97, v187, v97, v191
	v_cvt_pk_bf16_f32 v146, v94, v95
	v_cvt_pk_bf16_f32 v147, v96, v97
	s_nop 1
	v_permlane16_swap_b32 v144, v146
	v_permlane16_swap_b32 v145, v147
	global_store_dwordx4 v137, v[144:147], s[94:95]
	s_add_u32 s94, s94, 0x2000
	s_addc_u32 s95, s95, 0
	ds_read_b128 v[184:187], v136 offset:192
	ds_read_b128 v[188:191], v136 offset:4288
	s_waitcnt lgkmcnt(2)
	v_sub_f32_e32 v90, v90, v192
	v_mul_f32_e32 v90, v90, v193
	v_fma_f32 v90, v176, v90, v180
	v_sub_f32_e32 v91, v91, v192
	v_mul_f32_e32 v91, v91, v193
	v_fma_f32 v91, v177, v91, v181
	v_sub_f32_e32 v92, v92, v192
	v_mul_f32_e32 v92, v92, v193
	v_fma_f32 v92, v178, v92, v182
	v_sub_f32_e32 v93, v93, v192
	v_mul_f32_e32 v93, v93, v193
	v_fma_f32 v93, v179, v93, v183
	v_cvt_pk_bf16_f32 v152, v90, v91
	v_cvt_pk_bf16_f32 v153, v92, v93
	ds_read_b128 v[176:179], v136 offset:256
	ds_read_b128 v[180:183], v136 offset:4352
	s_waitcnt lgkmcnt(2)
	v_sub_f32_e32 v86, v86, v192
	v_mul_f32_e32 v86, v86, v193
	v_fma_f32 v86, v184, v86, v188
	v_sub_f32_e32 v87, v87, v192
	v_mul_f32_e32 v87, v87, v193
	v_fma_f32 v87, v185, v87, v189
	v_sub_f32_e32 v88, v88, v192
	v_mul_f32_e32 v88, v88, v193
	v_fma_f32 v88, v186, v88, v190
	v_sub_f32_e32 v89, v89, v192
	v_mul_f32_e32 v89, v89, v193
	v_fma_f32 v89, v187, v89, v191
	v_cvt_pk_bf16_f32 v154, v86, v87
	v_cvt_pk_bf16_f32 v155, v88, v89
	s_nop 1
	v_permlane16_swap_b32 v152, v154
	v_permlane16_swap_b32 v153, v155
	global_store_dwordx4 v137, v[152:155], s[94:95]
	s_add_u32 s94, s94, 0x2000
	s_addc_u32 s95, s95, 0
	ds_read_b128 v[184:187], v136 offset:320
	ds_read_b128 v[188:191], v136 offset:4416
	s_waitcnt lgkmcnt(2)
	v_sub_f32_e32 v82, v82, v192
	v_mul_f32_e32 v82, v82, v193
	v_fma_f32 v82, v176, v82, v180
	v_sub_f32_e32 v83, v83, v192
	v_mul_f32_e32 v83, v83, v193
	v_fma_f32 v83, v177, v83, v181
	v_sub_f32_e32 v84, v84, v192
	v_mul_f32_e32 v84, v84, v193
	v_fma_f32 v84, v178, v84, v182
	v_sub_f32_e32 v85, v85, v192
	v_mul_f32_e32 v85, v85, v193
	v_fma_f32 v85, v179, v85, v183
	v_cvt_pk_bf16_f32 v144, v82, v83
	v_cvt_pk_bf16_f32 v145, v84, v85
	ds_read_b128 v[176:179], v136 offset:384
	ds_read_b128 v[180:183], v136 offset:4480
	s_waitcnt lgkmcnt(2)
	v_sub_f32_e32 v78, v78, v192
	v_mul_f32_e32 v78, v78, v193
	v_fma_f32 v78, v184, v78, v188
	v_sub_f32_e32 v79, v79, v192
	v_mul_f32_e32 v79, v79, v193
	v_fma_f32 v79, v185, v79, v189
	v_sub_f32_e32 v80, v80, v192
	v_mul_f32_e32 v80, v80, v193
	v_fma_f32 v80, v186, v80, v190
	v_sub_f32_e32 v81, v81, v192
	v_mul_f32_e32 v81, v81, v193
	v_fma_f32 v81, v187, v81, v191
	v_cvt_pk_bf16_f32 v146, v78, v79
	v_cvt_pk_bf16_f32 v147, v80, v81
	s_nop 1
	v_permlane16_swap_b32 v144, v146
	v_permlane16_swap_b32 v145, v147
	global_store_dwordx4 v137, v[144:147], s[94:95]
	s_add_u32 s94, s94, 0x2000
	s_addc_u32 s95, s95, 0
	ds_read_b128 v[184:187], v136 offset:448
	ds_read_b128 v[188:191], v136 offset:4544
	s_waitcnt lgkmcnt(2)
	v_sub_f32_e32 v74, v74, v192
	v_mul_f32_e32 v74, v74, v193
	v_fma_f32 v74, v176, v74, v180
	v_sub_f32_e32 v75, v75, v192
	v_mul_f32_e32 v75, v75, v193
	v_fma_f32 v75, v177, v75, v181
	v_sub_f32_e32 v76, v76, v192
	v_mul_f32_e32 v76, v76, v193
	v_fma_f32 v76, v178, v76, v182
	v_sub_f32_e32 v77, v77, v192
	v_mul_f32_e32 v77, v77, v193
	v_fma_f32 v77, v179, v77, v183
	v_cvt_pk_bf16_f32 v152, v74, v75
	v_cvt_pk_bf16_f32 v153, v76, v77
	s_waitcnt lgkmcnt(0)
	v_sub_f32_e32 v70, v70, v192
	v_mul_f32_e32 v70, v70, v193
	v_fma_f32 v70, v184, v70, v188
	v_sub_f32_e32 v71, v71, v192
	v_mul_f32_e32 v71, v71, v193
	v_fma_f32 v71, v185, v71, v189
	v_sub_f32_e32 v72, v72, v192
	v_mul_f32_e32 v72, v72, v193
	v_fma_f32 v72, v186, v72, v190
	v_sub_f32_e32 v73, v73, v192
	v_mul_f32_e32 v73, v73, v193
	v_fma_f32 v73, v187, v73, v191
	v_cvt_pk_bf16_f32 v154, v70, v71
	v_cvt_pk_bf16_f32 v155, v72, v73
	s_nop 1
	v_permlane16_swap_b32 v152, v154
	v_permlane16_swap_b32 v153, v155
	global_store_dwordx4 v137, v[152:155], s[94:95]
	s_waitcnt vmcnt(12) lgkmcnt(0)
	s_barrier
; DI float bf2f(unsigned b) { return __uint_as_float(b << 16); }
; DI size_t xb_off(int tok, int col) { return ((size_t)(((tok >> 7) * 32 + (col >> 5)) * 128 + (tok & 127))) * 32 + (col & 31); }
; DI void unit_O(const Params& p, char* lds, int l, int tile, int glu_tiles, int tile_b) {
;     ...
;         for (int mh = 0; mh < 2; ++mh) {
;             const int mt = half * 2 + mh, rl = mh * 16 + l15;
;             float s = 0.f, ss = 0.f;
; #pragma unroll
;             for (int nt = 0; nt < 8; ++nt) {
;                 f32x4 xr;
;                 if (l == 0) {
;                     const int chunk = wid * 32 + nt * 4 + quad;
;                     xr = *(const f32x4*)(XR + rl * 4096 + ((chunk ^ l15) << 4));
;                 } else {
;                     const u32x2 hb = *(const u32x2*)(XR + ((wid * 4 + (nt >> 1)) * 32 + rl) * 64 + (nt & 1) * 32 + quad * 8);
;                     xr = (f32x4){bf2f(hb[0] & 0xffffu), bf2f(hb[0] >> 16), bf2f(hb[1] & 0xffffu), bf2f(hb[1] >> 16)};
;                 }
; #pragma unroll
;                 for (int i = 0; i < 4; ++i) { const float v = acc[mt][nt][i] + DN_ALPHA * xr[i]; acc[mt][nt][i] = v; s += v; ss += v * v; }
;             }
;             s2[mh] = s; ss2[mh] = ss;
;         }
; #pragma unroll
;         for (int mh = 0; mh < 2; ++mh) { s2[mh] += __shfl_xor(s2[mh], 16); ss2[mh] += __shfl_xor(ss2[mh], 16); }
; #pragma unroll
;         for (int mh = 0; mh < 2; ++mh) { s2[mh] += __shfl_xor(s2[mh], 32); ss2[mh] += __shfl_xor(ss2[mh], 32); }
;         if (quad == 0) {
; #pragma unroll
;             for (int mh = 0; mh < 2; ++mh) *(f32x2*)&red[((mh * 16 + l15) * 8 + wid) * 2] = (f32x2){s2[mh], ss2[mh]};
;         }
;         __syncthreads();
;         if (half == 0) issue_x(1);
; #pragma unroll
;         for (int mh = 0; mh < 2; ++mh) {
;             const int mt = half * 2 + mh, rl = mh * 16 + l15, row = mt * 16 + l15;
;             float s = 0.f, ss = 0.f;
; #pragma unroll
;             for (int w = 0; w < 4; ++w) { const f32x4 v = *(const f32x4*)&red[rl * 16 + 4 * w]; s += v[0] + v[2]; ss += v[1] + v[3]; }
;             const float mu = s * (1.f / 1024.f);
;             const float var = ss * (1.f / 1024.f) - mu * mu;
;             const float rs = rsqrtf(var + LN_EPS);
;             float* orow = xo + (r0 + row) * 1024 + wid * 128 + quad * 4;
;             bf16_t* brow = xbo + xb_off((int)r0 + row, wid * 128) + quad * 4;
	ds_read_b128 v[144:147], v204
	ds_read_b128 v[148:151], v205
	ds_read_b128 v[152:155], v206
	ds_read_b128 v[156:159], v207
	ds_read_b128 v[160:163], v204 offset:256
	ds_read_b128 v[164:167], v205 offset:256
	ds_read_b128 v[168:171], v206 offset:256
	ds_read_b128 v[172:175], v207 offset:256
	s_waitcnt lgkmcnt(7)
	v_fmac_f32_e32 v126, s58, v144
	v_fmac_f32_e32 v127, s58, v145
	v_fmac_f32_e32 v128, s58, v146
	v_fmac_f32_e32 v129, s58, v147
	v_mov_b32_e32 v196, v126
	v_mul_f32_e32 v197, v126, v126
	v_mov_b32_e32 v130, v127
	v_mul_f32_e32 v142, v127, v127
	v_add_f32_e32 v196, v196, v128
	v_fmac_f32_e32 v197, v128, v128
	v_add_f32_e32 v130, v130, v129
	v_fmac_f32_e32 v142, v129, v129
	s_waitcnt lgkmcnt(6)
	v_fmac_f32_e32 v122, s58, v148
	v_fmac_f32_e32 v123, s58, v149
	v_fmac_f32_e32 v124, s58, v150
	v_fmac_f32_e32 v125, s58, v151
	v_add_f32_e32 v196, v196, v122
	v_fmac_f32_e32 v197, v122, v122
	v_add_f32_e32 v130, v130, v123
	v_fmac_f32_e32 v142, v123, v123
	v_add_f32_e32 v196, v196, v124
	v_fmac_f32_e32 v197, v124, v124
	v_add_f32_e32 v130, v130, v125
	v_fmac_f32_e32 v142, v125, v125
	s_waitcnt lgkmcnt(5)
	v_fmac_f32_e32 v118, s58, v152
	v_fmac_f32_e32 v119, s58, v153
	v_fmac_f32_e32 v120, s58, v154
	v_fmac_f32_e32 v121, s58, v155
	v_add_f32_e32 v196, v196, v118
	v_fmac_f32_e32 v197, v118, v118
	v_add_f32_e32 v130, v130, v119
	v_fmac_f32_e32 v142, v119, v119
	v_add_f32_e32 v196, v196, v120
	v_fmac_f32_e32 v197, v120, v120
	v_add_f32_e32 v130, v130, v121
	v_fmac_f32_e32 v142, v121, v121
	s_waitcnt lgkmcnt(4)
	v_fmac_f32_e32 v114, s58, v156
	v_fmac_f32_e32 v115, s58, v157
	v_fmac_f32_e32 v116, s58, v158
	v_fmac_f32_e32 v117, s58, v159
	v_add_f32_e32 v196, v196, v114
	v_fmac_f32_e32 v197, v114, v114
	v_add_f32_e32 v130, v130, v115
	v_fmac_f32_e32 v142, v115, v115
	v_add_f32_e32 v196, v196, v116
	v_fmac_f32_e32 v197, v116, v116
	v_add_f32_e32 v130, v130, v117
	v_fmac_f32_e32 v142, v117, v117
	s_waitcnt lgkmcnt(3)
	v_fmac_f32_e32 v110, s58, v160
	v_fmac_f32_e32 v111, s58, v161
	v_fmac_f32_e32 v112, s58, v162
	v_fmac_f32_e32 v113, s58, v163
	v_add_f32_e32 v196, v196, v110
	v_fmac_f32_e32 v197, v110, v110
	v_add_f32_e32 v130, v130, v111
	v_fmac_f32_e32 v142, v111, v111
	v_add_f32_e32 v196, v196, v112
	v_fmac_f32_e32 v197, v112, v112
	v_add_f32_e32 v130, v130, v113
	v_fmac_f32_e32 v142, v113, v113
	s_waitcnt lgkmcnt(2)
	v_fmac_f32_e32 v106, s58, v164
	v_fmac_f32_e32 v107, s58, v165
	v_fmac_f32_e32 v108, s58, v166
	v_fmac_f32_e32 v109, s58, v167
	v_add_f32_e32 v196, v196, v106
	v_fmac_f32_e32 v197, v106, v106
	v_add_f32_e32 v130, v130, v107
	v_fmac_f32_e32 v142, v107, v107
	v_add_f32_e32 v196, v196, v108
	v_fmac_f32_e32 v197, v108, v108
	v_add_f32_e32 v130, v130, v109
	v_fmac_f32_e32 v142, v109, v109
	s_waitcnt lgkmcnt(1)
	v_fmac_f32_e32 v102, s58, v168
	v_fmac_f32_e32 v103, s58, v169
	v_fmac_f32_e32 v104, s58, v170
	v_fmac_f32_e32 v105, s58, v171
	v_add_f32_e32 v196, v196, v102
	v_fmac_f32_e32 v197, v102, v102
	v_add_f32_e32 v130, v130, v103
	v_fmac_f32_e32 v142, v103, v103
	v_add_f32_e32 v196, v196, v104
	v_fmac_f32_e32 v197, v104, v104
	v_add_f32_e32 v130, v130, v105
	v_fmac_f32_e32 v142, v105, v105
	s_waitcnt lgkmcnt(0)
	v_fmac_f32_e32 v66, s58, v172
	v_fmac_f32_e32 v67, s58, v173
	v_fmac_f32_e32 v68, s58, v174
	v_fmac_f32_e32 v69, s58, v175
	v_add_f32_e32 v196, v196, v66
	v_fmac_f32_e32 v197, v66, v66
	v_add_f32_e32 v130, v130, v67
	v_fmac_f32_e32 v142, v67, v67
	v_add_f32_e32 v196, v196, v68
	v_fmac_f32_e32 v197, v68, v68
	v_add_f32_e32 v130, v130, v69
	v_fmac_f32_e32 v142, v69, v69
	v_add_f32_e32 v196, v196, v130
	v_add_f32_e32 v197, v197, v142
	v_mov_b32_e32 v198, v196
	v_mov_b32_e32 v199, v197
	s_nop 1
	v_permlane16_swap_b32 v198, v196
	v_permlane16_swap_b32 v199, v197
	v_add_f32_e32 v196, v196, v198
	v_add_f32_e32 v197, v197, v199
	v_mov_b32_e32 v198, v196
	v_mov_b32_e32 v199, v197
	s_nop 1
	v_permlane32_swap_b32 v198, v196
	v_permlane32_swap_b32 v199, v197
	v_add_f32_e32 v196, v196, v198
	v_add_f32_e32 v197, v197, v199
	s_mov_b64 exec, 0xffff
	ds_write_b64 v134, v[196:197]
	s_mov_b64 exec, -1
	s_waitcnt lgkmcnt(0)
	s_barrier
	s_add_u32 s92, s96, 0x30000
	s_addc_u32 s93, s97, 0
	s_add_u32 s40, s91, 0x10000
	s_mov_b32 m0, s40
	s_nop 0
	global_load_lds_dwordx4 v208, s[92:93]
	global_load_lds_dwordx4 v208, s[92:93] offset:1024
	global_load_lds_dwordx4 v208, s[92:93] offset:2048
	global_load_lds_dwordx4 v208, s[92:93] offset:3072
	s_add_u32 s92, s96, 0x31000
	s_addc_u32 s93, s97, 0
	s_add_u32 s40, s91, 0x11000
	s_mov_b32 m0, s40
	s_nop 0
	global_load_lds_dwordx4 v209, s[92:93]
	global_load_lds_dwordx4 v209, s[92:93] offset:1024
	global_load_lds_dwordx4 v209, s[92:93] offset:2048
	global_load_lds_dwordx4 v209, s[92:93] offset:3072
	ds_read_b128 v[160:163], v135 offset:0
	ds_read_b128 v[164:167], v135 offset:16
	ds_read_b128 v[168:171], v135 offset:32
	ds_read_b128 v[172:175], v135 offset:48
	s_waitcnt lgkmcnt(0)
	v_add_f32_e32 v160, v160, v162
	v_add_f32_e32 v161, v161, v163
	v_add_f32_e32 v164, v164, v166
	v_add_f32_e32 v165, v165, v167
	v_add_f32_e32 v168, v168, v170
	v_add_f32_e32 v169, v169, v171
	v_add_f32_e32 v172, v172, v174
	v_add_f32_e32 v173, v173, v175
	v_add_f32_e32 v160, v160, v164
	v_add_f32_e32 v161, v161, v165
	v_add_f32_e32 v168, v168, v172
	v_add_f32_e32 v169, v169, v173
	v_add_f32_e32 v160, v160, v168
	v_add_f32_e32 v161, v161, v169
	v_mul_f32_e32 v192, 0x3a800000, v160
	v_mul_f32_e32 v193, 0x3a800000, v161
	v_fma_f32 v193, -v192, v192, v193
	v_add_f32_e32 v193, 0x3727c5ac, v193
	v_rsq_f32_e32 v193, v193
	s_nop 0
	s_add_u32 s94, s78, 0x400
	s_addc_u32 s95, s79, 0
	ds_read_b128 v[176:179], v136
	ds_read_b128 v[180:183], v136 offset:4096
	ds_read_b128 v[184:187], v136 offset:64
	ds_read_b128 v[188:191], v136 offset:4160
	s_waitcnt lgkmcnt(2)
; DI unsigned pk2(float lo, float hi) { const f32x2 v = {lo, hi}; const bf16x2_t b = __builtin_convertvector(v, bf16x2_t); return __builtin_bit_cast(unsigned, b); }
; DI void unit_O(const Params& p, char* lds, int l, int tile, int glu_tiles, int tile_b) {
;     ...
;             for (int nt = 0; nt < 8; ++nt) {
;                 const f32x4 g = *(const f32x4*)(gp + nt * 16), bb = *(const f32x4*)(gp + 1024 + nt * 16);
;                 f32x4 o;
; #pragma unroll
;                 for (int i = 0; i < 4; ++i) o[i] = (acc[mt][nt][i] - mu) * rs * g[i] + bb[i];
;                 if (l == 0) *(u32x2*)(brow + (nt >> 1) * 4096 + (nt & 1) * 16) = (u32x2){pk2(o[0], o[1]), pk2(o[2], o[3])};
;                 else *(f32x4*)(orow + nt * 16) = o;
;             }
	v_sub_f32_e32 v126, v126, v192
	v_mul_f32_e32 v126, v126, v193
	v_fma_f32 v126, v176, v126, v180
	v_sub_f32_e32 v127, v127, v192
	v_mul_f32_e32 v127, v127, v193
	v_fma_f32 v127, v177, v127, v181
	v_sub_f32_e32 v128, v128, v192
	v_mul_f32_e32 v128, v128, v193
	v_fma_f32 v128, v178, v128, v182
	v_sub_f32_e32 v129, v129, v192
	v_mul_f32_e32 v129, v129, v193
	v_fma_f32 v129, v179, v129, v183
	v_cvt_pk_bf16_f32 v144, v126, v127
	v_cvt_pk_bf16_f32 v145, v128, v129
	ds_read_b128 v[176:179], v136 offset:128
	ds_read_b128 v[180:183], v136 offset:4224
	s_waitcnt lgkmcnt(2)
	v_sub_f32_e32 v122, v122, v192
	v_mul_f32_e32 v122, v122, v193
	v_fma_f32 v122, v184, v122, v188
	v_sub_f32_e32 v123, v123, v192
	v_mul_f32_e32 v123, v123, v193
	v_fma_f32 v123, v185, v123, v189
	v_sub_f32_e32 v124, v124, v192
	v_mul_f32_e32 v124, v124, v193
	v_fma_f32 v124, v186, v124, v190
	v_sub_f32_e32 v125, v125, v192
	v_mul_f32_e32 v125, v125, v193
	v_fma_f32 v125, v187, v125, v191
	v_cvt_pk_bf16_f32 v146, v122, v123
	v_cvt_pk_bf16_f32 v147, v124, v125
	s_nop 1
	v_permlane16_swap_b32 v144, v146
	v_permlane16_swap_b32 v145, v147
	global_store_dwordx4 v137, v[144:147], s[94:95]
	s_add_u32 s94, s94, 0x2000
	s_addc_u32 s95, s95, 0
	ds_read_b128 v[184:187], v136 offset:192
	ds_read_b128 v[188:191], v136 offset:4288
	s_waitcnt lgkmcnt(2)
	v_sub_f32_e32 v118, v118, v192
	v_mul_f32_e32 v118, v118, v193
	v_fma_f32 v118, v176, v118, v180
	v_sub_f32_e32 v119, v119, v192
	v_mul_f32_e32 v119, v119, v193
	v_fma_f32 v119, v177, v119, v181
	v_sub_f32_e32 v120, v120, v192
	v_mul_f32_e32 v120, v120, v193
	v_fma_f32 v120, v178, v120, v182
	v_sub_f32_e32 v121, v121, v192
	v_mul_f32_e32 v121, v121, v193
	v_fma_f32 v121, v179, v121, v183
	v_cvt_pk_bf16_f32 v152, v118, v119
	v_cvt_pk_bf16_f32 v153, v120, v121
	ds_read_b128 v[176:179], v136 offset:256
	ds_read_b128 v[180:183], v136 offset:4352
	s_waitcnt lgkmcnt(2)
	v_sub_f32_e32 v114, v114, v192
	v_mul_f32_e32 v114, v114, v193
	v_fma_f32 v114, v184, v114, v188
	v_sub_f32_e32 v115, v115, v192
	v_mul_f32_e32 v115, v115, v193
	v_fma_f32 v115, v185, v115, v189
	v_sub_f32_e32 v116, v116, v192
	v_mul_f32_e32 v116, v116, v193
	v_fma_f32 v116, v186, v116, v190
	v_sub_f32_e32 v117, v117, v192
	v_mul_f32_e32 v117, v117, v193
	v_fma_f32 v117, v187, v117, v191
	v_cvt_pk_bf16_f32 v154, v114, v115
	v_cvt_pk_bf16_f32 v155, v116, v117
	s_nop 1
	v_permlane16_swap_b32 v152, v154
	v_permlane16_swap_b32 v153, v155
	global_store_dwordx4 v137, v[152:155], s[94:95]
	s_add_u32 s94, s94, 0x2000
	s_addc_u32 s95, s95, 0
	ds_read_b128 v[184:187], v136 offset:320
	ds_read_b128 v[188:191], v136 offset:4416
	s_waitcnt lgkmcnt(2)
	v_sub_f32_e32 v110, v110, v192
	v_mul_f32_e32 v110, v110, v193
	v_fma_f32 v110, v176, v110, v180
	v_sub_f32_e32 v111, v111, v192
	v_mul_f32_e32 v111, v111, v193
	v_fma_f32 v111, v177, v111, v181
	v_sub_f32_e32 v112, v112, v192
	v_mul_f32_e32 v112, v112, v193
	v_fma_f32 v112, v178, v112, v182
	v_sub_f32_e32 v113, v113, v192
	v_mul_f32_e32 v113, v113, v193
	v_fma_f32 v113, v179, v113, v183
	v_cvt_pk_bf16_f32 v144, v110, v111
	v_cvt_pk_bf16_f32 v145, v112, v113
	ds_read_b128 v[176:179], v136 offset:384
	ds_read_b128 v[180:183], v136 offset:4480
	s_waitcnt lgkmcnt(2)
	v_sub_f32_e32 v106, v106, v192
	v_mul_f32_e32 v106, v106, v193
	v_fma_f32 v106, v184, v106, v188
	v_sub_f32_e32 v107, v107, v192
	v_mul_f32_e32 v107, v107, v193
	v_fma_f32 v107, v185, v107, v189
	v_sub_f32_e32 v108, v108, v192
	v_mul_f32_e32 v108, v108, v193
	v_fma_f32 v108, v186, v108, v190
	v_sub_f32_e32 v109, v109, v192
	v_mul_f32_e32 v109, v109, v193
	v_fma_f32 v109, v187, v109, v191
	v_cvt_pk_bf16_f32 v146, v106, v107
	v_cvt_pk_bf16_f32 v147, v108, v109
	s_nop 1
	v_permlane16_swap_b32 v144, v146
	v_permlane16_swap_b32 v145, v147
	global_store_dwordx4 v137, v[144:147], s[94:95]
	s_add_u32 s94, s94, 0x2000
	s_addc_u32 s95, s95, 0
	ds_read_b128 v[184:187], v136 offset:448
	ds_read_b128 v[188:191], v136 offset:4544
	s_waitcnt lgkmcnt(2)
	v_sub_f32_e32 v102, v102, v192
	v_mul_f32_e32 v102, v102, v193
	v_fma_f32 v102, v176, v102, v180
	v_sub_f32_e32 v103, v103, v192
	v_mul_f32_e32 v103, v103, v193
	v_fma_f32 v103, v177, v103, v181
	v_sub_f32_e32 v104, v104, v192
	v_mul_f32_e32 v104, v104, v193
	v_fma_f32 v104, v178, v104, v182
	v_sub_f32_e32 v105, v105, v192
	v_mul_f32_e32 v105, v105, v193
	v_fma_f32 v105, v179, v105, v183
	v_cvt_pk_bf16_f32 v152, v102, v103
	v_cvt_pk_bf16_f32 v153, v104, v105
	s_waitcnt lgkmcnt(0)
	v_sub_f32_e32 v66, v66, v192
	v_mul_f32_e32 v66, v66, v193
	v_fma_f32 v66, v184, v66, v188
	v_sub_f32_e32 v67, v67, v192
	v_mul_f32_e32 v67, v67, v193
	v_fma_f32 v67, v185, v67, v189
	v_sub_f32_e32 v68, v68, v192
	v_mul_f32_e32 v68, v68, v193
	v_fma_f32 v68, v186, v68, v190
	v_sub_f32_e32 v69, v69, v192
	v_mul_f32_e32 v69, v69, v193
	v_fma_f32 v69, v187, v69, v191
	v_cvt_pk_bf16_f32 v154, v66, v67
	v_cvt_pk_bf16_f32 v155, v68, v69
	s_nop 1
	v_permlane16_swap_b32 v152, v154
	v_permlane16_swap_b32 v153, v155
	global_store_dwordx4 v137, v[152:155], s[94:95]
	s_waitcnt vmcnt(16) lgkmcnt(0)
	s_barrier
; DI float bf2f(unsigned b) { return __uint_as_float(b << 16); }
; DI void unit_O(const Params& p, char* lds, int l, int tile, int glu_tiles, int tile_b) {
;     ...
;         for (int mh = 0; mh < 2; ++mh) {
;             const int mt = half * 2 + mh, rl = mh * 16 + l15;
;             float s = 0.f, ss = 0.f;
; #pragma unroll
;             for (int nt = 0; nt < 8; ++nt) {
;                 f32x4 xr;
;                 if (l == 0) {
;                     const int chunk = wid * 32 + nt * 4 + quad;
;                     xr = *(const f32x4*)(XR + rl * 4096 + ((chunk ^ l15) << 4));
;                 } else {
;                     const u32x2 hb = *(const u32x2*)(XR + ((wid * 4 + (nt >> 1)) * 32 + rl) * 64 + (nt & 1) * 32 + quad * 8);
;                     xr = (f32x4){bf2f(hb[0] & 0xffffu), bf2f(hb[0] >> 16), bf2f(hb[1] & 0xffffu), bf2f(hb[1] >> 16)};
;                 }
; #pragma unroll
;                 for (int i = 0; i < 4; ++i) { const float v = acc[mt][nt][i] + DN_ALPHA * xr[i]; acc[mt][nt][i] = v; s += v; ss += v * v; }
;             }
;             s2[mh] = s; ss2[mh] = ss;
;         }
; #pragma unroll
;         for (int mh = 0; mh < 2; ++mh) { s2[mh] += __shfl_xor(s2[mh], 16); ss2[mh] += __shfl_xor(ss2[mh], 16); }
; #pragma unroll
;         for (int mh = 0; mh < 2; ++mh) { s2[mh] += __shfl_xor(s2[mh], 32); ss2[mh] += __shfl_xor(ss2[mh], 32); }
;         if (quad == 0) {
; #pragma unroll
;             for (int mh = 0; mh < 2; ++mh) *(f32x2*)&red[((mh * 16 + l15) * 8 + wid) * 2] = (f32x2){s2[mh], ss2[mh]};
;         }
;         __syncthreads();
;         if (half == 0) issue_x(1);
; #pragma unroll
;         for (int mh = 0; mh < 2; ++mh) {
;             const int mt = half * 2 + mh, rl = mh * 16 + l15, row = mt * 16 + l15;
;             float s = 0.f, ss = 0.f;
; #pragma unroll
;             for (int w = 0; w < 4; ++w) { const f32x4 v = *(const f32x4*)&red[rl * 16 + 4 * w]; s += v[0] + v[2]; ss += v[1] + v[3]; }
;             const float mu = s * (1.f / 1024.f);
;             const float var = ss * (1.f / 1024.f) - mu * mu;
;             const float rs = rsqrtf(var + LN_EPS);
;             float* orow = xo + (r0 + row) * 1024 + wid * 128 + quad * 4;
;             bf16_t* brow = xbo + xb_off((int)r0 + row, wid * 128) + quad * 4;
;             const float* gp = GB + wid * 128 + quad * 4;
; #pragma unroll
;             for (int nt = 0; nt < 8; ++nt) {
	ds_read_b128 v[144:147], v200
	ds_read_b128 v[148:151], v201
	ds_read_b128 v[152:155], v202
	ds_read_b128 v[156:159], v203
	ds_read_b128 v[160:163], v200 offset:256
	ds_read_b128 v[164:167], v201 offset:256
	ds_read_b128 v[168:171], v202 offset:256
	ds_read_b128 v[172:175], v203 offset:256
	s_waitcnt lgkmcnt(7)
	v_fmac_f32_e32 v34, s58, v144
	v_fmac_f32_e32 v35, s58, v145
	v_fmac_f32_e32 v36, s58, v146
	v_fmac_f32_e32 v37, s58, v147
	v_mov_b32_e32 v196, v34
	v_mul_f32_e32 v197, v34, v34
	v_mov_b32_e32 v130, v35
	v_mul_f32_e32 v142, v35, v35
	v_add_f32_e32 v196, v196, v36
	v_fmac_f32_e32 v197, v36, v36
	v_add_f32_e32 v130, v130, v37
	v_fmac_f32_e32 v142, v37, v37
	s_waitcnt lgkmcnt(6)
	v_fmac_f32_e32 v30, s58, v148
	v_fmac_f32_e32 v31, s58, v149
	v_fmac_f32_e32 v32, s58, v150
	v_fmac_f32_e32 v33, s58, v151
	v_add_f32_e32 v196, v196, v30
	v_fmac_f32_e32 v197, v30, v30
	v_add_f32_e32 v130, v130, v31
	v_fmac_f32_e32 v142, v31, v31
	v_add_f32_e32 v196, v196, v32
	v_fmac_f32_e32 v197, v32, v32
	v_add_f32_e32 v130, v130, v33
	v_fmac_f32_e32 v142, v33, v33
	s_waitcnt lgkmcnt(5)
	v_fmac_f32_e32 v26, s58, v152
	v_fmac_f32_e32 v27, s58, v153
	v_fmac_f32_e32 v28, s58, v154
	v_fmac_f32_e32 v29, s58, v155
	v_add_f32_e32 v196, v196, v26
	v_fmac_f32_e32 v197, v26, v26
	v_add_f32_e32 v130, v130, v27
	v_fmac_f32_e32 v142, v27, v27
	v_add_f32_e32 v196, v196, v28
	v_fmac_f32_e32 v197, v28, v28
	v_add_f32_e32 v130, v130, v29
	v_fmac_f32_e32 v142, v29, v29
	s_waitcnt lgkmcnt(4)
	v_fmac_f32_e32 v22, s58, v156
	v_fmac_f32_e32 v23, s58, v157
	v_fmac_f32_e32 v24, s58, v158
	v_fmac_f32_e32 v25, s58, v159
	v_add_f32_e32 v196, v196, v22
	v_fmac_f32_e32 v197, v22, v22
	v_add_f32_e32 v130, v130, v23
	v_fmac_f32_e32 v142, v23, v23
	v_add_f32_e32 v196, v196, v24
	v_fmac_f32_e32 v197, v24, v24
	v_add_f32_e32 v130, v130, v25
	v_fmac_f32_e32 v142, v25, v25
	s_waitcnt lgkmcnt(3)
	v_fmac_f32_e32 v18, s58, v160
	v_fmac_f32_e32 v19, s58, v161
	v_fmac_f32_e32 v20, s58, v162
	v_fmac_f32_e32 v21, s58, v163
	v_add_f32_e32 v196, v196, v18
	v_fmac_f32_e32 v197, v18, v18
	v_add_f32_e32 v130, v130, v19
	v_fmac_f32_e32 v142, v19, v19
	v_add_f32_e32 v196, v196, v20
	v_fmac_f32_e32 v197, v20, v20
	v_add_f32_e32 v130, v130, v21
	v_fmac_f32_e32 v142, v21, v21
	s_waitcnt lgkmcnt(2)
	v_fmac_f32_e32 v14, s58, v164
	v_fmac_f32_e32 v15, s58, v165
	v_fmac_f32_e32 v16, s58, v166
	v_fmac_f32_e32 v17, s58, v167
	v_add_f32_e32 v196, v196, v14
	v_fmac_f32_e32 v197, v14, v14
	v_add_f32_e32 v130, v130, v15
	v_fmac_f32_e32 v142, v15, v15
	v_add_f32_e32 v196, v196, v16
	v_fmac_f32_e32 v197, v16, v16
	v_add_f32_e32 v130, v130, v17
	v_fmac_f32_e32 v142, v17, v17
	s_waitcnt lgkmcnt(1)
	v_fmac_f32_e32 v10, s58, v168
	v_fmac_f32_e32 v11, s58, v169
	v_fmac_f32_e32 v12, s58, v170
	v_fmac_f32_e32 v13, s58, v171
	v_add_f32_e32 v196, v196, v10
	v_fmac_f32_e32 v197, v10, v10
	v_add_f32_e32 v130, v130, v11
	v_fmac_f32_e32 v142, v11, v11
	v_add_f32_e32 v196, v196, v12
	v_fmac_f32_e32 v197, v12, v12
	v_add_f32_e32 v130, v130, v13
	v_fmac_f32_e32 v142, v13, v13
	s_waitcnt lgkmcnt(0)
	v_fmac_f32_e32 v6, s58, v172
	v_fmac_f32_e32 v7, s58, v173
	v_fmac_f32_e32 v8, s58, v174
	v_fmac_f32_e32 v9, s58, v175
	v_add_f32_e32 v196, v196, v6
	v_fmac_f32_e32 v197, v6, v6
	v_add_f32_e32 v130, v130, v7
	v_fmac_f32_e32 v142, v7, v7
	v_add_f32_e32 v196, v196, v8
	v_fmac_f32_e32 v197, v8, v8
	v_add_f32_e32 v130, v130, v9
	v_fmac_f32_e32 v142, v9, v9
	v_add_f32_e32 v196, v196, v130
	v_add_f32_e32 v197, v197, v142
	v_mov_b32_e32 v198, v196
	v_mov_b32_e32 v199, v197
	s_nop 1
	v_permlane16_swap_b32 v198, v196
	v_permlane16_swap_b32 v199, v197
	v_add_f32_e32 v196, v196, v198
	v_add_f32_e32 v197, v197, v199
	v_mov_b32_e32 v198, v196
	v_mov_b32_e32 v199, v197
	s_nop 1
	v_permlane32_swap_b32 v198, v196
	v_permlane32_swap_b32 v199, v197
	v_add_f32_e32 v196, v196, v198
	v_add_f32_e32 v197, v197, v199
	s_mov_b64 exec, 0xffff
	ds_write_b64 v134, v[196:197]
	s_mov_b64 exec, -1
	s_waitcnt lgkmcnt(0)
	s_barrier
	ds_read_b128 v[160:163], v135 offset:0
	ds_read_b128 v[164:167], v135 offset:16
	ds_read_b128 v[168:171], v135 offset:32
	ds_read_b128 v[172:175], v135 offset:48
	s_waitcnt lgkmcnt(0)
	v_add_f32_e32 v160, v160, v162
	v_add_f32_e32 v161, v161, v163
	v_add_f32_e32 v164, v164, v166
	v_add_f32_e32 v165, v165, v167
	v_add_f32_e32 v168, v168, v170
	v_add_f32_e32 v169, v169, v171
	v_add_f32_e32 v172, v172, v174
	v_add_f32_e32 v173, v173, v175
	v_add_f32_e32 v160, v160, v164
	v_add_f32_e32 v161, v161, v165
	v_add_f32_e32 v168, v168, v172
	v_add_f32_e32 v169, v169, v173
	v_add_f32_e32 v160, v160, v168
	v_add_f32_e32 v161, v161, v169
	v_mul_f32_e32 v192, 0x3a800000, v160
	v_mul_f32_e32 v193, 0x3a800000, v161
	v_fma_f32 v193, -v192, v192, v193
	v_add_f32_e32 v193, 0x3727c5ac, v193
	v_rsq_f32_e32 v193, v193
	s_nop 0
	s_add_u32 s94, s78, 0x800
	s_addc_u32 s95, s79, 0
	ds_read_b128 v[176:179], v136
	ds_read_b128 v[180:183], v136 offset:4096
	ds_read_b128 v[184:187], v136 offset:64
	ds_read_b128 v[188:191], v136 offset:4160
	s_waitcnt lgkmcnt(2)
	v_sub_f32_e32 v34, v34, v192
	v_mul_f32_e32 v34, v34, v193
	v_fma_f32 v34, v176, v34, v180
	v_sub_f32_e32 v35, v35, v192
	v_mul_f32_e32 v35, v35, v193
	v_fma_f32 v35, v177, v35, v181
	v_sub_f32_e32 v36, v36, v192
	v_mul_f32_e32 v36, v36, v193
	v_fma_f32 v36, v178, v36, v182
	v_sub_f32_e32 v37, v37, v192
	v_mul_f32_e32 v37, v37, v193
	v_fma_f32 v37, v179, v37, v183
	v_cvt_pk_bf16_f32 v144, v34, v35
	v_cvt_pk_bf16_f32 v145, v36, v37
	ds_read_b128 v[176:179], v136 offset:128
	ds_read_b128 v[180:183], v136 offset:4224
	s_waitcnt lgkmcnt(2)
; DI unsigned pk2(float lo, float hi) { const f32x2 v = {lo, hi}; const bf16x2_t b = __builtin_convertvector(v, bf16x2_t); return __builtin_bit_cast(unsigned, b); }
; DI void unit_O(const Params& p, char* lds, int l, int tile, int glu_tiles, int tile_b) {
;     ...
;             for (int nt = 0; nt < 8; ++nt) {
;                 const f32x4 g = *(const f32x4*)(gp + nt * 16), bb = *(const f32x4*)(gp + 1024 + nt * 16);
;                 f32x4 o;
; #pragma unroll
;                 for (int i = 0; i < 4; ++i) o[i] = (acc[mt][nt][i] - mu) * rs * g[i] + bb[i];
;                 if (l == 0) *(u32x2*)(brow + (nt >> 1) * 4096 + (nt & 1) * 16) = (u32x2){pk2(o[0], o[1]), pk2(o[2], o[3])};
;                 else *(f32x4*)(orow + nt * 16) = o;
;             }
	v_sub_f32_e32 v30, v30, v192
	v_mul_f32_e32 v30, v30, v193
	v_fma_f32 v30, v184, v30, v188
	v_sub_f32_e32 v31, v31, v192
	v_mul_f32_e32 v31, v31, v193
	v_fma_f32 v31, v185, v31, v189
	v_sub_f32_e32 v32, v32, v192
	v_mul_f32_e32 v32, v32, v193
	v_fma_f32 v32, v186, v32, v190
	v_sub_f32_e32 v33, v33, v192
	v_mul_f32_e32 v33, v33, v193
	v_fma_f32 v33, v187, v33, v191
	v_cvt_pk_bf16_f32 v146, v30, v31
	v_cvt_pk_bf16_f32 v147, v32, v33
	s_nop 1
	v_permlane16_swap_b32 v144, v146
	v_permlane16_swap_b32 v145, v147
	global_store_dwordx4 v137, v[144:147], s[94:95]
	s_add_u32 s94, s94, 0x2000
	s_addc_u32 s95, s95, 0
	ds_read_b128 v[184:187], v136 offset:192
	ds_read_b128 v[188:191], v136 offset:4288
	s_waitcnt lgkmcnt(2)
	v_sub_f32_e32 v26, v26, v192
	v_mul_f32_e32 v26, v26, v193
	v_fma_f32 v26, v176, v26, v180
	v_sub_f32_e32 v27, v27, v192
	v_mul_f32_e32 v27, v27, v193
	v_fma_f32 v27, v177, v27, v181
	v_sub_f32_e32 v28, v28, v192
	v_mul_f32_e32 v28, v28, v193
	v_fma_f32 v28, v178, v28, v182
	v_sub_f32_e32 v29, v29, v192
	v_mul_f32_e32 v29, v29, v193
	v_fma_f32 v29, v179, v29, v183
	v_cvt_pk_bf16_f32 v152, v26, v27
	v_cvt_pk_bf16_f32 v153, v28, v29
	ds_read_b128 v[176:179], v136 offset:256
	ds_read_b128 v[180:183], v136 offset:4352
	s_waitcnt lgkmcnt(2)
	v_sub_f32_e32 v22, v22, v192
	v_mul_f32_e32 v22, v22, v193
	v_fma_f32 v22, v184, v22, v188
	v_sub_f32_e32 v23, v23, v192
	v_mul_f32_e32 v23, v23, v193
	v_fma_f32 v23, v185, v23, v189
	v_sub_f32_e32 v24, v24, v192
	v_mul_f32_e32 v24, v24, v193
	v_fma_f32 v24, v186, v24, v190
	v_sub_f32_e32 v25, v25, v192
	v_mul_f32_e32 v25, v25, v193
	v_fma_f32 v25, v187, v25, v191
	v_cvt_pk_bf16_f32 v154, v22, v23
	v_cvt_pk_bf16_f32 v155, v24, v25
	s_nop 1
	v_permlane16_swap_b32 v152, v154
	v_permlane16_swap_b32 v153, v155
	global_store_dwordx4 v137, v[152:155], s[94:95]
	s_add_u32 s94, s94, 0x2000
	s_addc_u32 s95, s95, 0
	ds_read_b128 v[184:187], v136 offset:320
	ds_read_b128 v[188:191], v136 offset:4416
	s_waitcnt lgkmcnt(2)
	v_sub_f32_e32 v18, v18, v192
	v_mul_f32_e32 v18, v18, v193
	v_fma_f32 v18, v176, v18, v180
	v_sub_f32_e32 v19, v19, v192
	v_mul_f32_e32 v19, v19, v193
	v_fma_f32 v19, v177, v19, v181
	v_sub_f32_e32 v20, v20, v192
	v_mul_f32_e32 v20, v20, v193
	v_fma_f32 v20, v178, v20, v182
	v_sub_f32_e32 v21, v21, v192
	v_mul_f32_e32 v21, v21, v193
	v_fma_f32 v21, v179, v21, v183
	v_cvt_pk_bf16_f32 v144, v18, v19
	v_cvt_pk_bf16_f32 v145, v20, v21
	ds_read_b128 v[176:179], v136 offset:384
	ds_read_b128 v[180:183], v136 offset:4480
	s_waitcnt lgkmcnt(2)
	v_sub_f32_e32 v14, v14, v192
	v_mul_f32_e32 v14, v14, v193
	v_fma_f32 v14, v184, v14, v188
	v_sub_f32_e32 v15, v15, v192
	v_mul_f32_e32 v15, v15, v193
	v_fma_f32 v15, v185, v15, v189
	v_sub_f32_e32 v16, v16, v192
	v_mul_f32_e32 v16, v16, v193
	v_fma_f32 v16, v186, v16, v190
	v_sub_f32_e32 v17, v17, v192
	v_mul_f32_e32 v17, v17, v193
	v_fma_f32 v17, v187, v17, v191
	v_cvt_pk_bf16_f32 v146, v14, v15
	v_cvt_pk_bf16_f32 v147, v16, v17
	s_nop 1
	v_permlane16_swap_b32 v144, v146
	v_permlane16_swap_b32 v145, v147
	global_store_dwordx4 v137, v[144:147], s[94:95]
	s_add_u32 s94, s94, 0x2000
	s_addc_u32 s95, s95, 0
	ds_read_b128 v[184:187], v136 offset:448
	ds_read_b128 v[188:191], v136 offset:4544
	s_waitcnt lgkmcnt(2)
	v_sub_f32_e32 v10, v10, v192
	v_mul_f32_e32 v10, v10, v193
	v_fma_f32 v10, v176, v10, v180
	v_sub_f32_e32 v11, v11, v192
	v_mul_f32_e32 v11, v11, v193
	v_fma_f32 v11, v177, v11, v181
	v_sub_f32_e32 v12, v12, v192
	v_mul_f32_e32 v12, v12, v193
	v_fma_f32 v12, v178, v12, v182
	v_sub_f32_e32 v13, v13, v192
	v_mul_f32_e32 v13, v13, v193
	v_fma_f32 v13, v179, v13, v183
	v_cvt_pk_bf16_f32 v152, v10, v11
	v_cvt_pk_bf16_f32 v153, v12, v13
	s_waitcnt lgkmcnt(0)
	v_sub_f32_e32 v6, v6, v192
	v_mul_f32_e32 v6, v6, v193
	v_fma_f32 v6, v184, v6, v188
	v_sub_f32_e32 v7, v7, v192
	v_mul_f32_e32 v7, v7, v193
	v_fma_f32 v7, v185, v7, v189
	v_sub_f32_e32 v8, v8, v192
	v_mul_f32_e32 v8, v8, v193
	v_fma_f32 v8, v186, v8, v190
	v_sub_f32_e32 v9, v9, v192
	v_mul_f32_e32 v9, v9, v193
	v_fma_f32 v9, v187, v9, v191
	v_cvt_pk_bf16_f32 v154, v6, v7
	v_cvt_pk_bf16_f32 v155, v8, v9
	s_nop 1
	v_permlane16_swap_b32 v152, v154
	v_permlane16_swap_b32 v153, v155
	global_store_dwordx4 v137, v[152:155], s[94:95]
	s_waitcnt vmcnt(8) lgkmcnt(0)
	s_barrier
; DI float bf2f(unsigned b) { return __uint_as_float(b << 16); }
; DI void unit_O(const Params& p, char* lds, int l, int tile, int glu_tiles, int tile_b) {
;     ...
;         for (int mh = 0; mh < 2; ++mh) {
;             const int mt = half * 2 + mh, rl = mh * 16 + l15;
;             float s = 0.f, ss = 0.f;
; #pragma unroll
;             for (int nt = 0; nt < 8; ++nt) {
;                 f32x4 xr;
;                 if (l == 0) {
;                     const int chunk = wid * 32 + nt * 4 + quad;
;                     xr = *(const f32x4*)(XR + rl * 4096 + ((chunk ^ l15) << 4));
;                 } else {
;                     const u32x2 hb = *(const u32x2*)(XR + ((wid * 4 + (nt >> 1)) * 32 + rl) * 64 + (nt & 1) * 32 + quad * 8);
;                     xr = (f32x4){bf2f(hb[0] & 0xffffu), bf2f(hb[0] >> 16), bf2f(hb[1] & 0xffffu), bf2f(hb[1] >> 16)};
;                 }
; #pragma unroll
;                 for (int i = 0; i < 4; ++i) { const float v = acc[mt][nt][i] + DN_ALPHA * xr[i]; acc[mt][nt][i] = v; s += v; ss += v * v; }
;             }
;             s2[mh] = s; ss2[mh] = ss;
;         }
; #pragma unroll
;         for (int mh = 0; mh < 2; ++mh) { s2[mh] += __shfl_xor(s2[mh], 16); ss2[mh] += __shfl_xor(ss2[mh], 16); }
; #pragma unroll
;         for (int mh = 0; mh < 2; ++mh) { s2[mh] += __shfl_xor(s2[mh], 32); ss2[mh] += __shfl_xor(ss2[mh], 32); }
;         if (quad == 0) {
; #pragma unroll
;             for (int mh = 0; mh < 2; ++mh) *(f32x2*)&red[((mh * 16 + l15) * 8 + wid) * 2] = (f32x2){s2[mh], ss2[mh]};
;         }
;         __syncthreads();
;         if (half == 0) issue_x(1);
; #pragma unroll
;         for (int mh = 0; mh < 2; ++mh) {
;             const int mt = half * 2 + mh, rl = mh * 16 + l15, row = mt * 16 + l15;
;             float s = 0.f, ss = 0.f;
; #pragma unroll
;             for (int w = 0; w < 4; ++w) { const f32x4 v = *(const f32x4*)&red[rl * 16 + 4 * w]; s += v[0] + v[2]; ss += v[1] + v[3]; }
;             const float mu = s * (1.f / 1024.f);
;             const float var = ss * (1.f / 1024.f) - mu * mu;
;             const float rs = rsqrtf(var + LN_EPS);
;             float* orow = xo + (r0 + row) * 1024 + wid * 128 + quad * 4;
;             bf16_t* brow = xbo + xb_off((int)r0 + row, wid * 128) + quad * 4;
;             const float* gp = GB + wid * 128 + quad * 4;
; #pragma unroll
;             for (int nt = 0; nt < 8; ++nt) {
	ds_read_b128 v[144:147], v204
	ds_read_b128 v[148:151], v205
	ds_read_b128 v[152:155], v206
	ds_read_b128 v[156:159], v207
	ds_read_b128 v[160:163], v204 offset:256
	ds_read_b128 v[164:167], v205 offset:256
	ds_read_b128 v[168:171], v206 offset:256
	ds_read_b128 v[172:175], v207 offset:256
	s_waitcnt lgkmcnt(7)
	v_fmac_f32_e32 v62, s58, v144
	v_fmac_f32_e32 v63, s58, v145
	v_fmac_f32_e32 v64, s58, v146
	v_fmac_f32_e32 v65, s58, v147
	v_mov_b32_e32 v196, v62
	v_mul_f32_e32 v197, v62, v62
	v_mov_b32_e32 v130, v63
	v_mul_f32_e32 v142, v63, v63
	v_add_f32_e32 v196, v196, v64
	v_fmac_f32_e32 v197, v64, v64
	v_add_f32_e32 v130, v130, v65
	v_fmac_f32_e32 v142, v65, v65
	s_waitcnt lgkmcnt(6)
	v_fmac_f32_e32 v58, s58, v148
	v_fmac_f32_e32 v59, s58, v149
	v_fmac_f32_e32 v60, s58, v150
	v_fmac_f32_e32 v61, s58, v151
	v_add_f32_e32 v196, v196, v58
	v_fmac_f32_e32 v197, v58, v58
	v_add_f32_e32 v130, v130, v59
	v_fmac_f32_e32 v142, v59, v59
	v_add_f32_e32 v196, v196, v60
	v_fmac_f32_e32 v197, v60, v60
	v_add_f32_e32 v130, v130, v61
	v_fmac_f32_e32 v142, v61, v61
	s_waitcnt lgkmcnt(5)
	v_fmac_f32_e32 v54, s58, v152
	v_fmac_f32_e32 v55, s58, v153
	v_fmac_f32_e32 v56, s58, v154
	v_fmac_f32_e32 v57, s58, v155
	v_add_f32_e32 v196, v196, v54
	v_fmac_f32_e32 v197, v54, v54
	v_add_f32_e32 v130, v130, v55
	v_fmac_f32_e32 v142, v55, v55
	v_add_f32_e32 v196, v196, v56
	v_fmac_f32_e32 v197, v56, v56
	v_add_f32_e32 v130, v130, v57
	v_fmac_f32_e32 v142, v57, v57
	s_waitcnt lgkmcnt(4)
	v_fmac_f32_e32 v50, s58, v156
	v_fmac_f32_e32 v51, s58, v157
	v_fmac_f32_e32 v52, s58, v158
	v_fmac_f32_e32 v53, s58, v159
	v_add_f32_e32 v196, v196, v50
	v_fmac_f32_e32 v197, v50, v50
	v_add_f32_e32 v130, v130, v51
	v_fmac_f32_e32 v142, v51, v51
	v_add_f32_e32 v196, v196, v52
	v_fmac_f32_e32 v197, v52, v52
	v_add_f32_e32 v130, v130, v53
	v_fmac_f32_e32 v142, v53, v53
	s_waitcnt lgkmcnt(3)
	v_fmac_f32_e32 v46, s58, v160
	v_fmac_f32_e32 v47, s58, v161
	v_fmac_f32_e32 v48, s58, v162
	v_fmac_f32_e32 v49, s58, v163
	v_add_f32_e32 v196, v196, v46
	v_fmac_f32_e32 v197, v46, v46
	v_add_f32_e32 v130, v130, v47
	v_fmac_f32_e32 v142, v47, v47
	v_add_f32_e32 v196, v196, v48
	v_fmac_f32_e32 v197, v48, v48
	v_add_f32_e32 v130, v130, v49
	v_fmac_f32_e32 v142, v49, v49
	s_waitcnt lgkmcnt(2)
	v_fmac_f32_e32 v42, s58, v164
	v_fmac_f32_e32 v43, s58, v165
	v_fmac_f32_e32 v44, s58, v166
	v_fmac_f32_e32 v45, s58, v167
	v_add_f32_e32 v196, v196, v42
	v_fmac_f32_e32 v197, v42, v42
	v_add_f32_e32 v130, v130, v43
	v_fmac_f32_e32 v142, v43, v43
	v_add_f32_e32 v196, v196, v44
	v_fmac_f32_e32 v197, v44, v44
	v_add_f32_e32 v130, v130, v45
	v_fmac_f32_e32 v142, v45, v45
	s_waitcnt lgkmcnt(1)
	v_fmac_f32_e32 v38, s58, v168
	v_fmac_f32_e32 v39, s58, v169
	v_fmac_f32_e32 v40, s58, v170
	v_fmac_f32_e32 v41, s58, v171
	v_add_f32_e32 v196, v196, v38
	v_fmac_f32_e32 v197, v38, v38
	v_add_f32_e32 v130, v130, v39
	v_fmac_f32_e32 v142, v39, v39
	v_add_f32_e32 v196, v196, v40
	v_fmac_f32_e32 v197, v40, v40
	v_add_f32_e32 v130, v130, v41
	v_fmac_f32_e32 v142, v41, v41
	s_waitcnt lgkmcnt(0)
	v_fmac_f32_e32 v2, s58, v172
	v_fmac_f32_e32 v3, s58, v173
	v_fmac_f32_e32 v4, s58, v174
	v_fmac_f32_e32 v5, s58, v175
	v_add_f32_e32 v196, v196, v2
	v_fmac_f32_e32 v197, v2, v2
	v_add_f32_e32 v130, v130, v3
	v_fmac_f32_e32 v142, v3, v3
	v_add_f32_e32 v196, v196, v4
	v_fmac_f32_e32 v197, v4, v4
	v_add_f32_e32 v130, v130, v5
	v_fmac_f32_e32 v142, v5, v5
	v_add_f32_e32 v196, v196, v130
	v_add_f32_e32 v197, v197, v142
	v_mov_b32_e32 v198, v196
	v_mov_b32_e32 v199, v197
	s_nop 1
	v_permlane16_swap_b32 v198, v196
	v_permlane16_swap_b32 v199, v197
	v_add_f32_e32 v196, v196, v198
	v_add_f32_e32 v197, v197, v199
	v_mov_b32_e32 v198, v196
	v_mov_b32_e32 v199, v197
	s_nop 1
	v_permlane32_swap_b32 v198, v196
	v_permlane32_swap_b32 v199, v197
	v_add_f32_e32 v196, v196, v198
	v_add_f32_e32 v197, v197, v199
	s_mov_b64 exec, 0xffff
	ds_write_b64 v134, v[196:197]
	s_mov_b64 exec, -1
	s_waitcnt lgkmcnt(0)
	s_barrier
	ds_read_b128 v[160:163], v135 offset:0
	ds_read_b128 v[164:167], v135 offset:16
	ds_read_b128 v[168:171], v135 offset:32
	ds_read_b128 v[172:175], v135 offset:48
	s_waitcnt lgkmcnt(0)
	v_add_f32_e32 v160, v160, v162
	v_add_f32_e32 v161, v161, v163
	v_add_f32_e32 v164, v164, v166
	v_add_f32_e32 v165, v165, v167
	v_add_f32_e32 v168, v168, v170
	v_add_f32_e32 v169, v169, v171
	v_add_f32_e32 v172, v172, v174
	v_add_f32_e32 v173, v173, v175
	v_add_f32_e32 v160, v160, v164
	v_add_f32_e32 v161, v161, v165
	v_add_f32_e32 v168, v168, v172
	v_add_f32_e32 v169, v169, v173
	v_add_f32_e32 v160, v160, v168
	v_add_f32_e32 v161, v161, v169
	v_mul_f32_e32 v192, 0x3a800000, v160
	v_mul_f32_e32 v193, 0x3a800000, v161
	v_fma_f32 v193, -v192, v192, v193
	v_add_f32_e32 v193, 0x3727c5ac, v193
	v_rsq_f32_e32 v193, v193
	s_nop 0
	s_add_u32 s94, s78, 0xc00
	s_addc_u32 s95, s79, 0
	ds_read_b128 v[176:179], v136
	ds_read_b128 v[180:183], v136 offset:4096
	ds_read_b128 v[184:187], v136 offset:64
	ds_read_b128 v[188:191], v136 offset:4160
	s_waitcnt lgkmcnt(2)
	v_sub_f32_e32 v62, v62, v192
	v_mul_f32_e32 v62, v62, v193
	v_fma_f32 v62, v176, v62, v180
	v_sub_f32_e32 v63, v63, v192
	v_mul_f32_e32 v63, v63, v193
	v_fma_f32 v63, v177, v63, v181
	v_sub_f32_e32 v64, v64, v192
	v_mul_f32_e32 v64, v64, v193
	v_fma_f32 v64, v178, v64, v182
	v_sub_f32_e32 v65, v65, v192
	v_mul_f32_e32 v65, v65, v193
	v_fma_f32 v65, v179, v65, v183
	v_cvt_pk_bf16_f32 v144, v62, v63
	v_cvt_pk_bf16_f32 v145, v64, v65
	ds_read_b128 v[176:179], v136 offset:128
	ds_read_b128 v[180:183], v136 offset:4224
	s_waitcnt lgkmcnt(2)
; DI unsigned pk2(float lo, float hi) { const f32x2 v = {lo, hi}; const bf16x2_t b = __builtin_convertvector(v, bf16x2_t); return __builtin_bit_cast(unsigned, b); }
; DI void unit_O(const Params& p, char* lds, int l, int tile, int glu_tiles, int tile_b) {
;     ...
;             for (int nt = 0; nt < 8; ++nt) {
;                 const f32x4 g = *(const f32x4*)(gp + nt * 16), bb = *(const f32x4*)(gp + 1024 + nt * 16);
;                 f32x4 o;
; #pragma unroll
;                 for (int i = 0; i < 4; ++i) o[i] = (acc[mt][nt][i] - mu) * rs * g[i] + bb[i];
;                 if (l == 0) *(u32x2*)(brow + (nt >> 1) * 4096 + (nt & 1) * 16) = (u32x2){pk2(o[0], o[1]), pk2(o[2], o[3])};
;                 else *(f32x4*)(orow + nt * 16) = o;
;             }
	v_sub_f32_e32 v58, v58, v192
	v_mul_f32_e32 v58, v58, v193
	v_fma_f32 v58, v184, v58, v188
	v_sub_f32_e32 v59, v59, v192
	v_mul_f32_e32 v59, v59, v193
	v_fma_f32 v59, v185, v59, v189
	v_sub_f32_e32 v60, v60, v192
	v_mul_f32_e32 v60, v60, v193
	v_fma_f32 v60, v186, v60, v190
	v_sub_f32_e32 v61, v61, v192
	v_mul_f32_e32 v61, v61, v193
	v_fma_f32 v61, v187, v61, v191
	v_cvt_pk_bf16_f32 v146, v58, v59
	v_cvt_pk_bf16_f32 v147, v60, v61
	s_nop 1
	v_permlane16_swap_b32 v144, v146
	v_permlane16_swap_b32 v145, v147
	global_store_dwordx4 v137, v[144:147], s[94:95]
	s_add_u32 s94, s94, 0x2000
	s_addc_u32 s95, s95, 0
	ds_read_b128 v[184:187], v136 offset:192
	ds_read_b128 v[188:191], v136 offset:4288
	s_waitcnt lgkmcnt(2)
	v_sub_f32_e32 v54, v54, v192
	v_mul_f32_e32 v54, v54, v193
	v_fma_f32 v54, v176, v54, v180
	v_sub_f32_e32 v55, v55, v192
	v_mul_f32_e32 v55, v55, v193
	v_fma_f32 v55, v177, v55, v181
	v_sub_f32_e32 v56, v56, v192
	v_mul_f32_e32 v56, v56, v193
	v_fma_f32 v56, v178, v56, v182
	v_sub_f32_e32 v57, v57, v192
	v_mul_f32_e32 v57, v57, v193
	v_fma_f32 v57, v179, v57, v183
	v_cvt_pk_bf16_f32 v152, v54, v55
	v_cvt_pk_bf16_f32 v153, v56, v57
	ds_read_b128 v[176:179], v136 offset:256
	ds_read_b128 v[180:183], v136 offset:4352
	s_waitcnt lgkmcnt(2)
	v_sub_f32_e32 v50, v50, v192
	v_mul_f32_e32 v50, v50, v193
	v_fma_f32 v50, v184, v50, v188
	v_sub_f32_e32 v51, v51, v192
	v_mul_f32_e32 v51, v51, v193
	v_fma_f32 v51, v185, v51, v189
	v_sub_f32_e32 v52, v52, v192
	v_mul_f32_e32 v52, v52, v193
	v_fma_f32 v52, v186, v52, v190
	v_sub_f32_e32 v53, v53, v192
	v_mul_f32_e32 v53, v53, v193
	v_fma_f32 v53, v187, v53, v191
	v_cvt_pk_bf16_f32 v154, v50, v51
	v_cvt_pk_bf16_f32 v155, v52, v53
	s_nop 1
	v_permlane16_swap_b32 v152, v154
	v_permlane16_swap_b32 v153, v155
	global_store_dwordx4 v137, v[152:155], s[94:95]
	s_add_u32 s94, s94, 0x2000
	s_addc_u32 s95, s95, 0
	ds_read_b128 v[184:187], v136 offset:320
	ds_read_b128 v[188:191], v136 offset:4416
	s_waitcnt lgkmcnt(2)
	v_sub_f32_e32 v46, v46, v192
	v_mul_f32_e32 v46, v46, v193
	v_fma_f32 v46, v176, v46, v180
	v_sub_f32_e32 v47, v47, v192
	v_mul_f32_e32 v47, v47, v193
	v_fma_f32 v47, v177, v47, v181
	v_sub_f32_e32 v48, v48, v192
	v_mul_f32_e32 v48, v48, v193
	v_fma_f32 v48, v178, v48, v182
	v_sub_f32_e32 v49, v49, v192
	v_mul_f32_e32 v49, v49, v193
	v_fma_f32 v49, v179, v49, v183
	v_cvt_pk_bf16_f32 v144, v46, v47
	v_cvt_pk_bf16_f32 v145, v48, v49
	ds_read_b128 v[176:179], v136 offset:384
	ds_read_b128 v[180:183], v136 offset:4480
	s_waitcnt lgkmcnt(2)
	v_sub_f32_e32 v42, v42, v192
	v_mul_f32_e32 v42, v42, v193
	v_fma_f32 v42, v184, v42, v188
	v_sub_f32_e32 v43, v43, v192
	v_mul_f32_e32 v43, v43, v193
	v_fma_f32 v43, v185, v43, v189
	v_sub_f32_e32 v44, v44, v192
	v_mul_f32_e32 v44, v44, v193
	v_fma_f32 v44, v186, v44, v190
	v_sub_f32_e32 v45, v45, v192
	v_mul_f32_e32 v45, v45, v193
	v_fma_f32 v45, v187, v45, v191
	v_cvt_pk_bf16_f32 v146, v42, v43
	v_cvt_pk_bf16_f32 v147, v44, v45
	s_nop 1
	v_permlane16_swap_b32 v144, v146
	v_permlane16_swap_b32 v145, v147
	global_store_dwordx4 v137, v[144:147], s[94:95]
	s_add_u32 s94, s94, 0x2000
	s_addc_u32 s95, s95, 0
	ds_read_b128 v[184:187], v136 offset:448
	ds_read_b128 v[188:191], v136 offset:4544
	s_waitcnt lgkmcnt(2)
	v_sub_f32_e32 v38, v38, v192
	v_mul_f32_e32 v38, v38, v193
	v_fma_f32 v38, v176, v38, v180
	v_sub_f32_e32 v39, v39, v192
	v_mul_f32_e32 v39, v39, v193
	v_fma_f32 v39, v177, v39, v181
	v_sub_f32_e32 v40, v40, v192
	v_mul_f32_e32 v40, v40, v193
	v_fma_f32 v40, v178, v40, v182
	v_sub_f32_e32 v41, v41, v192
	v_mul_f32_e32 v41, v41, v193
	v_fma_f32 v41, v179, v41, v183
	v_cvt_pk_bf16_f32 v152, v38, v39
	v_cvt_pk_bf16_f32 v153, v40, v41
	s_waitcnt lgkmcnt(0)
	v_sub_f32_e32 v2, v2, v192
	v_mul_f32_e32 v2, v2, v193
	v_fma_f32 v2, v184, v2, v188
	v_sub_f32_e32 v3, v3, v192
	v_mul_f32_e32 v3, v3, v193
	v_fma_f32 v3, v185, v3, v189
	v_sub_f32_e32 v4, v4, v192
	v_mul_f32_e32 v4, v4, v193
	v_fma_f32 v4, v186, v4, v190
	v_sub_f32_e32 v5, v5, v192
	v_mul_f32_e32 v5, v5, v193
	v_fma_f32 v5, v187, v5, v191
	v_cvt_pk_bf16_f32 v154, v2, v3
	v_cvt_pk_bf16_f32 v155, v4, v5
	s_nop 1
	v_permlane16_swap_b32 v152, v154
	v_permlane16_swap_b32 v153, v155
	global_store_dwordx4 v137, v[152:155], s[94:95]
	s_branch .Le2_done
; DI float bf2f(unsigned b) { return __uint_as_float(b << 16); }
; DI void unit_O(const Params& p, char* lds, int l, int tile, int glu_tiles, int tile_b) {
;     ...
;     const bf16_t* xbres = WS_PTR(const bf16_t, OFF_XB1) + ((size_t)((tile >> 1) * 32) * 128 + (tile & 1) * 64) * 32;
;     auto issue_x = [&](int half) {
;         if (l == 0) {
; #pragma unroll 1
;             for (int i = 0; i < 16; ++i) {
;                 const int pc = (wid * 16 + i + xrot) & 127, row = pc >> 2, phys = (pc & 3) * 64 + lane, logical = phys ^ (row & 15);
;                 __builtin_amdgcn_global_load_lds((const unsigned*)(xres + (r0 + half * 32 + row) * 1024 + logical * 4), (unsigned*)(XR + pc * 1024 + lane * 16), 16, 0, 0);
;             }
;         } else {
; #pragma unroll 1
;             for (int i = 0; i < 8; ++i) {
;                 const int pc = (wid * 8 + i + (xrot >> 1)) & 63, kt = pc >> 1, sub = pc & 1;
;                 __builtin_amdgcn_global_load_lds((const unsigned*)(xbres + ((size_t)kt * 128 + half * 32) * 32 + sub * 512 + lane * 8), (unsigned*)(XR + pc * 1024 + lane * 16), 16, 0, 0);
;             }
;         }
;     };
;     issue_x(0);
;     {
;         const float* gsrc = (tid < 256) ? (p.ln_g + l * 1024 + tid * 4) : (p.ln_b + l * 1024 + (tid - 256) * 4);
;         *(f32x4*)(GB + tid * 4) = *(const f32x4*)gsrc;
;     }
;     float* xo = (l == 0) ? WS_PTR(float, OFF_X1) : p.out;
;     bf16_t* xbo = WS_PTR(bf16_t, OFF_XB1);
; #pragma unroll
;     for (int half = 0; half < 2; ++half) {
;         if (half == 0) wait_vm<0>();
;         else wait_vm<8>();
;         __syncthreads();
;         float s2[2], ss2[2];
; #pragma unroll
;         for (int mh = 0; mh < 2; ++mh) {
;             const int mt = half * 2 + mh, rl = mh * 16 + l15;
;             float s = 0.f, ss = 0.f;
; #pragma unroll
;             for (int nt = 0; nt < 8; ++nt) {
;                 f32x4 xr;
;                 if (l == 0) {
;                     const int chunk = wid * 32 + nt * 4 + quad;
;                     xr = *(const f32x4*)(XR + rl * 4096 + ((chunk ^ l15) << 4));
;                 } else {
;                     const u32x2 hb = *(const u32x2*)(XR + ((wid * 4 + (nt >> 1)) * 32 + rl) * 64 + (nt & 1) * 32 + quad * 8);
;                     xr = (f32x4){bf2f(hb[0] & 0xffffu), bf2f(hb[0] >> 16), bf2f(hb[1] & 0xffffu), bf2f(hb[1] >> 16)};
;                 }
; #pragma unroll
.Le2_l1:
	s_lshr_b32 s40, s48, 1
	s_lshl_b32 s40, s40, 18
	s_and_b32 s94, s48, 1
	s_lshl_b32 s94, s94, 12
	s_add_u32 s40, s40, s94
	s_lshl_b32 s91, s90, 12
	s_lshl_b32 s94, s90, 15
	s_add_u32 s96, s56, s40
	s_addc_u32 s97, s57, 0
	s_add_u32 s96, s96, s94
	s_addc_u32 s97, s97, 0
	v_lshlrev_b32_e32 v208, 4, v141
	v_lshlrev_b32_e32 v133, 12, v140
	v_lshl_add_u32 v133, v138, 6, v133
	v_lshl_add_u32 v133, v139, 3, v133
	v_lshlrev_b32_e32 v137, 12, v138
	v_lshl_add_u32 v137, v140, 9, v137
	v_lshl_add_u32 v137, v139, 4, v137
	s_lshl_b32 s40, s48, 18
	s_add_u32 s78, s16, s40
	s_addc_u32 s79, s17, 0
	s_add_u32 s92, s96, 0x0
	s_addc_u32 s93, s97, 0
	s_add_u32 s40, s91, 0x0
	s_mov_b32 m0, s40
	s_nop 0
	global_load_lds_dwordx4 v208, s[92:93]
	s_add_u32 s92, s92, 0x2000
	s_addc_u32 s93, s93, 0
	s_add_u32 m0, m0, 0x400
	s_nop 0
	global_load_lds_dwordx4 v208, s[92:93]
	s_add_u32 s92, s92, 0x2000
	s_addc_u32 s93, s93, 0
	s_add_u32 m0, m0, 0x400
	s_nop 0
	global_load_lds_dwordx4 v208, s[92:93]
	s_add_u32 s92, s92, 0x2000
	s_addc_u32 s93, s93, 0
	s_add_u32 m0, m0, 0x400
	s_nop 0
	global_load_lds_dwordx4 v208, s[92:93]
	s_add_u32 s92, s96, 0x400
	s_addc_u32 s93, s97, 0
	s_add_u32 s40, s91, 0x8000
	s_mov_b32 m0, s40
	s_nop 0
	global_load_lds_dwordx4 v208, s[92:93]
	s_add_u32 s92, s92, 0x2000
	s_addc_u32 s93, s93, 0
	s_add_u32 m0, m0, 0x400
	s_nop 0
	global_load_lds_dwordx4 v208, s[92:93]
	s_add_u32 s92, s92, 0x2000
	s_addc_u32 s93, s93, 0
	s_add_u32 m0, m0, 0x400
	s_nop 0
	global_load_lds_dwordx4 v208, s[92:93]
	s_add_u32 s92, s92, 0x2000
	s_addc_u32 s93, s93, 0
	s_add_u32 m0, m0, 0x400
	s_nop 0
	global_load_lds_dwordx4 v208, s[92:93]
	s_waitcnt vmcnt(8)
	ds_write_b128 v143, v[176:179]
	s_waitcnt vmcnt(4) lgkmcnt(0)
	s_barrier
	ds_read_b64 v[180:181], v133 offset:0
	ds_read_b64 v[182:183], v133 offset:32
	ds_read_b64 v[184:185], v133 offset:1024
	ds_read_b64 v[186:187], v133 offset:1056
	ds_read_b64 v[188:189], v133 offset:2048
	ds_read_b64 v[190:191], v133 offset:2080
	ds_read_b64 v[192:193], v133 offset:3072
	ds_read_b64 v[194:195], v133 offset:3104
	s_waitcnt lgkmcnt(7)
	v_lshlrev_b32_e32 v144, 16, v180
	v_and_b32_e32 v145, 0xffff0000, v180
	v_lshlrev_b32_e32 v146, 16, v181
	v_and_b32_e32 v147, 0xffff0000, v181
	v_fmac_f32_e32 v98, s58, v144
	v_fmac_f32_e32 v99, s58, v145
	v_fmac_f32_e32 v100, s58, v146
	v_fmac_f32_e32 v101, s58, v147
	v_mov_b32_e32 v196, v98
	v_mul_f32_e32 v197, v98, v98
	v_mov_b32_e32 v130, v99
	v_mul_f32_e32 v142, v99, v99
	v_add_f32_e32 v196, v196, v100
	v_fmac_f32_e32 v197, v100, v100
	v_add_f32_e32 v130, v130, v101
	v_fmac_f32_e32 v142, v101, v101
	s_waitcnt lgkmcnt(6)
	v_lshlrev_b32_e32 v148, 16, v182
	v_and_b32_e32 v149, 0xffff0000, v182
	v_lshlrev_b32_e32 v150, 16, v183
	v_and_b32_e32 v151, 0xffff0000, v183
	v_fmac_f32_e32 v94, s58, v148
	v_fmac_f32_e32 v95, s58, v149
	v_fmac_f32_e32 v96, s58, v150
	v_fmac_f32_e32 v97, s58, v151
	v_add_f32_e32 v196, v196, v94
	v_fmac_f32_e32 v197, v94, v94
	v_add_f32_e32 v130, v130, v95
	v_fmac_f32_e32 v142, v95, v95
	v_add_f32_e32 v196, v196, v96
	v_fmac_f32_e32 v197, v96, v96
	v_add_f32_e32 v130, v130, v97
	v_fmac_f32_e32 v142, v97, v97
	s_waitcnt lgkmcnt(5)
	v_lshlrev_b32_e32 v152, 16, v184
	v_and_b32_e32 v153, 0xffff0000, v184
	v_lshlrev_b32_e32 v154, 16, v185
	v_and_b32_e32 v155, 0xffff0000, v185
	v_fmac_f32_e32 v90, s58, v152
	v_fmac_f32_e32 v91, s58, v153
	v_fmac_f32_e32 v92, s58, v154
	v_fmac_f32_e32 v93, s58, v155
	v_add_f32_e32 v196, v196, v90
	v_fmac_f32_e32 v197, v90, v90
	v_add_f32_e32 v130, v130, v91
	v_fmac_f32_e32 v142, v91, v91
	v_add_f32_e32 v196, v196, v92
	v_fmac_f32_e32 v197, v92, v92
	v_add_f32_e32 v130, v130, v93
	v_fmac_f32_e32 v142, v93, v93
	s_waitcnt lgkmcnt(4)
	v_lshlrev_b32_e32 v156, 16, v186
	v_and_b32_e32 v157, 0xffff0000, v186
	v_lshlrev_b32_e32 v158, 16, v187
	v_and_b32_e32 v159, 0xffff0000, v187
	v_fmac_f32_e32 v86, s58, v156
	v_fmac_f32_e32 v87, s58, v157
	v_fmac_f32_e32 v88, s58, v158
	v_fmac_f32_e32 v89, s58, v159
	v_add_f32_e32 v196, v196, v86
	v_fmac_f32_e32 v197, v86, v86
	v_add_f32_e32 v130, v130, v87
	v_fmac_f32_e32 v142, v87, v87
	v_add_f32_e32 v196, v196, v88
	v_fmac_f32_e32 v197, v88, v88
	v_add_f32_e32 v130, v130, v89
	v_fmac_f32_e32 v142, v89, v89
	s_waitcnt lgkmcnt(3)
	v_lshlrev_b32_e32 v160, 16, v188
	v_and_b32_e32 v161, 0xffff0000, v188
	v_lshlrev_b32_e32 v162, 16, v189
	v_and_b32_e32 v163, 0xffff0000, v189
	v_fmac_f32_e32 v82, s58, v160
	v_fmac_f32_e32 v83, s58, v161
	v_fmac_f32_e32 v84, s58, v162
	v_fmac_f32_e32 v85, s58, v163
	v_add_f32_e32 v196, v196, v82
	v_fmac_f32_e32 v197, v82, v82
	v_add_f32_e32 v130, v130, v83
	v_fmac_f32_e32 v142, v83, v83
	v_add_f32_e32 v196, v196, v84
	v_fmac_f32_e32 v197, v84, v84
	v_add_f32_e32 v130, v130, v85
	v_fmac_f32_e32 v142, v85, v85
	s_waitcnt lgkmcnt(2)
	v_lshlrev_b32_e32 v164, 16, v190
	v_and_b32_e32 v165, 0xffff0000, v190
	v_lshlrev_b32_e32 v166, 16, v191
	v_and_b32_e32 v167, 0xffff0000, v191
	v_fmac_f32_e32 v78, s58, v164
	v_fmac_f32_e32 v79, s58, v165
	v_fmac_f32_e32 v80, s58, v166
	v_fmac_f32_e32 v81, s58, v167
	v_add_f32_e32 v196, v196, v78
	v_fmac_f32_e32 v197, v78, v78
	v_add_f32_e32 v130, v130, v79
	v_fmac_f32_e32 v142, v79, v79
	v_add_f32_e32 v196, v196, v80
	v_fmac_f32_e32 v197, v80, v80
	v_add_f32_e32 v130, v130, v81
	v_fmac_f32_e32 v142, v81, v81
	s_waitcnt lgkmcnt(1)
	v_lshlrev_b32_e32 v168, 16, v192
	v_and_b32_e32 v169, 0xffff0000, v192
	v_lshlrev_b32_e32 v170, 16, v193
	v_and_b32_e32 v171, 0xffff0000, v193
	v_fmac_f32_e32 v74, s58, v168
	v_fmac_f32_e32 v75, s58, v169
	v_fmac_f32_e32 v76, s58, v170
	v_fmac_f32_e32 v77, s58, v171
	v_add_f32_e32 v196, v196, v74
	v_fmac_f32_e32 v197, v74, v74
	v_add_f32_e32 v130, v130, v75
	v_fmac_f32_e32 v142, v75, v75
	v_add_f32_e32 v196, v196, v76
	v_fmac_f32_e32 v197, v76, v76
	v_add_f32_e32 v130, v130, v77
	v_fmac_f32_e32 v142, v77, v77
	s_waitcnt lgkmcnt(0)
	v_lshlrev_b32_e32 v172, 16, v194
	v_and_b32_e32 v173, 0xffff0000, v194
	v_lshlrev_b32_e32 v174, 16, v195
	v_and_b32_e32 v175, 0xffff0000, v195
	v_fmac_f32_e32 v70, s58, v172
	v_fmac_f32_e32 v71, s58, v173
	v_fmac_f32_e32 v72, s58, v174
	v_fmac_f32_e32 v73, s58, v175
	v_add_f32_e32 v196, v196, v70
	v_fmac_f32_e32 v197, v70, v70
	v_add_f32_e32 v130, v130, v71
	v_fmac_f32_e32 v142, v71, v71
	v_add_f32_e32 v196, v196, v72
	v_fmac_f32_e32 v197, v72, v72
	v_add_f32_e32 v130, v130, v73
	v_fmac_f32_e32 v142, v73, v73
	v_add_f32_e32 v196, v196, v130
	v_add_f32_e32 v197, v197, v142
	v_mov_b32_e32 v198, v196
	v_mov_b32_e32 v199, v197
	s_nop 1
	v_permlane16_swap_b32 v198, v196
	v_permlane16_swap_b32 v199, v197
	v_add_f32_e32 v196, v196, v198
	v_add_f32_e32 v197, v197, v199
	v_mov_b32_e32 v198, v196
	v_mov_b32_e32 v199, v197
	s_nop 1
	v_permlane32_swap_b32 v198, v196
	v_permlane32_swap_b32 v199, v197
	v_add_f32_e32 v196, v196, v198
	v_add_f32_e32 v197, v197, v199
	s_mov_b64 exec, 0xffff
	ds_write_b64 v134, v[196:197]
	s_mov_b64 exec, -1
	s_waitcnt lgkmcnt(0)
	s_barrier
; DI unsigned pk2(float lo, float hi) { const f32x2 v = {lo, hi}; const bf16x2_t b = __builtin_convertvector(v, bf16x2_t); return __builtin_bit_cast(unsigned, b); }
; DI size_t xb_off(int tok, int col) { return ((size_t)(((tok >> 7) * 32 + (col >> 5)) * 128 + (tok & 127))) * 32 + (col & 31); }
; DI void unit_O(const Params& p, char* lds, int l, int tile, int glu_tiles, int tile_b) {
;     ...
; #pragma unroll 1
;             for (int i = 0; i < 8; ++i) {
;                 const int pc = (wid * 8 + i + (xrot >> 1)) & 63, kt = pc >> 1, sub = pc & 1;
;                 __builtin_amdgcn_global_load_lds((const unsigned*)(xbres + ((size_t)kt * 128 + half * 32) * 32 + sub * 512 + lane * 8), (unsigned*)(XR + pc * 1024 + lane * 16), 16, 0, 0);
;             }
;     ...
;         if (half == 0) issue_x(1);
; #pragma unroll
;         for (int mh = 0; mh < 2; ++mh) {
;             const int mt = half * 2 + mh, rl = mh * 16 + l15, row = mt * 16 + l15;
;             float s = 0.f, ss = 0.f;
; #pragma unroll
;             for (int w = 0; w < 4; ++w) { const f32x4 v = *(const f32x4*)&red[rl * 16 + 4 * w]; s += v[0] + v[2]; ss += v[1] + v[3]; }
;             const float mu = s * (1.f / 1024.f);
;             const float var = ss * (1.f / 1024.f) - mu * mu;
;             const float rs = rsqrtf(var + LN_EPS);
;             float* orow = xo + (r0 + row) * 1024 + wid * 128 + quad * 4;
;             bf16_t* brow = xbo + xb_off((int)r0 + row, wid * 128) + quad * 4;
;             const float* gp = GB + wid * 128 + quad * 4;
; #pragma unroll
;             for (int nt = 0; nt < 8; ++nt) {
;                 const f32x4 g = *(const f32x4*)(gp + nt * 16), bb = *(const f32x4*)(gp + 1024 + nt * 16);
;                 f32x4 o;
; #pragma unroll
;                 for (int i = 0; i < 4; ++i) o[i] = (acc[mt][nt][i] - mu) * rs * g[i] + bb[i];
;                 if (l == 0) *(u32x2*)(brow + (nt >> 1) * 4096 + (nt & 1) * 16) = (u32x2){pk2(o[0], o[1]), pk2(o[2], o[3])};
;                 else *(f32x4*)(orow + nt * 16) = o;
;             }
;         }
	s_add_u32 s92, s96, 0x800
	s_addc_u32 s93, s97, 0
	s_add_u32 s40, s91, 0x0
	s_mov_b32 m0, s40
	s_nop 0
	global_load_lds_dwordx4 v208, s[92:93]
	s_add_u32 s92, s92, 0x2000
	s_addc_u32 s93, s93, 0
	s_add_u32 m0, m0, 0x400
	s_nop 0
	global_load_lds_dwordx4 v208, s[92:93]
	s_add_u32 s92, s92, 0x2000
	s_addc_u32 s93, s93, 0
	s_add_u32 m0, m0, 0x400
	s_nop 0
	global_load_lds_dwordx4 v208, s[92:93]
	s_add_u32 s92, s92, 0x2000
	s_addc_u32 s93, s93, 0
	s_add_u32 m0, m0, 0x400
	s_nop 0
	global_load_lds_dwordx4 v208, s[92:93]
	ds_read_b128 v[160:163], v135 offset:0
	ds_read_b128 v[164:167], v135 offset:16
	ds_read_b128 v[168:171], v135 offset:32
	ds_read_b128 v[172:175], v135 offset:48
	s_waitcnt lgkmcnt(0)
	v_add_f32_e32 v160, v160, v162
	v_add_f32_e32 v161, v161, v163
	v_add_f32_e32 v164, v164, v166
	v_add_f32_e32 v165, v165, v167
	v_add_f32_e32 v168, v168, v170
	v_add_f32_e32 v169, v169, v171
	v_add_f32_e32 v172, v172, v174
	v_add_f32_e32 v173, v173, v175
	v_add_f32_e32 v160, v160, v164
	v_add_f32_e32 v161, v161, v165
	v_add_f32_e32 v168, v168, v172
	v_add_f32_e32 v169, v169, v173
	v_add_f32_e32 v160, v160, v168
	v_add_f32_e32 v161, v161, v169
	v_mul_f32_e32 v192, 0x3a800000, v160
	v_mul_f32_e32 v193, 0x3a800000, v161
	v_fma_f32 v193, -v192, v192, v193
	v_add_f32_e32 v193, 0x3727c5ac, v193
	v_rsq_f32_e32 v193, v193
	s_nop 0
	s_add_u32 s94, s78, 0x0
	s_addc_u32 s95, s79, 0
	ds_read_b128 v[176:179], v136
	ds_read_b128 v[180:183], v136 offset:4096
	ds_read_b128 v[184:187], v136 offset:64
	ds_read_b128 v[188:191], v136 offset:4160
	s_waitcnt lgkmcnt(2)
	v_sub_f32_e32 v98, v98, v192
	v_mul_f32_e32 v98, v98, v193
	v_fma_f32 v98, v176, v98, v180
	v_sub_f32_e32 v99, v99, v192
	v_mul_f32_e32 v99, v99, v193
	v_fma_f32 v99, v177, v99, v181
	v_sub_f32_e32 v100, v100, v192
	v_mul_f32_e32 v100, v100, v193
	v_fma_f32 v100, v178, v100, v182
	v_sub_f32_e32 v101, v101, v192
	v_mul_f32_e32 v101, v101, v193
	v_fma_f32 v101, v179, v101, v183
	global_store_dwordx4 v137, v[98:101], s[94:95]
	ds_read_b128 v[176:179], v136 offset:128
	ds_read_b128 v[180:183], v136 offset:4224
	s_waitcnt lgkmcnt(2)
	v_sub_f32_e32 v94, v94, v192
	v_mul_f32_e32 v94, v94, v193
	v_fma_f32 v94, v184, v94, v188
	v_sub_f32_e32 v95, v95, v192
	v_mul_f32_e32 v95, v95, v193
	v_fma_f32 v95, v185, v95, v189
	v_sub_f32_e32 v96, v96, v192
	v_mul_f32_e32 v96, v96, v193
	v_fma_f32 v96, v186, v96, v190
	v_sub_f32_e32 v97, v97, v192
	v_mul_f32_e32 v97, v97, v193
	v_fma_f32 v97, v187, v97, v191
	global_store_dwordx4 v137, v[94:97], s[94:95] offset:64
	ds_read_b128 v[184:187], v136 offset:192
	ds_read_b128 v[188:191], v136 offset:4288
	s_waitcnt lgkmcnt(2)
	v_sub_f32_e32 v90, v90, v192
	v_mul_f32_e32 v90, v90, v193
	v_fma_f32 v90, v176, v90, v180
	v_sub_f32_e32 v91, v91, v192
	v_mul_f32_e32 v91, v91, v193
	v_fma_f32 v91, v177, v91, v181
	v_sub_f32_e32 v92, v92, v192
	v_mul_f32_e32 v92, v92, v193
	v_fma_f32 v92, v178, v92, v182
	v_sub_f32_e32 v93, v93, v192
	v_mul_f32_e32 v93, v93, v193
	v_fma_f32 v93, v179, v93, v183
	global_store_dwordx4 v137, v[90:93], s[94:95] offset:128
	ds_read_b128 v[176:179], v136 offset:256
	ds_read_b128 v[180:183], v136 offset:4352
	s_waitcnt lgkmcnt(2)
	v_sub_f32_e32 v86, v86, v192
	v_mul_f32_e32 v86, v86, v193
	v_fma_f32 v86, v184, v86, v188
	v_sub_f32_e32 v87, v87, v192
	v_mul_f32_e32 v87, v87, v193
	v_fma_f32 v87, v185, v87, v189
	v_sub_f32_e32 v88, v88, v192
	v_mul_f32_e32 v88, v88, v193
	v_fma_f32 v88, v186, v88, v190
	v_sub_f32_e32 v89, v89, v192
	v_mul_f32_e32 v89, v89, v193
	v_fma_f32 v89, v187, v89, v191
	global_store_dwordx4 v137, v[86:89], s[94:95] offset:192
	ds_read_b128 v[184:187], v136 offset:320
	ds_read_b128 v[188:191], v136 offset:4416
	s_waitcnt lgkmcnt(2)
	v_sub_f32_e32 v82, v82, v192
	v_mul_f32_e32 v82, v82, v193
	v_fma_f32 v82, v176, v82, v180
	v_sub_f32_e32 v83, v83, v192
	v_mul_f32_e32 v83, v83, v193
	v_fma_f32 v83, v177, v83, v181
	v_sub_f32_e32 v84, v84, v192
	v_mul_f32_e32 v84, v84, v193
	v_fma_f32 v84, v178, v84, v182
	v_sub_f32_e32 v85, v85, v192
	v_mul_f32_e32 v85, v85, v193
	v_fma_f32 v85, v179, v85, v183
	global_store_dwordx4 v137, v[82:85], s[94:95] offset:256
	ds_read_b128 v[176:179], v136 offset:384
	ds_read_b128 v[180:183], v136 offset:4480
	s_waitcnt lgkmcnt(2)
	v_sub_f32_e32 v78, v78, v192
	v_mul_f32_e32 v78, v78, v193
	v_fma_f32 v78, v184, v78, v188
	v_sub_f32_e32 v79, v79, v192
	v_mul_f32_e32 v79, v79, v193
	v_fma_f32 v79, v185, v79, v189
	v_sub_f32_e32 v80, v80, v192
	v_mul_f32_e32 v80, v80, v193
	v_fma_f32 v80, v186, v80, v190
	v_sub_f32_e32 v81, v81, v192
	v_mul_f32_e32 v81, v81, v193
	v_fma_f32 v81, v187, v81, v191
	global_store_dwordx4 v137, v[78:81], s[94:95] offset:320
	ds_read_b128 v[184:187], v136 offset:448
	ds_read_b128 v[188:191], v136 offset:4544
	s_waitcnt lgkmcnt(2)
	v_sub_f32_e32 v74, v74, v192
	v_mul_f32_e32 v74, v74, v193
	v_fma_f32 v74, v176, v74, v180
	v_sub_f32_e32 v75, v75, v192
	v_mul_f32_e32 v75, v75, v193
	v_fma_f32 v75, v177, v75, v181
	v_sub_f32_e32 v76, v76, v192
	v_mul_f32_e32 v76, v76, v193
	v_fma_f32 v76, v178, v76, v182
	v_sub_f32_e32 v77, v77, v192
	v_mul_f32_e32 v77, v77, v193
	v_fma_f32 v77, v179, v77, v183
	global_store_dwordx4 v137, v[74:77], s[94:95] offset:384
	s_waitcnt lgkmcnt(0)
	v_sub_f32_e32 v70, v70, v192
	v_mul_f32_e32 v70, v70, v193
	v_fma_f32 v70, v184, v70, v188
	v_sub_f32_e32 v71, v71, v192
	v_mul_f32_e32 v71, v71, v193
	v_fma_f32 v71, v185, v71, v189
	v_sub_f32_e32 v72, v72, v192
	v_mul_f32_e32 v72, v72, v193
	v_fma_f32 v72, v186, v72, v190
	v_sub_f32_e32 v73, v73, v192
	v_mul_f32_e32 v73, v73, v193
	v_fma_f32 v73, v187, v73, v191
	global_store_dwordx4 v137, v[70:73], s[94:95] offset:448
	s_waitcnt vmcnt(12) lgkmcnt(0)
	s_barrier
; DI float bf2f(unsigned b) { return __uint_as_float(b << 16); }
; DI void unit_O(const Params& p, char* lds, int l, int tile, int glu_tiles, int tile_b) {
;     ...
;         for (int mh = 0; mh < 2; ++mh) {
;             const int mt = half * 2 + mh, rl = mh * 16 + l15;
;             float s = 0.f, ss = 0.f;
; #pragma unroll
;             for (int nt = 0; nt < 8; ++nt) {
;                 f32x4 xr;
;                 if (l == 0) {
;                     const int chunk = wid * 32 + nt * 4 + quad;
;                     xr = *(const f32x4*)(XR + rl * 4096 + ((chunk ^ l15) << 4));
;                 } else {
;                     const u32x2 hb = *(const u32x2*)(XR + ((wid * 4 + (nt >> 1)) * 32 + rl) * 64 + (nt & 1) * 32 + quad * 8);
;                     xr = (f32x4){bf2f(hb[0] & 0xffffu), bf2f(hb[0] >> 16), bf2f(hb[1] & 0xffffu), bf2f(hb[1] >> 16)};
;                 }
; #pragma unroll
;                 for (int i = 0; i < 4; ++i) { const float v = acc[mt][nt][i] + DN_ALPHA * xr[i]; acc[mt][nt][i] = v; s += v; ss += v * v; }
;             }
;             s2[mh] = s; ss2[mh] = ss;
;         }
; #pragma unroll
;         for (int mh = 0; mh < 2; ++mh) { s2[mh] += __shfl_xor(s2[mh], 16); ss2[mh] += __shfl_xor(ss2[mh], 16); }
; #pragma unroll
;         for (int mh = 0; mh < 2; ++mh) { s2[mh] += __shfl_xor(s2[mh], 32); ss2[mh] += __shfl_xor(ss2[mh], 32); }
;         if (quad == 0) {
; #pragma unroll
;             for (int mh = 0; mh < 2; ++mh) *(f32x2*)&red[((mh * 16 + l15) * 8 + wid) * 2] = (f32x2){s2[mh], ss2[mh]};
;         }
;         __syncthreads();
	ds_read_b64 v[180:181], v133 offset:32768
	ds_read_b64 v[182:183], v133 offset:32800
	ds_read_b64 v[184:185], v133 offset:33792
	ds_read_b64 v[186:187], v133 offset:33824
	ds_read_b64 v[188:189], v133 offset:34816
	ds_read_b64 v[190:191], v133 offset:34848
	ds_read_b64 v[192:193], v133 offset:35840
	ds_read_b64 v[194:195], v133 offset:35872
	s_waitcnt lgkmcnt(7)
	v_lshlrev_b32_e32 v144, 16, v180
	v_and_b32_e32 v145, 0xffff0000, v180
	v_lshlrev_b32_e32 v146, 16, v181
	v_and_b32_e32 v147, 0xffff0000, v181
	v_fmac_f32_e32 v126, s58, v144
	v_fmac_f32_e32 v127, s58, v145
	v_fmac_f32_e32 v128, s58, v146
	v_fmac_f32_e32 v129, s58, v147
	v_mov_b32_e32 v196, v126
	v_mul_f32_e32 v197, v126, v126
	v_mov_b32_e32 v130, v127
	v_mul_f32_e32 v142, v127, v127
	v_add_f32_e32 v196, v196, v128
	v_fmac_f32_e32 v197, v128, v128
	v_add_f32_e32 v130, v130, v129
	v_fmac_f32_e32 v142, v129, v129
	s_waitcnt lgkmcnt(6)
	v_lshlrev_b32_e32 v148, 16, v182
	v_and_b32_e32 v149, 0xffff0000, v182
	v_lshlrev_b32_e32 v150, 16, v183
	v_and_b32_e32 v151, 0xffff0000, v183
	v_fmac_f32_e32 v122, s58, v148
	v_fmac_f32_e32 v123, s58, v149
	v_fmac_f32_e32 v124, s58, v150
	v_fmac_f32_e32 v125, s58, v151
	v_add_f32_e32 v196, v196, v122
	v_fmac_f32_e32 v197, v122, v122
	v_add_f32_e32 v130, v130, v123
	v_fmac_f32_e32 v142, v123, v123
	v_add_f32_e32 v196, v196, v124
	v_fmac_f32_e32 v197, v124, v124
	v_add_f32_e32 v130, v130, v125
	v_fmac_f32_e32 v142, v125, v125
	s_waitcnt lgkmcnt(5)
	v_lshlrev_b32_e32 v152, 16, v184
	v_and_b32_e32 v153, 0xffff0000, v184
	v_lshlrev_b32_e32 v154, 16, v185
	v_and_b32_e32 v155, 0xffff0000, v185
	v_fmac_f32_e32 v118, s58, v152
	v_fmac_f32_e32 v119, s58, v153
	v_fmac_f32_e32 v120, s58, v154
	v_fmac_f32_e32 v121, s58, v155
	v_add_f32_e32 v196, v196, v118
	v_fmac_f32_e32 v197, v118, v118
	v_add_f32_e32 v130, v130, v119
	v_fmac_f32_e32 v142, v119, v119
	v_add_f32_e32 v196, v196, v120
	v_fmac_f32_e32 v197, v120, v120
	v_add_f32_e32 v130, v130, v121
	v_fmac_f32_e32 v142, v121, v121
	s_waitcnt lgkmcnt(4)
	v_lshlrev_b32_e32 v156, 16, v186
	v_and_b32_e32 v157, 0xffff0000, v186
	v_lshlrev_b32_e32 v158, 16, v187
	v_and_b32_e32 v159, 0xffff0000, v187
	v_fmac_f32_e32 v114, s58, v156
	v_fmac_f32_e32 v115, s58, v157
	v_fmac_f32_e32 v116, s58, v158
	v_fmac_f32_e32 v117, s58, v159
	v_add_f32_e32 v196, v196, v114
	v_fmac_f32_e32 v197, v114, v114
	v_add_f32_e32 v130, v130, v115
	v_fmac_f32_e32 v142, v115, v115
	v_add_f32_e32 v196, v196, v116
	v_fmac_f32_e32 v197, v116, v116
	v_add_f32_e32 v130, v130, v117
	v_fmac_f32_e32 v142, v117, v117
	s_waitcnt lgkmcnt(3)
	v_lshlrev_b32_e32 v160, 16, v188
	v_and_b32_e32 v161, 0xffff0000, v188
	v_lshlrev_b32_e32 v162, 16, v189
	v_and_b32_e32 v163, 0xffff0000, v189
	v_fmac_f32_e32 v110, s58, v160
	v_fmac_f32_e32 v111, s58, v161
	v_fmac_f32_e32 v112, s58, v162
	v_fmac_f32_e32 v113, s58, v163
	v_add_f32_e32 v196, v196, v110
	v_fmac_f32_e32 v197, v110, v110
	v_add_f32_e32 v130, v130, v111
	v_fmac_f32_e32 v142, v111, v111
	v_add_f32_e32 v196, v196, v112
	v_fmac_f32_e32 v197, v112, v112
	v_add_f32_e32 v130, v130, v113
	v_fmac_f32_e32 v142, v113, v113
	s_waitcnt lgkmcnt(2)
	v_lshlrev_b32_e32 v164, 16, v190
	v_and_b32_e32 v165, 0xffff0000, v190
	v_lshlrev_b32_e32 v166, 16, v191
	v_and_b32_e32 v167, 0xffff0000, v191
	v_fmac_f32_e32 v106, s58, v164
	v_fmac_f32_e32 v107, s58, v165
	v_fmac_f32_e32 v108, s58, v166
	v_fmac_f32_e32 v109, s58, v167
	v_add_f32_e32 v196, v196, v106
	v_fmac_f32_e32 v197, v106, v106
	v_add_f32_e32 v130, v130, v107
	v_fmac_f32_e32 v142, v107, v107
	v_add_f32_e32 v196, v196, v108
	v_fmac_f32_e32 v197, v108, v108
	v_add_f32_e32 v130, v130, v109
	v_fmac_f32_e32 v142, v109, v109
	s_waitcnt lgkmcnt(1)
	v_lshlrev_b32_e32 v168, 16, v192
	v_and_b32_e32 v169, 0xffff0000, v192
	v_lshlrev_b32_e32 v170, 16, v193
	v_and_b32_e32 v171, 0xffff0000, v193
	v_fmac_f32_e32 v102, s58, v168
	v_fmac_f32_e32 v103, s58, v169
	v_fmac_f32_e32 v104, s58, v170
	v_fmac_f32_e32 v105, s58, v171
	v_add_f32_e32 v196, v196, v102
	v_fmac_f32_e32 v197, v102, v102
	v_add_f32_e32 v130, v130, v103
	v_fmac_f32_e32 v142, v103, v103
	v_add_f32_e32 v196, v196, v104
	v_fmac_f32_e32 v197, v104, v104
	v_add_f32_e32 v130, v130, v105
	v_fmac_f32_e32 v142, v105, v105
	s_waitcnt lgkmcnt(0)
	v_lshlrev_b32_e32 v172, 16, v194
	v_and_b32_e32 v173, 0xffff0000, v194
	v_lshlrev_b32_e32 v174, 16, v195
	v_and_b32_e32 v175, 0xffff0000, v195
	v_fmac_f32_e32 v66, s58, v172
	v_fmac_f32_e32 v67, s58, v173
	v_fmac_f32_e32 v68, s58, v174
	v_fmac_f32_e32 v69, s58, v175
	v_add_f32_e32 v196, v196, v66
	v_fmac_f32_e32 v197, v66, v66
	v_add_f32_e32 v130, v130, v67
	v_fmac_f32_e32 v142, v67, v67
	v_add_f32_e32 v196, v196, v68
	v_fmac_f32_e32 v197, v68, v68
	v_add_f32_e32 v130, v130, v69
	v_fmac_f32_e32 v142, v69, v69
	v_add_f32_e32 v196, v196, v130
	v_add_f32_e32 v197, v197, v142
	v_mov_b32_e32 v198, v196
	v_mov_b32_e32 v199, v197
	s_nop 1
	v_permlane16_swap_b32 v198, v196
	v_permlane16_swap_b32 v199, v197
	v_add_f32_e32 v196, v196, v198
	v_add_f32_e32 v197, v197, v199
	v_mov_b32_e32 v198, v196
	v_mov_b32_e32 v199, v197
	s_nop 1
	v_permlane32_swap_b32 v198, v196
	v_permlane32_swap_b32 v199, v197
	v_add_f32_e32 v196, v196, v198
	v_add_f32_e32 v197, v197, v199
	s_mov_b64 exec, 0xffff
	ds_write_b64 v134, v[196:197]
	s_mov_b64 exec, -1
	s_waitcnt lgkmcnt(0)
	s_barrier
; DI unsigned pk2(float lo, float hi) { const f32x2 v = {lo, hi}; const bf16x2_t b = __builtin_convertvector(v, bf16x2_t); return __builtin_bit_cast(unsigned, b); }
; DI size_t xb_off(int tok, int col) { return ((size_t)(((tok >> 7) * 32 + (col >> 5)) * 128 + (tok & 127))) * 32 + (col & 31); }
; DI void unit_O(const Params& p, char* lds, int l, int tile, int glu_tiles, int tile_b) {
;     ...
; #pragma unroll 1
;             for (int i = 0; i < 8; ++i) {
;                 const int pc = (wid * 8 + i + (xrot >> 1)) & 63, kt = pc >> 1, sub = pc & 1;
;                 __builtin_amdgcn_global_load_lds((const unsigned*)(xbres + ((size_t)kt * 128 + half * 32) * 32 + sub * 512 + lane * 8), (unsigned*)(XR + pc * 1024 + lane * 16), 16, 0, 0);
;             }
;     ...
;         if (half == 0) issue_x(1);
; #pragma unroll
;         for (int mh = 0; mh < 2; ++mh) {
;             const int mt = half * 2 + mh, rl = mh * 16 + l15, row = mt * 16 + l15;
;             float s = 0.f, ss = 0.f;
; #pragma unroll
;             for (int w = 0; w < 4; ++w) { const f32x4 v = *(const f32x4*)&red[rl * 16 + 4 * w]; s += v[0] + v[2]; ss += v[1] + v[3]; }
;             const float mu = s * (1.f / 1024.f);
;             const float var = ss * (1.f / 1024.f) - mu * mu;
;             const float rs = rsqrtf(var + LN_EPS);
;             float* orow = xo + (r0 + row) * 1024 + wid * 128 + quad * 4;
;             bf16_t* brow = xbo + xb_off((int)r0 + row, wid * 128) + quad * 4;
;             const float* gp = GB + wid * 128 + quad * 4;
; #pragma unroll
;             for (int nt = 0; nt < 8; ++nt) {
;                 const f32x4 g = *(const f32x4*)(gp + nt * 16), bb = *(const f32x4*)(gp + 1024 + nt * 16);
;                 f32x4 o;
; #pragma unroll
;                 for (int i = 0; i < 4; ++i) o[i] = (acc[mt][nt][i] - mu) * rs * g[i] + bb[i];
;                 if (l == 0) *(u32x2*)(brow + (nt >> 1) * 4096 + (nt & 1) * 16) = (u32x2){pk2(o[0], o[1]), pk2(o[2], o[3])};
;                 else *(f32x4*)(orow + nt * 16) = o;
;             }
;         }
	s_add_u32 s92, s96, 0xc00
	s_addc_u32 s93, s97, 0
	s_add_u32 s40, s91, 0x8000
	s_mov_b32 m0, s40
	s_nop 0
	global_load_lds_dwordx4 v208, s[92:93]
	s_add_u32 s92, s92, 0x2000
	s_addc_u32 s93, s93, 0
	s_add_u32 m0, m0, 0x400
	s_nop 0
	global_load_lds_dwordx4 v208, s[92:93]
	s_add_u32 s92, s92, 0x2000
	s_addc_u32 s93, s93, 0
	s_add_u32 m0, m0, 0x400
	s_nop 0
	global_load_lds_dwordx4 v208, s[92:93]
	s_add_u32 s92, s92, 0x2000
	s_addc_u32 s93, s93, 0
	s_add_u32 m0, m0, 0x400
	s_nop 0
	global_load_lds_dwordx4 v208, s[92:93]
	ds_read_b128 v[160:163], v135 offset:0
	ds_read_b128 v[164:167], v135 offset:16
	ds_read_b128 v[168:171], v135 offset:32
	ds_read_b128 v[172:175], v135 offset:48
	s_waitcnt lgkmcnt(0)
	v_add_f32_e32 v160, v160, v162
	v_add_f32_e32 v161, v161, v163
	v_add_f32_e32 v164, v164, v166
	v_add_f32_e32 v165, v165, v167
	v_add_f32_e32 v168, v168, v170
	v_add_f32_e32 v169, v169, v171
	v_add_f32_e32 v172, v172, v174
	v_add_f32_e32 v173, v173, v175
	v_add_f32_e32 v160, v160, v164
	v_add_f32_e32 v161, v161, v165
	v_add_f32_e32 v168, v168, v172
	v_add_f32_e32 v169, v169, v173
	v_add_f32_e32 v160, v160, v168
	v_add_f32_e32 v161, v161, v169
	v_mul_f32_e32 v192, 0x3a800000, v160
	v_mul_f32_e32 v193, 0x3a800000, v161
	v_fma_f32 v193, -v192, v192, v193
	v_add_f32_e32 v193, 0x3727c5ac, v193
	v_rsq_f32_e32 v193, v193
	s_nop 0
	s_add_u32 s94, s78, 0x10000
	s_addc_u32 s95, s79, 0
	ds_read_b128 v[176:179], v136
	ds_read_b128 v[180:183], v136 offset:4096
	ds_read_b128 v[184:187], v136 offset:64
	ds_read_b128 v[188:191], v136 offset:4160
	s_waitcnt lgkmcnt(2)
	v_sub_f32_e32 v126, v126, v192
	v_mul_f32_e32 v126, v126, v193
	v_fma_f32 v126, v176, v126, v180
	v_sub_f32_e32 v127, v127, v192
	v_mul_f32_e32 v127, v127, v193
	v_fma_f32 v127, v177, v127, v181
	v_sub_f32_e32 v128, v128, v192
	v_mul_f32_e32 v128, v128, v193
	v_fma_f32 v128, v178, v128, v182
	v_sub_f32_e32 v129, v129, v192
	v_mul_f32_e32 v129, v129, v193
	v_fma_f32 v129, v179, v129, v183
	global_store_dwordx4 v137, v[126:129], s[94:95]
	ds_read_b128 v[176:179], v136 offset:128
	ds_read_b128 v[180:183], v136 offset:4224
	s_waitcnt lgkmcnt(2)
	v_sub_f32_e32 v122, v122, v192
	v_mul_f32_e32 v122, v122, v193
	v_fma_f32 v122, v184, v122, v188
	v_sub_f32_e32 v123, v123, v192
	v_mul_f32_e32 v123, v123, v193
	v_fma_f32 v123, v185, v123, v189
	v_sub_f32_e32 v124, v124, v192
	v_mul_f32_e32 v124, v124, v193
	v_fma_f32 v124, v186, v124, v190
	v_sub_f32_e32 v125, v125, v192
	v_mul_f32_e32 v125, v125, v193
	v_fma_f32 v125, v187, v125, v191
	global_store_dwordx4 v137, v[122:125], s[94:95] offset:64
	ds_read_b128 v[184:187], v136 offset:192
	ds_read_b128 v[188:191], v136 offset:4288
	s_waitcnt lgkmcnt(2)
	v_sub_f32_e32 v118, v118, v192
	v_mul_f32_e32 v118, v118, v193
	v_fma_f32 v118, v176, v118, v180
	v_sub_f32_e32 v119, v119, v192
	v_mul_f32_e32 v119, v119, v193
	v_fma_f32 v119, v177, v119, v181
	v_sub_f32_e32 v120, v120, v192
	v_mul_f32_e32 v120, v120, v193
	v_fma_f32 v120, v178, v120, v182
	v_sub_f32_e32 v121, v121, v192
	v_mul_f32_e32 v121, v121, v193
	v_fma_f32 v121, v179, v121, v183
	global_store_dwordx4 v137, v[118:121], s[94:95] offset:128
	ds_read_b128 v[176:179], v136 offset:256
	ds_read_b128 v[180:183], v136 offset:4352
	s_waitcnt lgkmcnt(2)
	v_sub_f32_e32 v114, v114, v192
	v_mul_f32_e32 v114, v114, v193
	v_fma_f32 v114, v184, v114, v188
	v_sub_f32_e32 v115, v115, v192
	v_mul_f32_e32 v115, v115, v193
	v_fma_f32 v115, v185, v115, v189
	v_sub_f32_e32 v116, v116, v192
	v_mul_f32_e32 v116, v116, v193
	v_fma_f32 v116, v186, v116, v190
	v_sub_f32_e32 v117, v117, v192
	v_mul_f32_e32 v117, v117, v193
	v_fma_f32 v117, v187, v117, v191
	global_store_dwordx4 v137, v[114:117], s[94:95] offset:192
	ds_read_b128 v[184:187], v136 offset:320
	ds_read_b128 v[188:191], v136 offset:4416
	s_waitcnt lgkmcnt(2)
	v_sub_f32_e32 v110, v110, v192
	v_mul_f32_e32 v110, v110, v193
	v_fma_f32 v110, v176, v110, v180
	v_sub_f32_e32 v111, v111, v192
	v_mul_f32_e32 v111, v111, v193
	v_fma_f32 v111, v177, v111, v181
	v_sub_f32_e32 v112, v112, v192
	v_mul_f32_e32 v112, v112, v193
	v_fma_f32 v112, v178, v112, v182
	v_sub_f32_e32 v113, v113, v192
	v_mul_f32_e32 v113, v113, v193
	v_fma_f32 v113, v179, v113, v183
	global_store_dwordx4 v137, v[110:113], s[94:95] offset:256
	ds_read_b128 v[176:179], v136 offset:384
	ds_read_b128 v[180:183], v136 offset:4480
	s_waitcnt lgkmcnt(2)
	v_sub_f32_e32 v106, v106, v192
	v_mul_f32_e32 v106, v106, v193
	v_fma_f32 v106, v184, v106, v188
	v_sub_f32_e32 v107, v107, v192
	v_mul_f32_e32 v107, v107, v193
	v_fma_f32 v107, v185, v107, v189
	v_sub_f32_e32 v108, v108, v192
	v_mul_f32_e32 v108, v108, v193
	v_fma_f32 v108, v186, v108, v190
	v_sub_f32_e32 v109, v109, v192
	v_mul_f32_e32 v109, v109, v193
	v_fma_f32 v109, v187, v109, v191
	global_store_dwordx4 v137, v[106:109], s[94:95] offset:320
	ds_read_b128 v[184:187], v136 offset:448
	ds_read_b128 v[188:191], v136 offset:4544
	s_waitcnt lgkmcnt(2)
	v_sub_f32_e32 v102, v102, v192
	v_mul_f32_e32 v102, v102, v193
	v_fma_f32 v102, v176, v102, v180
	v_sub_f32_e32 v103, v103, v192
	v_mul_f32_e32 v103, v103, v193
	v_fma_f32 v103, v177, v103, v181
	v_sub_f32_e32 v104, v104, v192
	v_mul_f32_e32 v104, v104, v193
	v_fma_f32 v104, v178, v104, v182
	v_sub_f32_e32 v105, v105, v192
	v_mul_f32_e32 v105, v105, v193
	v_fma_f32 v105, v179, v105, v183
	global_store_dwordx4 v137, v[102:105], s[94:95] offset:384
	s_waitcnt lgkmcnt(0)
	v_sub_f32_e32 v66, v66, v192
	v_mul_f32_e32 v66, v66, v193
	v_fma_f32 v66, v184, v66, v188
	v_sub_f32_e32 v67, v67, v192
	v_mul_f32_e32 v67, v67, v193
	v_fma_f32 v67, v185, v67, v189
	v_sub_f32_e32 v68, v68, v192
	v_mul_f32_e32 v68, v68, v193
	v_fma_f32 v68, v186, v68, v190
	v_sub_f32_e32 v69, v69, v192
	v_mul_f32_e32 v69, v69, v193
	v_fma_f32 v69, v187, v69, v191
	global_store_dwordx4 v137, v[66:69], s[94:95] offset:448
	s_waitcnt vmcnt(20) lgkmcnt(0)
	s_barrier
; DI float bf2f(unsigned b) { return __uint_as_float(b << 16); }
; DI void unit_O(const Params& p, char* lds, int l, int tile, int glu_tiles, int tile_b) {
;     ...
;         for (int mh = 0; mh < 2; ++mh) {
;             const int mt = half * 2 + mh, rl = mh * 16 + l15;
;             float s = 0.f, ss = 0.f;
; #pragma unroll
;             for (int nt = 0; nt < 8; ++nt) {
;                 f32x4 xr;
;                 if (l == 0) {
;                     const int chunk = wid * 32 + nt * 4 + quad;
;                     xr = *(const f32x4*)(XR + rl * 4096 + ((chunk ^ l15) << 4));
;                 } else {
;                     const u32x2 hb = *(const u32x2*)(XR + ((wid * 4 + (nt >> 1)) * 32 + rl) * 64 + (nt & 1) * 32 + quad * 8);
;                     xr = (f32x4){bf2f(hb[0] & 0xffffu), bf2f(hb[0] >> 16), bf2f(hb[1] & 0xffffu), bf2f(hb[1] >> 16)};
;                 }
; #pragma unroll
;                 for (int i = 0; i < 4; ++i) { const float v = acc[mt][nt][i] + DN_ALPHA * xr[i]; acc[mt][nt][i] = v; s += v; ss += v * v; }
;             }
;             s2[mh] = s; ss2[mh] = ss;
;         }
; #pragma unroll
;         for (int mh = 0; mh < 2; ++mh) { s2[mh] += __shfl_xor(s2[mh], 16); ss2[mh] += __shfl_xor(ss2[mh], 16); }
; #pragma unroll
;         for (int mh = 0; mh < 2; ++mh) { s2[mh] += __shfl_xor(s2[mh], 32); ss2[mh] += __shfl_xor(ss2[mh], 32); }
;         if (quad == 0) {
; #pragma unroll
;             for (int mh = 0; mh < 2; ++mh) *(f32x2*)&red[((mh * 16 + l15) * 8 + wid) * 2] = (f32x2){s2[mh], ss2[mh]};
;         }
;         __syncthreads();
	ds_read_b64 v[180:181], v133 offset:0
	ds_read_b64 v[182:183], v133 offset:32
	ds_read_b64 v[184:185], v133 offset:1024
	ds_read_b64 v[186:187], v133 offset:1056
	ds_read_b64 v[188:189], v133 offset:2048
	ds_read_b64 v[190:191], v133 offset:2080
	ds_read_b64 v[192:193], v133 offset:3072
	ds_read_b64 v[194:195], v133 offset:3104
	s_waitcnt lgkmcnt(7)
	v_lshlrev_b32_e32 v144, 16, v180
	v_and_b32_e32 v145, 0xffff0000, v180
	v_lshlrev_b32_e32 v146, 16, v181
	v_and_b32_e32 v147, 0xffff0000, v181
	v_fmac_f32_e32 v34, s58, v144
	v_fmac_f32_e32 v35, s58, v145
	v_fmac_f32_e32 v36, s58, v146
	v_fmac_f32_e32 v37, s58, v147
	v_mov_b32_e32 v196, v34
	v_mul_f32_e32 v197, v34, v34
	v_mov_b32_e32 v130, v35
	v_mul_f32_e32 v142, v35, v35
	v_add_f32_e32 v196, v196, v36
	v_fmac_f32_e32 v197, v36, v36
	v_add_f32_e32 v130, v130, v37
	v_fmac_f32_e32 v142, v37, v37
	s_waitcnt lgkmcnt(6)
	v_lshlrev_b32_e32 v148, 16, v182
	v_and_b32_e32 v149, 0xffff0000, v182
	v_lshlrev_b32_e32 v150, 16, v183
	v_and_b32_e32 v151, 0xffff0000, v183
	v_fmac_f32_e32 v30, s58, v148
	v_fmac_f32_e32 v31, s58, v149
	v_fmac_f32_e32 v32, s58, v150
	v_fmac_f32_e32 v33, s58, v151
	v_add_f32_e32 v196, v196, v30
	v_fmac_f32_e32 v197, v30, v30
	v_add_f32_e32 v130, v130, v31
	v_fmac_f32_e32 v142, v31, v31
	v_add_f32_e32 v196, v196, v32
	v_fmac_f32_e32 v197, v32, v32
	v_add_f32_e32 v130, v130, v33
	v_fmac_f32_e32 v142, v33, v33
	s_waitcnt lgkmcnt(5)
	v_lshlrev_b32_e32 v152, 16, v184
	v_and_b32_e32 v153, 0xffff0000, v184
	v_lshlrev_b32_e32 v154, 16, v185
	v_and_b32_e32 v155, 0xffff0000, v185
	v_fmac_f32_e32 v26, s58, v152
	v_fmac_f32_e32 v27, s58, v153
	v_fmac_f32_e32 v28, s58, v154
	v_fmac_f32_e32 v29, s58, v155
	v_add_f32_e32 v196, v196, v26
	v_fmac_f32_e32 v197, v26, v26
	v_add_f32_e32 v130, v130, v27
	v_fmac_f32_e32 v142, v27, v27
	v_add_f32_e32 v196, v196, v28
	v_fmac_f32_e32 v197, v28, v28
	v_add_f32_e32 v130, v130, v29
	v_fmac_f32_e32 v142, v29, v29
	s_waitcnt lgkmcnt(4)
	v_lshlrev_b32_e32 v156, 16, v186
	v_and_b32_e32 v157, 0xffff0000, v186
	v_lshlrev_b32_e32 v158, 16, v187
	v_and_b32_e32 v159, 0xffff0000, v187
	v_fmac_f32_e32 v22, s58, v156
	v_fmac_f32_e32 v23, s58, v157
	v_fmac_f32_e32 v24, s58, v158
	v_fmac_f32_e32 v25, s58, v159
	v_add_f32_e32 v196, v196, v22
	v_fmac_f32_e32 v197, v22, v22
	v_add_f32_e32 v130, v130, v23
	v_fmac_f32_e32 v142, v23, v23
	v_add_f32_e32 v196, v196, v24
	v_fmac_f32_e32 v197, v24, v24
	v_add_f32_e32 v130, v130, v25
	v_fmac_f32_e32 v142, v25, v25
	s_waitcnt lgkmcnt(3)
	v_lshlrev_b32_e32 v160, 16, v188
	v_and_b32_e32 v161, 0xffff0000, v188
	v_lshlrev_b32_e32 v162, 16, v189
	v_and_b32_e32 v163, 0xffff0000, v189
	v_fmac_f32_e32 v18, s58, v160
	v_fmac_f32_e32 v19, s58, v161
	v_fmac_f32_e32 v20, s58, v162
	v_fmac_f32_e32 v21, s58, v163
	v_add_f32_e32 v196, v196, v18
	v_fmac_f32_e32 v197, v18, v18
	v_add_f32_e32 v130, v130, v19
	v_fmac_f32_e32 v142, v19, v19
	v_add_f32_e32 v196, v196, v20
	v_fmac_f32_e32 v197, v20, v20
	v_add_f32_e32 v130, v130, v21
	v_fmac_f32_e32 v142, v21, v21
	s_waitcnt lgkmcnt(2)
	v_lshlrev_b32_e32 v164, 16, v190
	v_and_b32_e32 v165, 0xffff0000, v190
	v_lshlrev_b32_e32 v166, 16, v191
	v_and_b32_e32 v167, 0xffff0000, v191
	v_fmac_f32_e32 v14, s58, v164
	v_fmac_f32_e32 v15, s58, v165
	v_fmac_f32_e32 v16, s58, v166
	v_fmac_f32_e32 v17, s58, v167
	v_add_f32_e32 v196, v196, v14
	v_fmac_f32_e32 v197, v14, v14
	v_add_f32_e32 v130, v130, v15
	v_fmac_f32_e32 v142, v15, v15
	v_add_f32_e32 v196, v196, v16
	v_fmac_f32_e32 v197, v16, v16
	v_add_f32_e32 v130, v130, v17
	v_fmac_f32_e32 v142, v17, v17
	s_waitcnt lgkmcnt(1)
	v_lshlrev_b32_e32 v168, 16, v192
	v_and_b32_e32 v169, 0xffff0000, v192
	v_lshlrev_b32_e32 v170, 16, v193
	v_and_b32_e32 v171, 0xffff0000, v193
	v_fmac_f32_e32 v10, s58, v168
	v_fmac_f32_e32 v11, s58, v169
	v_fmac_f32_e32 v12, s58, v170
	v_fmac_f32_e32 v13, s58, v171
	v_add_f32_e32 v196, v196, v10
	v_fmac_f32_e32 v197, v10, v10
	v_add_f32_e32 v130, v130, v11
	v_fmac_f32_e32 v142, v11, v11
	v_add_f32_e32 v196, v196, v12
	v_fmac_f32_e32 v197, v12, v12
	v_add_f32_e32 v130, v130, v13
	v_fmac_f32_e32 v142, v13, v13
	s_waitcnt lgkmcnt(0)
	v_lshlrev_b32_e32 v172, 16, v194
	v_and_b32_e32 v173, 0xffff0000, v194
	v_lshlrev_b32_e32 v174, 16, v195
	v_and_b32_e32 v175, 0xffff0000, v195
	v_fmac_f32_e32 v6, s58, v172
	v_fmac_f32_e32 v7, s58, v173
	v_fmac_f32_e32 v8, s58, v174
	v_fmac_f32_e32 v9, s58, v175
	v_add_f32_e32 v196, v196, v6
	v_fmac_f32_e32 v197, v6, v6
	v_add_f32_e32 v130, v130, v7
	v_fmac_f32_e32 v142, v7, v7
	v_add_f32_e32 v196, v196, v8
	v_fmac_f32_e32 v197, v8, v8
	v_add_f32_e32 v130, v130, v9
	v_fmac_f32_e32 v142, v9, v9
	v_add_f32_e32 v196, v196, v130
	v_add_f32_e32 v197, v197, v142
	v_mov_b32_e32 v198, v196
	v_mov_b32_e32 v199, v197
	s_nop 1
	v_permlane16_swap_b32 v198, v196
	v_permlane16_swap_b32 v199, v197
	v_add_f32_e32 v196, v196, v198
	v_add_f32_e32 v197, v197, v199
	v_mov_b32_e32 v198, v196
	v_mov_b32_e32 v199, v197
	s_nop 1
	v_permlane32_swap_b32 v198, v196
	v_permlane32_swap_b32 v199, v197
	v_add_f32_e32 v196, v196, v198
	v_add_f32_e32 v197, v197, v199
	s_mov_b64 exec, 0xffff
	ds_write_b64 v134, v[196:197]
	s_mov_b64 exec, -1
	s_waitcnt lgkmcnt(0)
	s_barrier
; DI unsigned pk2(float lo, float hi) { const f32x2 v = {lo, hi}; const bf16x2_t b = __builtin_convertvector(v, bf16x2_t); return __builtin_bit_cast(unsigned, b); }
; DI size_t xb_off(int tok, int col) { return ((size_t)(((tok >> 7) * 32 + (col >> 5)) * 128 + (tok & 127))) * 32 + (col & 31); }
; DI void unit_O(const Params& p, char* lds, int l, int tile, int glu_tiles, int tile_b) {
;     ...
;         for (int mh = 0; mh < 2; ++mh) {
;             const int mt = half * 2 + mh, rl = mh * 16 + l15, row = mt * 16 + l15;
;             float s = 0.f, ss = 0.f;
; #pragma unroll
;             for (int w = 0; w < 4; ++w) { const f32x4 v = *(const f32x4*)&red[rl * 16 + 4 * w]; s += v[0] + v[2]; ss += v[1] + v[3]; }
;             const float mu = s * (1.f / 1024.f);
;             const float var = ss * (1.f / 1024.f) - mu * mu;
;             const float rs = rsqrtf(var + LN_EPS);
;             float* orow = xo + (r0 + row) * 1024 + wid * 128 + quad * 4;
;             bf16_t* brow = xbo + xb_off((int)r0 + row, wid * 128) + quad * 4;
;             const float* gp = GB + wid * 128 + quad * 4;
; #pragma unroll
;             for (int nt = 0; nt < 8; ++nt) {
;                 const f32x4 g = *(const f32x4*)(gp + nt * 16), bb = *(const f32x4*)(gp + 1024 + nt * 16);
;                 f32x4 o;
; #pragma unroll
;                 for (int i = 0; i < 4; ++i) o[i] = (acc[mt][nt][i] - mu) * rs * g[i] + bb[i];
;                 if (l == 0) *(u32x2*)(brow + (nt >> 1) * 4096 + (nt & 1) * 16) = (u32x2){pk2(o[0], o[1]), pk2(o[2], o[3])};
;                 else *(f32x4*)(orow + nt * 16) = o;
;             }
;         }
	ds_read_b128 v[160:163], v135 offset:0
	ds_read_b128 v[164:167], v135 offset:16
	ds_read_b128 v[168:171], v135 offset:32
	ds_read_b128 v[172:175], v135 offset:48
	s_waitcnt lgkmcnt(0)
	v_add_f32_e32 v160, v160, v162
	v_add_f32_e32 v161, v161, v163
	v_add_f32_e32 v164, v164, v166
	v_add_f32_e32 v165, v165, v167
	v_add_f32_e32 v168, v168, v170
	v_add_f32_e32 v169, v169, v171
	v_add_f32_e32 v172, v172, v174
	v_add_f32_e32 v173, v173, v175
	v_add_f32_e32 v160, v160, v164
	v_add_f32_e32 v161, v161, v165
	v_add_f32_e32 v168, v168, v172
	v_add_f32_e32 v169, v169, v173
	v_add_f32_e32 v160, v160, v168
	v_add_f32_e32 v161, v161, v169
	v_mul_f32_e32 v192, 0x3a800000, v160
	v_mul_f32_e32 v193, 0x3a800000, v161
	v_fma_f32 v193, -v192, v192, v193
	v_add_f32_e32 v193, 0x3727c5ac, v193
	v_rsq_f32_e32 v193, v193
	s_nop 0
	s_add_u32 s94, s78, 0x20000
	s_addc_u32 s95, s79, 0
	ds_read_b128 v[176:179], v136
	ds_read_b128 v[180:183], v136 offset:4096
	ds_read_b128 v[184:187], v136 offset:64
	ds_read_b128 v[188:191], v136 offset:4160
	s_waitcnt lgkmcnt(2)
	v_sub_f32_e32 v34, v34, v192
	v_mul_f32_e32 v34, v34, v193
	v_fma_f32 v34, v176, v34, v180
	v_sub_f32_e32 v35, v35, v192
	v_mul_f32_e32 v35, v35, v193
	v_fma_f32 v35, v177, v35, v181
	v_sub_f32_e32 v36, v36, v192
	v_mul_f32_e32 v36, v36, v193
	v_fma_f32 v36, v178, v36, v182
	v_sub_f32_e32 v37, v37, v192
	v_mul_f32_e32 v37, v37, v193
	v_fma_f32 v37, v179, v37, v183
	global_store_dwordx4 v137, v[34:37], s[94:95]
	ds_read_b128 v[176:179], v136 offset:128
	ds_read_b128 v[180:183], v136 offset:4224
	s_waitcnt lgkmcnt(2)
	v_sub_f32_e32 v30, v30, v192
	v_mul_f32_e32 v30, v30, v193
	v_fma_f32 v30, v184, v30, v188
	v_sub_f32_e32 v31, v31, v192
	v_mul_f32_e32 v31, v31, v193
	v_fma_f32 v31, v185, v31, v189
	v_sub_f32_e32 v32, v32, v192
	v_mul_f32_e32 v32, v32, v193
	v_fma_f32 v32, v186, v32, v190
	v_sub_f32_e32 v33, v33, v192
	v_mul_f32_e32 v33, v33, v193
	v_fma_f32 v33, v187, v33, v191
	global_store_dwordx4 v137, v[30:33], s[94:95] offset:64
	ds_read_b128 v[184:187], v136 offset:192
	ds_read_b128 v[188:191], v136 offset:4288
	s_waitcnt lgkmcnt(2)
	v_sub_f32_e32 v26, v26, v192
	v_mul_f32_e32 v26, v26, v193
	v_fma_f32 v26, v176, v26, v180
	v_sub_f32_e32 v27, v27, v192
	v_mul_f32_e32 v27, v27, v193
	v_fma_f32 v27, v177, v27, v181
	v_sub_f32_e32 v28, v28, v192
	v_mul_f32_e32 v28, v28, v193
	v_fma_f32 v28, v178, v28, v182
	v_sub_f32_e32 v29, v29, v192
	v_mul_f32_e32 v29, v29, v193
	v_fma_f32 v29, v179, v29, v183
	global_store_dwordx4 v137, v[26:29], s[94:95] offset:128
	ds_read_b128 v[176:179], v136 offset:256
	ds_read_b128 v[180:183], v136 offset:4352
	s_waitcnt lgkmcnt(2)
	v_sub_f32_e32 v22, v22, v192
	v_mul_f32_e32 v22, v22, v193
	v_fma_f32 v22, v184, v22, v188
	v_sub_f32_e32 v23, v23, v192
	v_mul_f32_e32 v23, v23, v193
	v_fma_f32 v23, v185, v23, v189
	v_sub_f32_e32 v24, v24, v192
	v_mul_f32_e32 v24, v24, v193
	v_fma_f32 v24, v186, v24, v190
	v_sub_f32_e32 v25, v25, v192
	v_mul_f32_e32 v25, v25, v193
	v_fma_f32 v25, v187, v25, v191
	global_store_dwordx4 v137, v[22:25], s[94:95] offset:192
	ds_read_b128 v[184:187], v136 offset:320
	ds_read_b128 v[188:191], v136 offset:4416
	s_waitcnt lgkmcnt(2)
	v_sub_f32_e32 v18, v18, v192
	v_mul_f32_e32 v18, v18, v193
	v_fma_f32 v18, v176, v18, v180
	v_sub_f32_e32 v19, v19, v192
	v_mul_f32_e32 v19, v19, v193
	v_fma_f32 v19, v177, v19, v181
	v_sub_f32_e32 v20, v20, v192
	v_mul_f32_e32 v20, v20, v193
	v_fma_f32 v20, v178, v20, v182
	v_sub_f32_e32 v21, v21, v192
	v_mul_f32_e32 v21, v21, v193
	v_fma_f32 v21, v179, v21, v183
	global_store_dwordx4 v137, v[18:21], s[94:95] offset:256
	ds_read_b128 v[176:179], v136 offset:384
	ds_read_b128 v[180:183], v136 offset:4480
	s_waitcnt lgkmcnt(2)
	v_sub_f32_e32 v14, v14, v192
	v_mul_f32_e32 v14, v14, v193
	v_fma_f32 v14, v184, v14, v188
	v_sub_f32_e32 v15, v15, v192
	v_mul_f32_e32 v15, v15, v193
	v_fma_f32 v15, v185, v15, v189
	v_sub_f32_e32 v16, v16, v192
	v_mul_f32_e32 v16, v16, v193
	v_fma_f32 v16, v186, v16, v190
	v_sub_f32_e32 v17, v17, v192
	v_mul_f32_e32 v17, v17, v193
	v_fma_f32 v17, v187, v17, v191
	global_store_dwordx4 v137, v[14:17], s[94:95] offset:320
	ds_read_b128 v[184:187], v136 offset:448
	ds_read_b128 v[188:191], v136 offset:4544
	s_waitcnt lgkmcnt(2)
	v_sub_f32_e32 v10, v10, v192
	v_mul_f32_e32 v10, v10, v193
	v_fma_f32 v10, v176, v10, v180
	v_sub_f32_e32 v11, v11, v192
	v_mul_f32_e32 v11, v11, v193
	v_fma_f32 v11, v177, v11, v181
	v_sub_f32_e32 v12, v12, v192
	v_mul_f32_e32 v12, v12, v193
	v_fma_f32 v12, v178, v12, v182
	v_sub_f32_e32 v13, v13, v192
	v_mul_f32_e32 v13, v13, v193
	v_fma_f32 v13, v179, v13, v183
	global_store_dwordx4 v137, v[10:13], s[94:95] offset:384
	s_waitcnt lgkmcnt(0)
	v_sub_f32_e32 v6, v6, v192
	v_mul_f32_e32 v6, v6, v193
	v_fma_f32 v6, v184, v6, v188
	v_sub_f32_e32 v7, v7, v192
	v_mul_f32_e32 v7, v7, v193
	v_fma_f32 v7, v185, v7, v189
	v_sub_f32_e32 v8, v8, v192
	v_mul_f32_e32 v8, v8, v193
	v_fma_f32 v8, v186, v8, v190
	v_sub_f32_e32 v9, v9, v192
	v_mul_f32_e32 v9, v9, v193
	v_fma_f32 v9, v187, v9, v191
	global_store_dwordx4 v137, v[6:9], s[94:95] offset:448
	s_waitcnt vmcnt(16) lgkmcnt(0)
	s_barrier
; DI float bf2f(unsigned b) { return __uint_as_float(b << 16); }
; DI void unit_O(const Params& p, char* lds, int l, int tile, int glu_tiles, int tile_b) {
;     ...
;         for (int mh = 0; mh < 2; ++mh) {
;             const int mt = half * 2 + mh, rl = mh * 16 + l15;
;             float s = 0.f, ss = 0.f;
; #pragma unroll
;             for (int nt = 0; nt < 8; ++nt) {
;                 f32x4 xr;
;                 if (l == 0) {
;                     const int chunk = wid * 32 + nt * 4 + quad;
;                     xr = *(const f32x4*)(XR + rl * 4096 + ((chunk ^ l15) << 4));
;                 } else {
;                     const u32x2 hb = *(const u32x2*)(XR + ((wid * 4 + (nt >> 1)) * 32 + rl) * 64 + (nt & 1) * 32 + quad * 8);
;                     xr = (f32x4){bf2f(hb[0] & 0xffffu), bf2f(hb[0] >> 16), bf2f(hb[1] & 0xffffu), bf2f(hb[1] >> 16)};
;                 }
; #pragma unroll
;                 for (int i = 0; i < 4; ++i) { const float v = acc[mt][nt][i] + DN_ALPHA * xr[i]; acc[mt][nt][i] = v; s += v; ss += v * v; }
;             }
;             s2[mh] = s; ss2[mh] = ss;
;         }
; #pragma unroll
;         for (int mh = 0; mh < 2; ++mh) { s2[mh] += __shfl_xor(s2[mh], 16); ss2[mh] += __shfl_xor(ss2[mh], 16); }
; #pragma unroll
;         for (int mh = 0; mh < 2; ++mh) { s2[mh] += __shfl_xor(s2[mh], 32); ss2[mh] += __shfl_xor(ss2[mh], 32); }
;         if (quad == 0) {
; #pragma unroll
;             for (int mh = 0; mh < 2; ++mh) *(f32x2*)&red[((mh * 16 + l15) * 8 + wid) * 2] = (f32x2){s2[mh], ss2[mh]};
;         }
;         __syncthreads();
	ds_read_b64 v[180:181], v133 offset:32768
	ds_read_b64 v[182:183], v133 offset:32800
	ds_read_b64 v[184:185], v133 offset:33792
	ds_read_b64 v[186:187], v133 offset:33824
	ds_read_b64 v[188:189], v133 offset:34816
	ds_read_b64 v[190:191], v133 offset:34848
	ds_read_b64 v[192:193], v133 offset:35840
	ds_read_b64 v[194:195], v133 offset:35872
	s_waitcnt lgkmcnt(7)
	v_lshlrev_b32_e32 v144, 16, v180
	v_and_b32_e32 v145, 0xffff0000, v180
	v_lshlrev_b32_e32 v146, 16, v181
	v_and_b32_e32 v147, 0xffff0000, v181
	v_fmac_f32_e32 v62, s58, v144
	v_fmac_f32_e32 v63, s58, v145
	v_fmac_f32_e32 v64, s58, v146
	v_fmac_f32_e32 v65, s58, v147
	v_mov_b32_e32 v196, v62
	v_mul_f32_e32 v197, v62, v62
	v_mov_b32_e32 v130, v63
	v_mul_f32_e32 v142, v63, v63
	v_add_f32_e32 v196, v196, v64
	v_fmac_f32_e32 v197, v64, v64
	v_add_f32_e32 v130, v130, v65
	v_fmac_f32_e32 v142, v65, v65
	s_waitcnt lgkmcnt(6)
	v_lshlrev_b32_e32 v148, 16, v182
	v_and_b32_e32 v149, 0xffff0000, v182
	v_lshlrev_b32_e32 v150, 16, v183
	v_and_b32_e32 v151, 0xffff0000, v183
	v_fmac_f32_e32 v58, s58, v148
	v_fmac_f32_e32 v59, s58, v149
	v_fmac_f32_e32 v60, s58, v150
	v_fmac_f32_e32 v61, s58, v151
	v_add_f32_e32 v196, v196, v58
	v_fmac_f32_e32 v197, v58, v58
	v_add_f32_e32 v130, v130, v59
	v_fmac_f32_e32 v142, v59, v59
	v_add_f32_e32 v196, v196, v60
	v_fmac_f32_e32 v197, v60, v60
	v_add_f32_e32 v130, v130, v61
	v_fmac_f32_e32 v142, v61, v61
	s_waitcnt lgkmcnt(5)
	v_lshlrev_b32_e32 v152, 16, v184
	v_and_b32_e32 v153, 0xffff0000, v184
	v_lshlrev_b32_e32 v154, 16, v185
	v_and_b32_e32 v155, 0xffff0000, v185
	v_fmac_f32_e32 v54, s58, v152
	v_fmac_f32_e32 v55, s58, v153
	v_fmac_f32_e32 v56, s58, v154
	v_fmac_f32_e32 v57, s58, v155
	v_add_f32_e32 v196, v196, v54
	v_fmac_f32_e32 v197, v54, v54
	v_add_f32_e32 v130, v130, v55
	v_fmac_f32_e32 v142, v55, v55
	v_add_f32_e32 v196, v196, v56
	v_fmac_f32_e32 v197, v56, v56
	v_add_f32_e32 v130, v130, v57
	v_fmac_f32_e32 v142, v57, v57
	s_waitcnt lgkmcnt(4)
	v_lshlrev_b32_e32 v156, 16, v186
	v_and_b32_e32 v157, 0xffff0000, v186
	v_lshlrev_b32_e32 v158, 16, v187
	v_and_b32_e32 v159, 0xffff0000, v187
	v_fmac_f32_e32 v50, s58, v156
	v_fmac_f32_e32 v51, s58, v157
	v_fmac_f32_e32 v52, s58, v158
	v_fmac_f32_e32 v53, s58, v159
	v_add_f32_e32 v196, v196, v50
	v_fmac_f32_e32 v197, v50, v50
	v_add_f32_e32 v130, v130, v51
	v_fmac_f32_e32 v142, v51, v51
	v_add_f32_e32 v196, v196, v52
	v_fmac_f32_e32 v197, v52, v52
	v_add_f32_e32 v130, v130, v53
	v_fmac_f32_e32 v142, v53, v53
	s_waitcnt lgkmcnt(3)
	v_lshlrev_b32_e32 v160, 16, v188
	v_and_b32_e32 v161, 0xffff0000, v188
	v_lshlrev_b32_e32 v162, 16, v189
	v_and_b32_e32 v163, 0xffff0000, v189
	v_fmac_f32_e32 v46, s58, v160
	v_fmac_f32_e32 v47, s58, v161
	v_fmac_f32_e32 v48, s58, v162
	v_fmac_f32_e32 v49, s58, v163
	v_add_f32_e32 v196, v196, v46
	v_fmac_f32_e32 v197, v46, v46
	v_add_f32_e32 v130, v130, v47
	v_fmac_f32_e32 v142, v47, v47
	v_add_f32_e32 v196, v196, v48
	v_fmac_f32_e32 v197, v48, v48
	v_add_f32_e32 v130, v130, v49
	v_fmac_f32_e32 v142, v49, v49
	s_waitcnt lgkmcnt(2)
	v_lshlrev_b32_e32 v164, 16, v190
	v_and_b32_e32 v165, 0xffff0000, v190
	v_lshlrev_b32_e32 v166, 16, v191
	v_and_b32_e32 v167, 0xffff0000, v191
	v_fmac_f32_e32 v42, s58, v164
	v_fmac_f32_e32 v43, s58, v165
	v_fmac_f32_e32 v44, s58, v166
	v_fmac_f32_e32 v45, s58, v167
	v_add_f32_e32 v196, v196, v42
	v_fmac_f32_e32 v197, v42, v42
	v_add_f32_e32 v130, v130, v43
	v_fmac_f32_e32 v142, v43, v43
	v_add_f32_e32 v196, v196, v44
	v_fmac_f32_e32 v197, v44, v44
	v_add_f32_e32 v130, v130, v45
	v_fmac_f32_e32 v142, v45, v45
	s_waitcnt lgkmcnt(1)
	v_lshlrev_b32_e32 v168, 16, v192
	v_and_b32_e32 v169, 0xffff0000, v192
	v_lshlrev_b32_e32 v170, 16, v193
	v_and_b32_e32 v171, 0xffff0000, v193
	v_fmac_f32_e32 v38, s58, v168
	v_fmac_f32_e32 v39, s58, v169
	v_fmac_f32_e32 v40, s58, v170
	v_fmac_f32_e32 v41, s58, v171
	v_add_f32_e32 v196, v196, v38
	v_fmac_f32_e32 v197, v38, v38
	v_add_f32_e32 v130, v130, v39
	v_fmac_f32_e32 v142, v39, v39
	v_add_f32_e32 v196, v196, v40
	v_fmac_f32_e32 v197, v40, v40
	v_add_f32_e32 v130, v130, v41
	v_fmac_f32_e32 v142, v41, v41
	s_waitcnt lgkmcnt(0)
	v_lshlrev_b32_e32 v172, 16, v194
	v_and_b32_e32 v173, 0xffff0000, v194
	v_lshlrev_b32_e32 v174, 16, v195
	v_and_b32_e32 v175, 0xffff0000, v195
	v_fmac_f32_e32 v2, s58, v172
	v_fmac_f32_e32 v3, s58, v173
	v_fmac_f32_e32 v4, s58, v174
	v_fmac_f32_e32 v5, s58, v175
	v_add_f32_e32 v196, v196, v2
	v_fmac_f32_e32 v197, v2, v2
	v_add_f32_e32 v130, v130, v3
	v_fmac_f32_e32 v142, v3, v3
	v_add_f32_e32 v196, v196, v4
	v_fmac_f32_e32 v197, v4, v4
	v_add_f32_e32 v130, v130, v5
	v_fmac_f32_e32 v142, v5, v5
	v_add_f32_e32 v196, v196, v130
	v_add_f32_e32 v197, v197, v142
	v_mov_b32_e32 v198, v196
	v_mov_b32_e32 v199, v197
	s_nop 1
	v_permlane16_swap_b32 v198, v196
	v_permlane16_swap_b32 v199, v197
	v_add_f32_e32 v196, v196, v198
	v_add_f32_e32 v197, v197, v199
	v_mov_b32_e32 v198, v196
	v_mov_b32_e32 v199, v197
	s_nop 1
	v_permlane32_swap_b32 v198, v196
	v_permlane32_swap_b32 v199, v197
	v_add_f32_e32 v196, v196, v198
	v_add_f32_e32 v197, v197, v199
	s_mov_b64 exec, 0xffff
	ds_write_b64 v134, v[196:197]
	s_mov_b64 exec, -1
	s_waitcnt lgkmcnt(0)
	s_barrier
; DI unsigned pk2(float lo, float hi) { const f32x2 v = {lo, hi}; const bf16x2_t b = __builtin_convertvector(v, bf16x2_t); return __builtin_bit_cast(unsigned, b); }
; DI size_t xb_off(int tok, int col) { return ((size_t)(((tok >> 7) * 32 + (col >> 5)) * 128 + (tok & 127))) * 32 + (col & 31); }
; DI void unit_O(const Params& p, char* lds, int l, int tile, int glu_tiles, int tile_b) {
;     ...
;         for (int mh = 0; mh < 2; ++mh) {
;             const int mt = half * 2 + mh, rl = mh * 16 + l15, row = mt * 16 + l15;
;             float s = 0.f, ss = 0.f;
; #pragma unroll
;             for (int w = 0; w < 4; ++w) { const f32x4 v = *(const f32x4*)&red[rl * 16 + 4 * w]; s += v[0] + v[2]; ss += v[1] + v[3]; }
;             const float mu = s * (1.f / 1024.f);
;             const float var = ss * (1.f / 1024.f) - mu * mu;
;             const float rs = rsqrtf(var + LN_EPS);
;             float* orow = xo + (r0 + row) * 1024 + wid * 128 + quad * 4;
;             bf16_t* brow = xbo + xb_off((int)r0 + row, wid * 128) + quad * 4;
;             const float* gp = GB + wid * 128 + quad * 4;
; #pragma unroll
;             for (int nt = 0; nt < 8; ++nt) {
;                 const f32x4 g = *(const f32x4*)(gp + nt * 16), bb = *(const f32x4*)(gp + 1024 + nt * 16);
;                 f32x4 o;
; #pragma unroll
;                 for (int i = 0; i < 4; ++i) o[i] = (acc[mt][nt][i] - mu) * rs * g[i] + bb[i];
;                 if (l == 0) *(u32x2*)(brow + (nt >> 1) * 4096 + (nt & 1) * 16) = (u32x2){pk2(o[0], o[1]), pk2(o[2], o[3])};
;                 else *(f32x4*)(orow + nt * 16) = o;
;             }
;         }
	ds_read_b128 v[160:163], v135 offset:0
	ds_read_b128 v[164:167], v135 offset:16
	ds_read_b128 v[168:171], v135 offset:32
	ds_read_b128 v[172:175], v135 offset:48
	s_waitcnt lgkmcnt(0)
	v_add_f32_e32 v160, v160, v162
	v_add_f32_e32 v161, v161, v163
	v_add_f32_e32 v164, v164, v166
	v_add_f32_e32 v165, v165, v167
	v_add_f32_e32 v168, v168, v170
	v_add_f32_e32 v169, v169, v171
	v_add_f32_e32 v172, v172, v174
	v_add_f32_e32 v173, v173, v175
	v_add_f32_e32 v160, v160, v164
	v_add_f32_e32 v161, v161, v165
	v_add_f32_e32 v168, v168, v172
	v_add_f32_e32 v169, v169, v173
	v_add_f32_e32 v160, v160, v168
	v_add_f32_e32 v161, v161, v169
	v_mul_f32_e32 v192, 0x3a800000, v160
	v_mul_f32_e32 v193, 0x3a800000, v161
	v_fma_f32 v193, -v192, v192, v193
	v_add_f32_e32 v193, 0x3727c5ac, v193
	v_rsq_f32_e32 v193, v193
	s_nop 0
	s_add_u32 s94, s78, 0x30000
	s_addc_u32 s95, s79, 0
	ds_read_b128 v[176:179], v136
	ds_read_b128 v[180:183], v136 offset:4096
	ds_read_b128 v[184:187], v136 offset:64
	ds_read_b128 v[188:191], v136 offset:4160
	s_waitcnt lgkmcnt(2)
	v_sub_f32_e32 v62, v62, v192
	v_mul_f32_e32 v62, v62, v193
	v_fma_f32 v62, v176, v62, v180
	v_sub_f32_e32 v63, v63, v192
	v_mul_f32_e32 v63, v63, v193
	v_fma_f32 v63, v177, v63, v181
	v_sub_f32_e32 v64, v64, v192
	v_mul_f32_e32 v64, v64, v193
	v_fma_f32 v64, v178, v64, v182
	v_sub_f32_e32 v65, v65, v192
	v_mul_f32_e32 v65, v65, v193
	v_fma_f32 v65, v179, v65, v183
	global_store_dwordx4 v137, v[62:65], s[94:95]
	ds_read_b128 v[176:179], v136 offset:128
	ds_read_b128 v[180:183], v136 offset:4224
	s_waitcnt lgkmcnt(2)
	v_sub_f32_e32 v58, v58, v192
	v_mul_f32_e32 v58, v58, v193
	v_fma_f32 v58, v184, v58, v188
	v_sub_f32_e32 v59, v59, v192
	v_mul_f32_e32 v59, v59, v193
	v_fma_f32 v59, v185, v59, v189
	v_sub_f32_e32 v60, v60, v192
	v_mul_f32_e32 v60, v60, v193
	v_fma_f32 v60, v186, v60, v190
	v_sub_f32_e32 v61, v61, v192
	v_mul_f32_e32 v61, v61, v193
	v_fma_f32 v61, v187, v61, v191
	global_store_dwordx4 v137, v[58:61], s[94:95] offset:64
	ds_read_b128 v[184:187], v136 offset:192
	ds_read_b128 v[188:191], v136 offset:4288
	s_waitcnt lgkmcnt(2)
	v_sub_f32_e32 v54, v54, v192
	v_mul_f32_e32 v54, v54, v193
	v_fma_f32 v54, v176, v54, v180
	v_sub_f32_e32 v55, v55, v192
	v_mul_f32_e32 v55, v55, v193
	v_fma_f32 v55, v177, v55, v181
	v_sub_f32_e32 v56, v56, v192
	v_mul_f32_e32 v56, v56, v193
	v_fma_f32 v56, v178, v56, v182
	v_sub_f32_e32 v57, v57, v192
	v_mul_f32_e32 v57, v57, v193
	v_fma_f32 v57, v179, v57, v183
	global_store_dwordx4 v137, v[54:57], s[94:95] offset:128
	ds_read_b128 v[176:179], v136 offset:256
	ds_read_b128 v[180:183], v136 offset:4352
	s_waitcnt lgkmcnt(2)
	v_sub_f32_e32 v50, v50, v192
	v_mul_f32_e32 v50, v50, v193
	v_fma_f32 v50, v184, v50, v188
	v_sub_f32_e32 v51, v51, v192
	v_mul_f32_e32 v51, v51, v193
	v_fma_f32 v51, v185, v51, v189
	v_sub_f32_e32 v52, v52, v192
	v_mul_f32_e32 v52, v52, v193
	v_fma_f32 v52, v186, v52, v190
	v_sub_f32_e32 v53, v53, v192
	v_mul_f32_e32 v53, v53, v193
	v_fma_f32 v53, v187, v53, v191
	global_store_dwordx4 v137, v[50:53], s[94:95] offset:192
	ds_read_b128 v[184:187], v136 offset:320
	ds_read_b128 v[188:191], v136 offset:4416
	s_waitcnt lgkmcnt(2)
	v_sub_f32_e32 v46, v46, v192
	v_mul_f32_e32 v46, v46, v193
	v_fma_f32 v46, v176, v46, v180
	v_sub_f32_e32 v47, v47, v192
	v_mul_f32_e32 v47, v47, v193
	v_fma_f32 v47, v177, v47, v181
	v_sub_f32_e32 v48, v48, v192
	v_mul_f32_e32 v48, v48, v193
	v_fma_f32 v48, v178, v48, v182
	v_sub_f32_e32 v49, v49, v192
	v_mul_f32_e32 v49, v49, v193
	v_fma_f32 v49, v179, v49, v183
	global_store_dwordx4 v137, v[46:49], s[94:95] offset:256
	ds_read_b128 v[176:179], v136 offset:384
	ds_read_b128 v[180:183], v136 offset:4480
	s_waitcnt lgkmcnt(2)
	v_sub_f32_e32 v42, v42, v192
	v_mul_f32_e32 v42, v42, v193
	v_fma_f32 v42, v184, v42, v188
	v_sub_f32_e32 v43, v43, v192
	v_mul_f32_e32 v43, v43, v193
	v_fma_f32 v43, v185, v43, v189
	v_sub_f32_e32 v44, v44, v192
	v_mul_f32_e32 v44, v44, v193
	v_fma_f32 v44, v186, v44, v190
	v_sub_f32_e32 v45, v45, v192
	v_mul_f32_e32 v45, v45, v193
	v_fma_f32 v45, v187, v45, v191
	global_store_dwordx4 v137, v[42:45], s[94:95] offset:320
	ds_read_b128 v[184:187], v136 offset:448
	ds_read_b128 v[188:191], v136 offset:4544
	s_waitcnt lgkmcnt(2)
	v_sub_f32_e32 v38, v38, v192
	v_mul_f32_e32 v38, v38, v193
	v_fma_f32 v38, v176, v38, v180
	v_sub_f32_e32 v39, v39, v192
	v_mul_f32_e32 v39, v39, v193
	v_fma_f32 v39, v177, v39, v181
	v_sub_f32_e32 v40, v40, v192
	v_mul_f32_e32 v40, v40, v193
	v_fma_f32 v40, v178, v40, v182
	v_sub_f32_e32 v41, v41, v192
	v_mul_f32_e32 v41, v41, v193
	v_fma_f32 v41, v179, v41, v183
	global_store_dwordx4 v137, v[38:41], s[94:95] offset:384
	s_waitcnt lgkmcnt(0)
	v_sub_f32_e32 v2, v2, v192
	v_mul_f32_e32 v2, v2, v193
	v_fma_f32 v2, v184, v2, v188
	v_sub_f32_e32 v3, v3, v192
	v_mul_f32_e32 v3, v3, v193
	v_fma_f32 v3, v185, v3, v189
	v_sub_f32_e32 v4, v4, v192
	v_mul_f32_e32 v4, v4, v193
	v_fma_f32 v4, v186, v4, v190
	v_sub_f32_e32 v5, v5, v192
	v_mul_f32_e32 v5, v5, v193
	v_fma_f32 v5, v187, v5, v191
	global_store_dwordx4 v137, v[2:5], s[94:95] offset:448
